# batched epilogue loads in merge (sigmoid gates) and pool (silu gates); DSA attention QK gathers batched per token
# speedup vs baseline: 1.0599x; 1.0599x over previous
;   __device__ __forceinline__ half_t* u() const { return (half_t*)(ws() + OFF_u); }
;   __device__ __forceinline__ half_t* ya() const { return (half_t*)(ws() + OFF_ya); }
; __device__ __forceinline__ float siluf_(float x) { return x / (1.f + __expf(-x)); }
; template <int NI, class LA, class LB, class EP>
; __device__ __forceinline__ void gemm_tile(int K, LA loadA, LB loadB, EP epi, char* smem) {
;     ...
; #pragma unroll
;   for (int mi = 0; mi < 2; ++mi)
; #pragma unroll
;     for (int ni = 0; ni < NI; ++ni)
; #pragma unroll
;       for (int r = 0; r < 16; ++r) {
;         const int row = wm * 64 + mi * 32 + (r & 3) + 8 * (r >> 2) + 4 * (lane >> 5);
;         const int col = wn * (NI * 32) + ni * 32 + (lane & 31);
;         epi(mi, ni, r, row, col, acc[mi][ni][r]);
;       }
; __device__ __forceinline__ void pool_item(const KP& p, int l, int item, char* smem) {
;     ...
;       [&](int mi, int ni, int r, int row, int col, float v) {
;         const int tok = m0 + row;
;         const float z = (float)p.u()[(size_t)tok * NU + C_AZ + g * 128 + col];
;         p.ya()[(size_t)tok * 512 + g * 128 + col] = (half_t)((v + pb[ni]) * ps[ni] * siluf_(z));
;       },
.LBB0_764:
	s_load_dwordx2 s[2:3], s[10:11], 0x98
	v_readlane_b32 s14, v252, 61
	v_readlane_b32 s0, v251, 7
	v_readlane_b32 s1, v251, 8
	v_lshrrev_b32_e32 v66, 7, v224
	v_lshlrev_b32_e32 v66, 4, v66
	v_bfe_u32 v67, v224, 5, 1
	v_add_u32_e32 v66, v66, v67
	v_mul_u32_u24_e32 v68, 0xe800, v66
	v_lshlrev_b32_e32 v69, 12, v66
	v_bfe_u32 v67, v224, 6, 1
	v_lshlrev_b32_e32 v67, 7, v67
	v_and_b32_e32 v70, 31, v224
	v_lshl_or_b32 v67, v70, 1, v67
	v_add_u32_e32 v68, v68, v67
	v_add_u32_e32 v69, v69, v67
	s_waitcnt lgkmcnt(0)
	s_lshl_b32 s14, s14, 1
	s_add_u32 s2, s2, s14
	s_addc_u32 s3, s3, 0
	s_add_u32 s2, s2, 0x6000400
	s_addc_u32 s3, s3, 0
	s_mul_i32 s14, s8, 0x3a00
	s_add_u32 s2, s2, s14
	s_addc_u32 s3, s3, 0
	s_lshl_b32 s14, s8, 10
	s_add_u32 s0, s0, s14
	s_addc_u32 s1, s1, 0
	v_mov_b32_e32 v70, v68
	global_load_ushort v97, v70, s[2:3]
	v_add_u32_e32 v70, 0x3a00, v68
	global_load_ushort v98, v70, s[2:3]
	v_add_u32_e32 v70, 0x7400, v68
	global_load_ushort v99, v70, s[2:3]
	v_add_u32_e32 v70, 0xae00, v68
	global_load_ushort v100, v70, s[2:3]
	v_add_u32_e32 v70, 0x1d000, v68
	global_load_ushort v101, v70, s[2:3]
	v_add_u32_e32 v70, 0x20a00, v68
	global_load_ushort v102, v70, s[2:3]
	v_add_u32_e32 v70, 0x24400, v68
	global_load_ushort v103, v70, s[2:3]
	v_add_u32_e32 v70, 0x27e00, v68
	global_load_ushort v104, v70, s[2:3]
	v_add_u32_e32 v70, 0x3a000, v68
	global_load_ushort v105, v70, s[2:3]
	v_add_u32_e32 v70, 0x3da00, v68
	global_load_ushort v106, v70, s[2:3]
	v_add_u32_e32 v70, 0x41400, v68
	global_load_ushort v107, v70, s[2:3]
	v_add_u32_e32 v70, 0x44e00, v68
	global_load_ushort v108, v70, s[2:3]
	v_add_u32_e32 v70, 0x57000, v68
	global_load_ushort v109, v70, s[2:3]
	v_add_u32_e32 v70, 0x5aa00, v68
	global_load_ushort v110, v70, s[2:3]
	v_add_u32_e32 v70, 0x5e400, v68
	global_load_ushort v111, v70, s[2:3]
	v_add_u32_e32 v70, 0x61e00, v68
	global_load_ushort v112, v70, s[2:3]
	v_mov_b32_e32 v70, v68
	global_load_ushort v113, v70, s[2:3] offset:64
	v_add_u32_e32 v70, 0x3a00, v68
	global_load_ushort v114, v70, s[2:3] offset:64
	v_add_u32_e32 v70, 0x7400, v68
	global_load_ushort v115, v70, s[2:3] offset:64
	v_add_u32_e32 v70, 0xae00, v68
	global_load_ushort v116, v70, s[2:3] offset:64
	v_add_u32_e32 v70, 0x1d000, v68
	global_load_ushort v117, v70, s[2:3] offset:64
	v_add_u32_e32 v70, 0x20a00, v68
	global_load_ushort v118, v70, s[2:3] offset:64
	v_add_u32_e32 v70, 0x24400, v68
	global_load_ushort v119, v70, s[2:3] offset:64
	v_add_u32_e32 v70, 0x27e00, v68
	global_load_ushort v120, v70, s[2:3] offset:64
	s_waitcnt vmcnt(23)
	v_add_f32_e32 v72, v189, v50
	v_mul_f32_e32 v72, v190, v72
	v_cvt_f32_f16_e32 v73, v97
	v_add_u32_e32 v70, 0x3a000, v68
	global_load_ushort v97, v70, s[2:3] offset:64
	v_mul_f32_e32 v74, 0xbfb8aa3b, v73
	v_exp_f32_e32 v74, v74
	s_nop 0
	v_add_f32_e32 v74, 1.0, v74
	v_div_scale_f32 v75, vcc, v74, v74, v73
	v_rcp_f32_e32 v76, v75
	v_div_scale_f32 v77, vcc, v73, v74, v73
	v_fma_f32 v78, -v75, v76, 1.0
	v_fmac_f32_e32 v76, v78, v76
	v_mul_f32_e32 v78, v77, v76
	v_fma_f32 v79, -v75, v78, v77
	v_fmac_f32_e32 v78, v79, v76
	v_fma_f32 v75, -v75, v78, v77
	v_div_fmas_f32 v75, v75, v76, v78
	v_div_fixup_f32 v73, v75, v74, v73
	v_fma_mixlo_f16 v73, v72, v73, 0
	v_mov_b32_e32 v71, v69
	global_store_short v71, v73, s[0:1]
	s_waitcnt vmcnt(24)
	v_add_f32_e32 v72, v189, v51
	v_mul_f32_e32 v72, v190, v72
	v_cvt_f32_f16_e32 v73, v98
	v_add_u32_e32 v70, 0x3da00, v68
	global_load_ushort v98, v70, s[2:3] offset:64
	v_mul_f32_e32 v74, 0xbfb8aa3b, v73
	v_exp_f32_e32 v74, v74
	s_nop 0
	v_add_f32_e32 v74, 1.0, v74
	v_div_scale_f32 v75, vcc, v74, v74, v73
	v_rcp_f32_e32 v76, v75
	v_div_scale_f32 v77, vcc, v73, v74, v73
	v_fma_f32 v78, -v75, v76, 1.0
	v_fmac_f32_e32 v76, v78, v76
	v_mul_f32_e32 v78, v77, v76
	v_fma_f32 v79, -v75, v78, v77
	v_fmac_f32_e32 v78, v79, v76
	v_fma_f32 v75, -v75, v78, v77
	v_div_fmas_f32 v75, v75, v76, v78
	v_div_fixup_f32 v73, v75, v74, v73
	v_fma_mixlo_f16 v73, v72, v73, 0
	v_add_u32_e32 v71, 0x400, v69
	global_store_short v71, v73, s[0:1]
	s_waitcnt vmcnt(25)
	v_add_f32_e32 v72, v189, v52
	v_mul_f32_e32 v72, v190, v72
	v_cvt_f32_f16_e32 v73, v99
	v_add_u32_e32 v70, 0x41400, v68
	global_load_ushort v99, v70, s[2:3] offset:64
	v_mul_f32_e32 v74, 0xbfb8aa3b, v73
	v_exp_f32_e32 v74, v74
	s_nop 0
	v_add_f32_e32 v74, 1.0, v74
	v_div_scale_f32 v75, vcc, v74, v74, v73
	v_rcp_f32_e32 v76, v75
	v_div_scale_f32 v77, vcc, v73, v74, v73
	v_fma_f32 v78, -v75, v76, 1.0
	v_fmac_f32_e32 v76, v78, v76
	v_mul_f32_e32 v78, v77, v76
	v_fma_f32 v79, -v75, v78, v77
	v_fmac_f32_e32 v78, v79, v76
	v_fma_f32 v75, -v75, v78, v77
	v_div_fmas_f32 v75, v75, v76, v78
	v_div_fixup_f32 v73, v75, v74, v73
	v_fma_mixlo_f16 v73, v72, v73, 0
	v_add_u32_e32 v71, 0x800, v69
	global_store_short v71, v73, s[0:1]
	s_waitcnt vmcnt(26)
	v_add_f32_e32 v72, v189, v53
	v_mul_f32_e32 v72, v190, v72
	v_cvt_f32_f16_e32 v73, v100
	v_add_u32_e32 v70, 0x44e00, v68
	global_load_ushort v100, v70, s[2:3] offset:64
	v_mul_f32_e32 v74, 0xbfb8aa3b, v73
	v_exp_f32_e32 v74, v74
	s_nop 0
	v_add_f32_e32 v74, 1.0, v74
	v_div_scale_f32 v75, vcc, v74, v74, v73
	v_rcp_f32_e32 v76, v75
	v_div_scale_f32 v77, vcc, v73, v74, v73
	v_fma_f32 v78, -v75, v76, 1.0
	v_fmac_f32_e32 v76, v78, v76
	v_mul_f32_e32 v78, v77, v76
	v_fma_f32 v79, -v75, v78, v77
	v_fmac_f32_e32 v78, v79, v76
	v_fma_f32 v75, -v75, v78, v77
	v_div_fmas_f32 v75, v75, v76, v78
	v_div_fixup_f32 v73, v75, v74, v73
	v_fma_mixlo_f16 v73, v72, v73, 0
	v_add_u32_e32 v71, 0xc00, v69
	global_store_short v71, v73, s[0:1]
	s_waitcnt vmcnt(27)
;   __device__ __forceinline__ half_t* u() const { return (half_t*)(ws() + OFF_u); }
;   __device__ __forceinline__ half_t* ya() const { return (half_t*)(ws() + OFF_ya); }
; __device__ __forceinline__ float siluf_(float x) { return x / (1.f + __expf(-x)); }
; template <int NI, class LA, class LB, class EP>
; __device__ __forceinline__ void gemm_tile(int K, LA loadA, LB loadB, EP epi, char* smem) {
;     ...
; #pragma unroll
;   for (int mi = 0; mi < 2; ++mi)
; #pragma unroll
;     for (int ni = 0; ni < NI; ++ni)
; #pragma unroll
;       for (int r = 0; r < 16; ++r) {
;         const int row = wm * 64 + mi * 32 + (r & 3) + 8 * (r >> 2) + 4 * (lane >> 5);
;         const int col = wn * (NI * 32) + ni * 32 + (lane & 31);
;         epi(mi, ni, r, row, col, acc[mi][ni][r]);
;       }
; __device__ __forceinline__ void pool_item(const KP& p, int l, int item, char* smem) {
;     ...
;       [&](int mi, int ni, int r, int row, int col, float v) {
;         const int tok = m0 + row;
;         const float z = (float)p.u()[(size_t)tok * NU + C_AZ + g * 128 + col];
;         p.ya()[(size_t)tok * 512 + g * 128 + col] = (half_t)((v + pb[ni]) * ps[ni] * siluf_(z));
;       },
	v_add_f32_e32 v72, v189, v54
	v_mul_f32_e32 v72, v190, v72
	v_cvt_f32_f16_e32 v73, v101
	v_add_u32_e32 v70, 0x57000, v68
	global_load_ushort v101, v70, s[2:3] offset:64
	v_mul_f32_e32 v74, 0xbfb8aa3b, v73
	v_exp_f32_e32 v74, v74
	s_nop 0
	v_add_f32_e32 v74, 1.0, v74
	v_div_scale_f32 v75, vcc, v74, v74, v73
	v_rcp_f32_e32 v76, v75
	v_div_scale_f32 v77, vcc, v73, v74, v73
	v_fma_f32 v78, -v75, v76, 1.0
	v_fmac_f32_e32 v76, v78, v76
	v_mul_f32_e32 v78, v77, v76
	v_fma_f32 v79, -v75, v78, v77
	v_fmac_f32_e32 v78, v79, v76
	v_fma_f32 v75, -v75, v78, v77
	v_div_fmas_f32 v75, v75, v76, v78
	v_div_fixup_f32 v73, v75, v74, v73
	v_fma_mixlo_f16 v73, v72, v73, 0
	v_add_u32_e32 v71, 0x2000, v69
	global_store_short v71, v73, s[0:1]
	s_waitcnt vmcnt(28)
	v_add_f32_e32 v72, v189, v55
	v_mul_f32_e32 v72, v190, v72
	v_cvt_f32_f16_e32 v73, v102
	v_add_u32_e32 v70, 0x5aa00, v68
	global_load_ushort v102, v70, s[2:3] offset:64
	v_mul_f32_e32 v74, 0xbfb8aa3b, v73
	v_exp_f32_e32 v74, v74
	s_nop 0
	v_add_f32_e32 v74, 1.0, v74
	v_div_scale_f32 v75, vcc, v74, v74, v73
	v_rcp_f32_e32 v76, v75
	v_div_scale_f32 v77, vcc, v73, v74, v73
	v_fma_f32 v78, -v75, v76, 1.0
	v_fmac_f32_e32 v76, v78, v76
	v_mul_f32_e32 v78, v77, v76
	v_fma_f32 v79, -v75, v78, v77
	v_fmac_f32_e32 v78, v79, v76
	v_fma_f32 v75, -v75, v78, v77
	v_div_fmas_f32 v75, v75, v76, v78
	v_div_fixup_f32 v73, v75, v74, v73
	v_fma_mixlo_f16 v73, v72, v73, 0
	v_add_u32_e32 v71, 0x2400, v69
	global_store_short v71, v73, s[0:1]
	s_waitcnt vmcnt(29)
	v_add_f32_e32 v72, v189, v56
	v_mul_f32_e32 v72, v190, v72
	v_cvt_f32_f16_e32 v73, v103
	v_add_u32_e32 v70, 0x5e400, v68
	global_load_ushort v103, v70, s[2:3] offset:64
	v_mul_f32_e32 v74, 0xbfb8aa3b, v73
	v_exp_f32_e32 v74, v74
	s_nop 0
	v_add_f32_e32 v74, 1.0, v74
	v_div_scale_f32 v75, vcc, v74, v74, v73
	v_rcp_f32_e32 v76, v75
	v_div_scale_f32 v77, vcc, v73, v74, v73
	v_fma_f32 v78, -v75, v76, 1.0
	v_fmac_f32_e32 v76, v78, v76
	v_mul_f32_e32 v78, v77, v76
	v_fma_f32 v79, -v75, v78, v77
	v_fmac_f32_e32 v78, v79, v76
	v_fma_f32 v75, -v75, v78, v77
	v_div_fmas_f32 v75, v75, v76, v78
	v_div_fixup_f32 v73, v75, v74, v73
	v_fma_mixlo_f16 v73, v72, v73, 0
	v_add_u32_e32 v71, 0x2800, v69
	global_store_short v71, v73, s[0:1]
	s_waitcnt vmcnt(30)
	v_add_f32_e32 v72, v189, v57
	v_mul_f32_e32 v72, v190, v72
	v_cvt_f32_f16_e32 v73, v104
	v_add_u32_e32 v70, 0x61e00, v68
	global_load_ushort v104, v70, s[2:3] offset:64
	v_mul_f32_e32 v74, 0xbfb8aa3b, v73
	v_exp_f32_e32 v74, v74
	s_nop 0
	v_add_f32_e32 v74, 1.0, v74
	v_div_scale_f32 v75, vcc, v74, v74, v73
	v_rcp_f32_e32 v76, v75
	v_div_scale_f32 v77, vcc, v73, v74, v73
	v_fma_f32 v78, -v75, v76, 1.0
	v_fmac_f32_e32 v76, v78, v76
	v_mul_f32_e32 v78, v77, v76
	v_fma_f32 v79, -v75, v78, v77
	v_fmac_f32_e32 v78, v79, v76
	v_fma_f32 v75, -v75, v78, v77
	v_div_fmas_f32 v75, v75, v76, v78
	v_div_fixup_f32 v73, v75, v74, v73
	v_fma_mixlo_f16 v73, v72, v73, 0
	v_add_u32_e32 v71, 0x2c00, v69
	global_store_short v71, v73, s[0:1]
	s_waitcnt vmcnt(31)
	v_add_f32_e32 v72, v189, v58
	v_mul_f32_e32 v72, v190, v72
	v_cvt_f32_f16_e32 v73, v105
	v_add_u32_e32 v70, 0x74000, v68
	global_load_ushort v105, v70, s[2:3]
	v_mul_f32_e32 v74, 0xbfb8aa3b, v73
	v_exp_f32_e32 v74, v74
	s_nop 0
	v_add_f32_e32 v74, 1.0, v74
	v_div_scale_f32 v75, vcc, v74, v74, v73
	v_rcp_f32_e32 v76, v75
	v_div_scale_f32 v77, vcc, v73, v74, v73
	v_fma_f32 v78, -v75, v76, 1.0
	v_fmac_f32_e32 v76, v78, v76
	v_mul_f32_e32 v78, v77, v76
	v_fma_f32 v79, -v75, v78, v77
	v_fmac_f32_e32 v78, v79, v76
	v_fma_f32 v75, -v75, v78, v77
	v_div_fmas_f32 v75, v75, v76, v78
	v_div_fixup_f32 v73, v75, v74, v73
	v_fma_mixlo_f16 v73, v72, v73, 0
	v_add_u32_e32 v71, 0x4000, v69
	global_store_short v71, v73, s[0:1]
	s_waitcnt vmcnt(32)
	v_add_f32_e32 v72, v189, v59
	v_mul_f32_e32 v72, v190, v72
	v_cvt_f32_f16_e32 v73, v106
	v_add_u32_e32 v70, 0x77a00, v68
	global_load_ushort v106, v70, s[2:3]
	v_mul_f32_e32 v74, 0xbfb8aa3b, v73
	v_exp_f32_e32 v74, v74
	s_nop 0
	v_add_f32_e32 v74, 1.0, v74
	v_div_scale_f32 v75, vcc, v74, v74, v73
	v_rcp_f32_e32 v76, v75
	v_div_scale_f32 v77, vcc, v73, v74, v73
	v_fma_f32 v78, -v75, v76, 1.0
	v_fmac_f32_e32 v76, v78, v76
	v_mul_f32_e32 v78, v77, v76
	v_fma_f32 v79, -v75, v78, v77
	v_fmac_f32_e32 v78, v79, v76
	v_fma_f32 v75, -v75, v78, v77
	v_div_fmas_f32 v75, v75, v76, v78
	v_div_fixup_f32 v73, v75, v74, v73
	v_fma_mixlo_f16 v73, v72, v73, 0
	v_add_u32_e32 v71, 0x4400, v69
	global_store_short v71, v73, s[0:1]
	s_waitcnt vmcnt(33)
	v_add_f32_e32 v72, v189, v60
	v_mul_f32_e32 v72, v190, v72
	v_cvt_f32_f16_e32 v73, v107
	v_add_u32_e32 v70, 0x7b400, v68
	global_load_ushort v107, v70, s[2:3]
	v_mul_f32_e32 v74, 0xbfb8aa3b, v73
	v_exp_f32_e32 v74, v74
	s_nop 0
	v_add_f32_e32 v74, 1.0, v74
	v_div_scale_f32 v75, vcc, v74, v74, v73
	v_rcp_f32_e32 v76, v75
	v_div_scale_f32 v77, vcc, v73, v74, v73
	v_fma_f32 v78, -v75, v76, 1.0
	v_fmac_f32_e32 v76, v78, v76
	v_mul_f32_e32 v78, v77, v76
	v_fma_f32 v79, -v75, v78, v77
	v_fmac_f32_e32 v78, v79, v76
	v_fma_f32 v75, -v75, v78, v77
	v_div_fmas_f32 v75, v75, v76, v78
	v_div_fixup_f32 v73, v75, v74, v73
	v_fma_mixlo_f16 v73, v72, v73, 0
	v_add_u32_e32 v71, 0x4800, v69
	global_store_short v71, v73, s[0:1]
	s_waitcnt vmcnt(34)
	v_add_f32_e32 v72, v189, v61
	v_mul_f32_e32 v72, v190, v72
	v_cvt_f32_f16_e32 v73, v108
	v_add_u32_e32 v70, 0x7ee00, v68
	global_load_ushort v108, v70, s[2:3]
	v_mul_f32_e32 v74, 0xbfb8aa3b, v73
	v_exp_f32_e32 v74, v74
	s_nop 0
	v_add_f32_e32 v74, 1.0, v74
	v_div_scale_f32 v75, vcc, v74, v74, v73
	v_rcp_f32_e32 v76, v75
	v_div_scale_f32 v77, vcc, v73, v74, v73
	v_fma_f32 v78, -v75, v76, 1.0
	v_fmac_f32_e32 v76, v78, v76
	v_mul_f32_e32 v78, v77, v76
	v_fma_f32 v79, -v75, v78, v77
	v_fmac_f32_e32 v78, v79, v76
	v_fma_f32 v75, -v75, v78, v77
	v_div_fmas_f32 v75, v75, v76, v78
	v_div_fixup_f32 v73, v75, v74, v73
	v_fma_mixlo_f16 v73, v72, v73, 0
	v_add_u32_e32 v71, 0x4c00, v69
	global_store_short v71, v73, s[0:1]
	s_waitcnt vmcnt(35)
;   __device__ __forceinline__ half_t* u() const { return (half_t*)(ws() + OFF_u); }
;   __device__ __forceinline__ half_t* ya() const { return (half_t*)(ws() + OFF_ya); }
; __device__ __forceinline__ float siluf_(float x) { return x / (1.f + __expf(-x)); }
; template <int NI, class LA, class LB, class EP>
; __device__ __forceinline__ void gemm_tile(int K, LA loadA, LB loadB, EP epi, char* smem) {
;     ...
; #pragma unroll
;   for (int mi = 0; mi < 2; ++mi)
; #pragma unroll
;     for (int ni = 0; ni < NI; ++ni)
; #pragma unroll
;       for (int r = 0; r < 16; ++r) {
;         const int row = wm * 64 + mi * 32 + (r & 3) + 8 * (r >> 2) + 4 * (lane >> 5);
;         const int col = wn * (NI * 32) + ni * 32 + (lane & 31);
;         epi(mi, ni, r, row, col, acc[mi][ni][r]);
;       }
; __device__ __forceinline__ void pool_item(const KP& p, int l, int item, char* smem) {
;     ...
;       [&](int mi, int ni, int r, int row, int col, float v) {
;         const int tok = m0 + row;
;         const float z = (float)p.u()[(size_t)tok * NU + C_AZ + g * 128 + col];
;         p.ya()[(size_t)tok * 512 + g * 128 + col] = (half_t)((v + pb[ni]) * ps[ni] * siluf_(z));
;       },
	v_add_f32_e32 v72, v189, v62
	v_mul_f32_e32 v72, v190, v72
	v_cvt_f32_f16_e32 v73, v109
	v_add_u32_e32 v70, 0x91000, v68
	global_load_ushort v109, v70, s[2:3]
	v_mul_f32_e32 v74, 0xbfb8aa3b, v73
	v_exp_f32_e32 v74, v74
	s_nop 0
	v_add_f32_e32 v74, 1.0, v74
	v_div_scale_f32 v75, vcc, v74, v74, v73
	v_rcp_f32_e32 v76, v75
	v_div_scale_f32 v77, vcc, v73, v74, v73
	v_fma_f32 v78, -v75, v76, 1.0
	v_fmac_f32_e32 v76, v78, v76
	v_mul_f32_e32 v78, v77, v76
	v_fma_f32 v79, -v75, v78, v77
	v_fmac_f32_e32 v78, v79, v76
	v_fma_f32 v75, -v75, v78, v77
	v_div_fmas_f32 v75, v75, v76, v78
	v_div_fixup_f32 v73, v75, v74, v73
	v_fma_mixlo_f16 v73, v72, v73, 0
	v_add_u32_e32 v71, 0x6000, v69
	global_store_short v71, v73, s[0:1]
	s_waitcnt vmcnt(36)
	v_add_f32_e32 v72, v189, v63
	v_mul_f32_e32 v72, v190, v72
	v_cvt_f32_f16_e32 v73, v110
	v_add_u32_e32 v70, 0x94a00, v68
	global_load_ushort v110, v70, s[2:3]
	v_mul_f32_e32 v74, 0xbfb8aa3b, v73
	v_exp_f32_e32 v74, v74
	s_nop 0
	v_add_f32_e32 v74, 1.0, v74
	v_div_scale_f32 v75, vcc, v74, v74, v73
	v_rcp_f32_e32 v76, v75
	v_div_scale_f32 v77, vcc, v73, v74, v73
	v_fma_f32 v78, -v75, v76, 1.0
	v_fmac_f32_e32 v76, v78, v76
	v_mul_f32_e32 v78, v77, v76
	v_fma_f32 v79, -v75, v78, v77
	v_fmac_f32_e32 v78, v79, v76
	v_fma_f32 v75, -v75, v78, v77
	v_div_fmas_f32 v75, v75, v76, v78
	v_div_fixup_f32 v73, v75, v74, v73
	v_fma_mixlo_f16 v73, v72, v73, 0
	v_add_u32_e32 v71, 0x6400, v69
	global_store_short v71, v73, s[0:1]
	s_waitcnt vmcnt(37)
	v_add_f32_e32 v72, v189, v64
	v_mul_f32_e32 v72, v190, v72
	v_cvt_f32_f16_e32 v73, v111
	v_add_u32_e32 v70, 0x98400, v68
	global_load_ushort v111, v70, s[2:3]
	v_mul_f32_e32 v74, 0xbfb8aa3b, v73
	v_exp_f32_e32 v74, v74
	s_nop 0
	v_add_f32_e32 v74, 1.0, v74
	v_div_scale_f32 v75, vcc, v74, v74, v73
	v_rcp_f32_e32 v76, v75
	v_div_scale_f32 v77, vcc, v73, v74, v73
	v_fma_f32 v78, -v75, v76, 1.0
	v_fmac_f32_e32 v76, v78, v76
	v_mul_f32_e32 v78, v77, v76
	v_fma_f32 v79, -v75, v78, v77
	v_fmac_f32_e32 v78, v79, v76
	v_fma_f32 v75, -v75, v78, v77
	v_div_fmas_f32 v75, v75, v76, v78
	v_div_fixup_f32 v73, v75, v74, v73
	v_fma_mixlo_f16 v73, v72, v73, 0
	v_add_u32_e32 v71, 0x6800, v69
	global_store_short v71, v73, s[0:1]
	s_waitcnt vmcnt(38)
	v_add_f32_e32 v72, v189, v65
	v_mul_f32_e32 v72, v190, v72
	v_cvt_f32_f16_e32 v73, v112
	v_add_u32_e32 v70, 0x9be00, v68
	global_load_ushort v112, v70, s[2:3]
	v_mul_f32_e32 v74, 0xbfb8aa3b, v73
	v_exp_f32_e32 v74, v74
	s_nop 0
	v_add_f32_e32 v74, 1.0, v74
	v_div_scale_f32 v75, vcc, v74, v74, v73
	v_rcp_f32_e32 v76, v75
	v_div_scale_f32 v77, vcc, v73, v74, v73
	v_fma_f32 v78, -v75, v76, 1.0
	v_fmac_f32_e32 v76, v78, v76
	v_mul_f32_e32 v78, v77, v76
	v_fma_f32 v79, -v75, v78, v77
	v_fmac_f32_e32 v78, v79, v76
	v_fma_f32 v75, -v75, v78, v77
	v_div_fmas_f32 v75, v75, v76, v78
	v_div_fixup_f32 v73, v75, v74, v73
	v_fma_mixlo_f16 v73, v72, v73, 0
	v_add_u32_e32 v71, 0x6c00, v69
	global_store_short v71, v73, s[0:1]
	s_waitcnt vmcnt(39)
	v_add_f32_e32 v72, v188, v34
	v_mul_f32_e32 v72, v187, v72
	v_cvt_f32_f16_e32 v73, v113
	v_add_u32_e32 v70, 0xae000, v68
	global_load_ushort v113, v70, s[2:3]
	v_mul_f32_e32 v74, 0xbfb8aa3b, v73
	v_exp_f32_e32 v74, v74
	s_nop 0
	v_add_f32_e32 v74, 1.0, v74
	v_div_scale_f32 v75, vcc, v74, v74, v73
	v_rcp_f32_e32 v76, v75
	v_div_scale_f32 v77, vcc, v73, v74, v73
	v_fma_f32 v78, -v75, v76, 1.0
	v_fmac_f32_e32 v76, v78, v76
	v_mul_f32_e32 v78, v77, v76
	v_fma_f32 v79, -v75, v78, v77
	v_fmac_f32_e32 v78, v79, v76
	v_fma_f32 v75, -v75, v78, v77
	v_div_fmas_f32 v75, v75, v76, v78
	v_div_fixup_f32 v73, v75, v74, v73
	v_fma_mixlo_f16 v73, v72, v73, 0
	v_mov_b32_e32 v71, v69
	global_store_short v71, v73, s[0:1] offset:64
	s_waitcnt vmcnt(40)
	v_add_f32_e32 v72, v188, v35
	v_mul_f32_e32 v72, v187, v72
	v_cvt_f32_f16_e32 v73, v114
	v_add_u32_e32 v70, 0xb1a00, v68
	global_load_ushort v114, v70, s[2:3]
	v_mul_f32_e32 v74, 0xbfb8aa3b, v73
	v_exp_f32_e32 v74, v74
	s_nop 0
	v_add_f32_e32 v74, 1.0, v74
	v_div_scale_f32 v75, vcc, v74, v74, v73
	v_rcp_f32_e32 v76, v75
	v_div_scale_f32 v77, vcc, v73, v74, v73
	v_fma_f32 v78, -v75, v76, 1.0
	v_fmac_f32_e32 v76, v78, v76
	v_mul_f32_e32 v78, v77, v76
	v_fma_f32 v79, -v75, v78, v77
	v_fmac_f32_e32 v78, v79, v76
	v_fma_f32 v75, -v75, v78, v77
	v_div_fmas_f32 v75, v75, v76, v78
	v_div_fixup_f32 v73, v75, v74, v73
	v_fma_mixlo_f16 v73, v72, v73, 0
	v_add_u32_e32 v71, 0x400, v69
	global_store_short v71, v73, s[0:1] offset:64
	s_waitcnt vmcnt(41)
	v_add_f32_e32 v72, v188, v36
	v_mul_f32_e32 v72, v187, v72
	v_cvt_f32_f16_e32 v73, v115
	v_add_u32_e32 v70, 0xb5400, v68
	global_load_ushort v115, v70, s[2:3]
	v_mul_f32_e32 v74, 0xbfb8aa3b, v73
	v_exp_f32_e32 v74, v74
	s_nop 0
	v_add_f32_e32 v74, 1.0, v74
	v_div_scale_f32 v75, vcc, v74, v74, v73
	v_rcp_f32_e32 v76, v75
	v_div_scale_f32 v77, vcc, v73, v74, v73
	v_fma_f32 v78, -v75, v76, 1.0
	v_fmac_f32_e32 v76, v78, v76
	v_mul_f32_e32 v78, v77, v76
	v_fma_f32 v79, -v75, v78, v77
	v_fmac_f32_e32 v78, v79, v76
	v_fma_f32 v75, -v75, v78, v77
	v_div_fmas_f32 v75, v75, v76, v78
	v_div_fixup_f32 v73, v75, v74, v73
	v_fma_mixlo_f16 v73, v72, v73, 0
	v_add_u32_e32 v71, 0x800, v69
	global_store_short v71, v73, s[0:1] offset:64
	s_waitcnt vmcnt(42)
	v_add_f32_e32 v72, v188, v37
	v_mul_f32_e32 v72, v187, v72
	v_cvt_f32_f16_e32 v73, v116
	v_add_u32_e32 v70, 0xb8e00, v68
	global_load_ushort v116, v70, s[2:3]
	v_mul_f32_e32 v74, 0xbfb8aa3b, v73
	v_exp_f32_e32 v74, v74
	s_nop 0
	v_add_f32_e32 v74, 1.0, v74
	v_div_scale_f32 v75, vcc, v74, v74, v73
	v_rcp_f32_e32 v76, v75
	v_div_scale_f32 v77, vcc, v73, v74, v73
	v_fma_f32 v78, -v75, v76, 1.0
	v_fmac_f32_e32 v76, v78, v76
	v_mul_f32_e32 v78, v77, v76
	v_fma_f32 v79, -v75, v78, v77
	v_fmac_f32_e32 v78, v79, v76
	v_fma_f32 v75, -v75, v78, v77
	v_div_fmas_f32 v75, v75, v76, v78
	v_div_fixup_f32 v73, v75, v74, v73
	v_fma_mixlo_f16 v73, v72, v73, 0
	v_add_u32_e32 v71, 0xc00, v69
	global_store_short v71, v73, s[0:1] offset:64
	s_waitcnt vmcnt(43)
;   __device__ __forceinline__ half_t* u() const { return (half_t*)(ws() + OFF_u); }
;   __device__ __forceinline__ half_t* ya() const { return (half_t*)(ws() + OFF_ya); }
; __device__ __forceinline__ float siluf_(float x) { return x / (1.f + __expf(-x)); }
; template <int NI, class LA, class LB, class EP>
; __device__ __forceinline__ void gemm_tile(int K, LA loadA, LB loadB, EP epi, char* smem) {
;     ...
; #pragma unroll
;   for (int mi = 0; mi < 2; ++mi)
; #pragma unroll
;     for (int ni = 0; ni < NI; ++ni)
; #pragma unroll
;       for (int r = 0; r < 16; ++r) {
;         const int row = wm * 64 + mi * 32 + (r & 3) + 8 * (r >> 2) + 4 * (lane >> 5);
;         const int col = wn * (NI * 32) + ni * 32 + (lane & 31);
;         epi(mi, ni, r, row, col, acc[mi][ni][r]);
;       }
; __device__ __forceinline__ void pool_item(const KP& p, int l, int item, char* smem) {
;     ...
;       [&](int mi, int ni, int r, int row, int col, float v) {
;         const int tok = m0 + row;
;         const float z = (float)p.u()[(size_t)tok * NU + C_AZ + g * 128 + col];
;         p.ya()[(size_t)tok * 512 + g * 128 + col] = (half_t)((v + pb[ni]) * ps[ni] * siluf_(z));
;       },
	v_add_f32_e32 v72, v188, v38
	v_mul_f32_e32 v72, v187, v72
	v_cvt_f32_f16_e32 v73, v117
	v_add_u32_e32 v70, 0xcb000, v68
	global_load_ushort v117, v70, s[2:3]
	v_mul_f32_e32 v74, 0xbfb8aa3b, v73
	v_exp_f32_e32 v74, v74
	s_nop 0
	v_add_f32_e32 v74, 1.0, v74
	v_div_scale_f32 v75, vcc, v74, v74, v73
	v_rcp_f32_e32 v76, v75
	v_div_scale_f32 v77, vcc, v73, v74, v73
	v_fma_f32 v78, -v75, v76, 1.0
	v_fmac_f32_e32 v76, v78, v76
	v_mul_f32_e32 v78, v77, v76
	v_fma_f32 v79, -v75, v78, v77
	v_fmac_f32_e32 v78, v79, v76
	v_fma_f32 v75, -v75, v78, v77
	v_div_fmas_f32 v75, v75, v76, v78
	v_div_fixup_f32 v73, v75, v74, v73
	v_fma_mixlo_f16 v73, v72, v73, 0
	v_add_u32_e32 v71, 0x2000, v69
	global_store_short v71, v73, s[0:1] offset:64
	s_waitcnt vmcnt(44)
	v_add_f32_e32 v72, v188, v39
	v_mul_f32_e32 v72, v187, v72
	v_cvt_f32_f16_e32 v73, v118
	v_add_u32_e32 v70, 0xcea00, v68
	global_load_ushort v118, v70, s[2:3]
	v_mul_f32_e32 v74, 0xbfb8aa3b, v73
	v_exp_f32_e32 v74, v74
	s_nop 0
	v_add_f32_e32 v74, 1.0, v74
	v_div_scale_f32 v75, vcc, v74, v74, v73
	v_rcp_f32_e32 v76, v75
	v_div_scale_f32 v77, vcc, v73, v74, v73
	v_fma_f32 v78, -v75, v76, 1.0
	v_fmac_f32_e32 v76, v78, v76
	v_mul_f32_e32 v78, v77, v76
	v_fma_f32 v79, -v75, v78, v77
	v_fmac_f32_e32 v78, v79, v76
	v_fma_f32 v75, -v75, v78, v77
	v_div_fmas_f32 v75, v75, v76, v78
	v_div_fixup_f32 v73, v75, v74, v73
	v_fma_mixlo_f16 v73, v72, v73, 0
	v_add_u32_e32 v71, 0x2400, v69
	global_store_short v71, v73, s[0:1] offset:64
	s_waitcnt vmcnt(45)
	v_add_f32_e32 v72, v188, v40
	v_mul_f32_e32 v72, v187, v72
	v_cvt_f32_f16_e32 v73, v119
	v_add_u32_e32 v70, 0xd2400, v68
	global_load_ushort v119, v70, s[2:3]
	v_mul_f32_e32 v74, 0xbfb8aa3b, v73
	v_exp_f32_e32 v74, v74
	s_nop 0
	v_add_f32_e32 v74, 1.0, v74
	v_div_scale_f32 v75, vcc, v74, v74, v73
	v_rcp_f32_e32 v76, v75
	v_div_scale_f32 v77, vcc, v73, v74, v73
	v_fma_f32 v78, -v75, v76, 1.0
	v_fmac_f32_e32 v76, v78, v76
	v_mul_f32_e32 v78, v77, v76
	v_fma_f32 v79, -v75, v78, v77
	v_fmac_f32_e32 v78, v79, v76
	v_fma_f32 v75, -v75, v78, v77
	v_div_fmas_f32 v75, v75, v76, v78
	v_div_fixup_f32 v73, v75, v74, v73
	v_fma_mixlo_f16 v73, v72, v73, 0
	v_add_u32_e32 v71, 0x2800, v69
	global_store_short v71, v73, s[0:1] offset:64
	s_waitcnt vmcnt(46)
	v_add_f32_e32 v72, v188, v41
	v_mul_f32_e32 v72, v187, v72
	v_cvt_f32_f16_e32 v73, v120
	v_add_u32_e32 v70, 0xd5e00, v68
	global_load_ushort v120, v70, s[2:3]
	v_mul_f32_e32 v74, 0xbfb8aa3b, v73
	v_exp_f32_e32 v74, v74
	s_nop 0
	v_add_f32_e32 v74, 1.0, v74
	v_div_scale_f32 v75, vcc, v74, v74, v73
	v_rcp_f32_e32 v76, v75
	v_div_scale_f32 v77, vcc, v73, v74, v73
	v_fma_f32 v78, -v75, v76, 1.0
	v_fmac_f32_e32 v76, v78, v76
	v_mul_f32_e32 v78, v77, v76
	v_fma_f32 v79, -v75, v78, v77
	v_fmac_f32_e32 v78, v79, v76
	v_fma_f32 v75, -v75, v78, v77
	v_div_fmas_f32 v75, v75, v76, v78
	v_div_fixup_f32 v73, v75, v74, v73
	v_fma_mixlo_f16 v73, v72, v73, 0
	v_add_u32_e32 v71, 0x2c00, v69
	global_store_short v71, v73, s[0:1] offset:64
	s_waitcnt vmcnt(47)
	v_add_f32_e32 v72, v188, v42
	v_mul_f32_e32 v72, v187, v72
	v_cvt_f32_f16_e32 v73, v97
	v_add_u32_e32 v70, 0x74000, v68
	global_load_ushort v97, v70, s[2:3] offset:64
	v_mul_f32_e32 v74, 0xbfb8aa3b, v73
	v_exp_f32_e32 v74, v74
	s_nop 0
	v_add_f32_e32 v74, 1.0, v74
	v_div_scale_f32 v75, vcc, v74, v74, v73
	v_rcp_f32_e32 v76, v75
	v_div_scale_f32 v77, vcc, v73, v74, v73
	v_fma_f32 v78, -v75, v76, 1.0
	v_fmac_f32_e32 v76, v78, v76
	v_mul_f32_e32 v78, v77, v76
	v_fma_f32 v79, -v75, v78, v77
	v_fmac_f32_e32 v78, v79, v76
	v_fma_f32 v75, -v75, v78, v77
	v_div_fmas_f32 v75, v75, v76, v78
	v_div_fixup_f32 v73, v75, v74, v73
	v_fma_mixlo_f16 v73, v72, v73, 0
	v_add_u32_e32 v71, 0x4000, v69
	global_store_short v71, v73, s[0:1] offset:64
	s_waitcnt vmcnt(47)
	v_add_f32_e32 v72, v188, v43
	v_mul_f32_e32 v72, v187, v72
	v_cvt_f32_f16_e32 v73, v98
	v_add_u32_e32 v70, 0x77a00, v68
	global_load_ushort v98, v70, s[2:3] offset:64
	v_mul_f32_e32 v74, 0xbfb8aa3b, v73
	v_exp_f32_e32 v74, v74
	s_nop 0
	v_add_f32_e32 v74, 1.0, v74
	v_div_scale_f32 v75, vcc, v74, v74, v73
	v_rcp_f32_e32 v76, v75
	v_div_scale_f32 v77, vcc, v73, v74, v73
	v_fma_f32 v78, -v75, v76, 1.0
	v_fmac_f32_e32 v76, v78, v76
	v_mul_f32_e32 v78, v77, v76
	v_fma_f32 v79, -v75, v78, v77
	v_fmac_f32_e32 v78, v79, v76
	v_fma_f32 v75, -v75, v78, v77
	v_div_fmas_f32 v75, v75, v76, v78
	v_div_fixup_f32 v73, v75, v74, v73
	v_fma_mixlo_f16 v73, v72, v73, 0
	v_add_u32_e32 v71, 0x4400, v69
	global_store_short v71, v73, s[0:1] offset:64
	s_waitcnt vmcnt(47)
	v_add_f32_e32 v72, v188, v44
	v_mul_f32_e32 v72, v187, v72
	v_cvt_f32_f16_e32 v73, v99
	v_add_u32_e32 v70, 0x7b400, v68
	global_load_ushort v99, v70, s[2:3] offset:64
	v_mul_f32_e32 v74, 0xbfb8aa3b, v73
	v_exp_f32_e32 v74, v74
	s_nop 0
	v_add_f32_e32 v74, 1.0, v74
	v_div_scale_f32 v75, vcc, v74, v74, v73
	v_rcp_f32_e32 v76, v75
	v_div_scale_f32 v77, vcc, v73, v74, v73
	v_fma_f32 v78, -v75, v76, 1.0
	v_fmac_f32_e32 v76, v78, v76
	v_mul_f32_e32 v78, v77, v76
	v_fma_f32 v79, -v75, v78, v77
	v_fmac_f32_e32 v78, v79, v76
	v_fma_f32 v75, -v75, v78, v77
	v_div_fmas_f32 v75, v75, v76, v78
	v_div_fixup_f32 v73, v75, v74, v73
	v_fma_mixlo_f16 v73, v72, v73, 0
	v_add_u32_e32 v71, 0x4800, v69
	global_store_short v71, v73, s[0:1] offset:64
	s_waitcnt vmcnt(47)
;   __device__ __forceinline__ half_t* u() const { return (half_t*)(ws() + OFF_u); }
;   __device__ __forceinline__ half_t* ya() const { return (half_t*)(ws() + OFF_ya); }
; __device__ __forceinline__ float siluf_(float x) { return x / (1.f + __expf(-x)); }
; template <int NI, class LA, class LB, class EP>
; __device__ __forceinline__ void gemm_tile(int K, LA loadA, LB loadB, EP epi, char* smem) {
;     ...
; #pragma unroll
;   for (int mi = 0; mi < 2; ++mi)
; #pragma unroll
;     for (int ni = 0; ni < NI; ++ni)
; #pragma unroll
;       for (int r = 0; r < 16; ++r) {
;         const int row = wm * 64 + mi * 32 + (r & 3) + 8 * (r >> 2) + 4 * (lane >> 5);
;         const int col = wn * (NI * 32) + ni * 32 + (lane & 31);
;         epi(mi, ni, r, row, col, acc[mi][ni][r]);
;       }
; __device__ __forceinline__ void pool_item(const KP& p, int l, int item, char* smem) {
;     ...
;       [&](int mi, int ni, int r, int row, int col, float v) {
;         const int tok = m0 + row;
;         const float z = (float)p.u()[(size_t)tok * NU + C_AZ + g * 128 + col];
;         p.ya()[(size_t)tok * 512 + g * 128 + col] = (half_t)((v + pb[ni]) * ps[ni] * siluf_(z));
;       },
	v_add_f32_e32 v72, v188, v45
	v_mul_f32_e32 v72, v187, v72
	v_cvt_f32_f16_e32 v73, v100
	v_add_u32_e32 v70, 0x7ee00, v68
	global_load_ushort v100, v70, s[2:3] offset:64
	v_mul_f32_e32 v74, 0xbfb8aa3b, v73
	v_exp_f32_e32 v74, v74
	s_nop 0
	v_add_f32_e32 v74, 1.0, v74
	v_div_scale_f32 v75, vcc, v74, v74, v73
	v_rcp_f32_e32 v76, v75
	v_div_scale_f32 v77, vcc, v73, v74, v73
	v_fma_f32 v78, -v75, v76, 1.0
	v_fmac_f32_e32 v76, v78, v76
	v_mul_f32_e32 v78, v77, v76
	v_fma_f32 v79, -v75, v78, v77
	v_fmac_f32_e32 v78, v79, v76
	v_fma_f32 v75, -v75, v78, v77
	v_div_fmas_f32 v75, v75, v76, v78
	v_div_fixup_f32 v73, v75, v74, v73
	v_fma_mixlo_f16 v73, v72, v73, 0
	v_add_u32_e32 v71, 0x4c00, v69
	global_store_short v71, v73, s[0:1] offset:64
	s_waitcnt vmcnt(47)
	v_add_f32_e32 v72, v188, v46
	v_mul_f32_e32 v72, v187, v72
	v_cvt_f32_f16_e32 v73, v101
	v_add_u32_e32 v70, 0x91000, v68
	global_load_ushort v101, v70, s[2:3] offset:64
	v_mul_f32_e32 v74, 0xbfb8aa3b, v73
	v_exp_f32_e32 v74, v74
	s_nop 0
	v_add_f32_e32 v74, 1.0, v74
	v_div_scale_f32 v75, vcc, v74, v74, v73
	v_rcp_f32_e32 v76, v75
	v_div_scale_f32 v77, vcc, v73, v74, v73
	v_fma_f32 v78, -v75, v76, 1.0
	v_fmac_f32_e32 v76, v78, v76
	v_mul_f32_e32 v78, v77, v76
	v_fma_f32 v79, -v75, v78, v77
	v_fmac_f32_e32 v78, v79, v76
	v_fma_f32 v75, -v75, v78, v77
	v_div_fmas_f32 v75, v75, v76, v78
	v_div_fixup_f32 v73, v75, v74, v73
	v_fma_mixlo_f16 v73, v72, v73, 0
	v_add_u32_e32 v71, 0x6000, v69
	global_store_short v71, v73, s[0:1] offset:64
	s_waitcnt vmcnt(47)
	v_add_f32_e32 v72, v188, v47
	v_mul_f32_e32 v72, v187, v72
	v_cvt_f32_f16_e32 v73, v102
	v_add_u32_e32 v70, 0x94a00, v68
	global_load_ushort v102, v70, s[2:3] offset:64
	v_mul_f32_e32 v74, 0xbfb8aa3b, v73
	v_exp_f32_e32 v74, v74
	s_nop 0
	v_add_f32_e32 v74, 1.0, v74
	v_div_scale_f32 v75, vcc, v74, v74, v73
	v_rcp_f32_e32 v76, v75
	v_div_scale_f32 v77, vcc, v73, v74, v73
	v_fma_f32 v78, -v75, v76, 1.0
	v_fmac_f32_e32 v76, v78, v76
	v_mul_f32_e32 v78, v77, v76
	v_fma_f32 v79, -v75, v78, v77
	v_fmac_f32_e32 v78, v79, v76
	v_fma_f32 v75, -v75, v78, v77
	v_div_fmas_f32 v75, v75, v76, v78
	v_div_fixup_f32 v73, v75, v74, v73
	v_fma_mixlo_f16 v73, v72, v73, 0
	v_add_u32_e32 v71, 0x6400, v69
	global_store_short v71, v73, s[0:1] offset:64
	s_waitcnt vmcnt(47)
	v_add_f32_e32 v72, v188, v48
	v_mul_f32_e32 v72, v187, v72
	v_cvt_f32_f16_e32 v73, v103
	v_add_u32_e32 v70, 0x98400, v68
	global_load_ushort v103, v70, s[2:3] offset:64
	v_mul_f32_e32 v74, 0xbfb8aa3b, v73
	v_exp_f32_e32 v74, v74
	s_nop 0
	v_add_f32_e32 v74, 1.0, v74
	v_div_scale_f32 v75, vcc, v74, v74, v73
	v_rcp_f32_e32 v76, v75
	v_div_scale_f32 v77, vcc, v73, v74, v73
	v_fma_f32 v78, -v75, v76, 1.0
	v_fmac_f32_e32 v76, v78, v76
	v_mul_f32_e32 v78, v77, v76
	v_fma_f32 v79, -v75, v78, v77
	v_fmac_f32_e32 v78, v79, v76
	v_fma_f32 v75, -v75, v78, v77
	v_div_fmas_f32 v75, v75, v76, v78
	v_div_fixup_f32 v73, v75, v74, v73
	v_fma_mixlo_f16 v73, v72, v73, 0
	v_add_u32_e32 v71, 0x6800, v69
	global_store_short v71, v73, s[0:1] offset:64
	s_waitcnt vmcnt(47)
	v_add_f32_e32 v72, v188, v49
	v_mul_f32_e32 v72, v187, v72
	v_cvt_f32_f16_e32 v73, v104
	v_add_u32_e32 v70, 0x9be00, v68
	global_load_ushort v104, v70, s[2:3] offset:64
	v_mul_f32_e32 v74, 0xbfb8aa3b, v73
	v_exp_f32_e32 v74, v74
	s_nop 0
	v_add_f32_e32 v74, 1.0, v74
	v_div_scale_f32 v75, vcc, v74, v74, v73
	v_rcp_f32_e32 v76, v75
	v_div_scale_f32 v77, vcc, v73, v74, v73
	v_fma_f32 v78, -v75, v76, 1.0
	v_fmac_f32_e32 v76, v78, v76
	v_mul_f32_e32 v78, v77, v76
	v_fma_f32 v79, -v75, v78, v77
	v_fmac_f32_e32 v78, v79, v76
	v_fma_f32 v75, -v75, v78, v77
	v_div_fmas_f32 v75, v75, v76, v78
	v_div_fixup_f32 v73, v75, v74, v73
	v_fma_mixlo_f16 v73, v72, v73, 0
	v_add_u32_e32 v71, 0x6c00, v69
	global_store_short v71, v73, s[0:1] offset:64
	s_waitcnt vmcnt(47)
	v_add_f32_e32 v72, v189, v18
	v_mul_f32_e32 v72, v190, v72
	v_cvt_f32_f16_e32 v73, v105
	v_add_u32_e32 v70, 0xae000, v68
	global_load_ushort v105, v70, s[2:3] offset:64
	v_mul_f32_e32 v74, 0xbfb8aa3b, v73
	v_exp_f32_e32 v74, v74
	s_nop 0
	v_add_f32_e32 v74, 1.0, v74
	v_div_scale_f32 v75, vcc, v74, v74, v73
	v_rcp_f32_e32 v76, v75
	v_div_scale_f32 v77, vcc, v73, v74, v73
	v_fma_f32 v78, -v75, v76, 1.0
	v_fmac_f32_e32 v76, v78, v76
	v_mul_f32_e32 v78, v77, v76
	v_fma_f32 v79, -v75, v78, v77
	v_fmac_f32_e32 v78, v79, v76
	v_fma_f32 v75, -v75, v78, v77
	v_div_fmas_f32 v75, v75, v76, v78
	v_div_fixup_f32 v73, v75, v74, v73
	v_fma_mixlo_f16 v73, v72, v73, 0
	v_add_u32_e32 v71, 0x8000, v69
	global_store_short v71, v73, s[0:1]
	s_waitcnt vmcnt(47)
	v_add_f32_e32 v72, v189, v19
	v_mul_f32_e32 v72, v190, v72
	v_cvt_f32_f16_e32 v73, v106
	v_add_u32_e32 v70, 0xb1a00, v68
	global_load_ushort v106, v70, s[2:3] offset:64
	v_mul_f32_e32 v74, 0xbfb8aa3b, v73
	v_exp_f32_e32 v74, v74
	s_nop 0
	v_add_f32_e32 v74, 1.0, v74
	v_div_scale_f32 v75, vcc, v74, v74, v73
	v_rcp_f32_e32 v76, v75
	v_div_scale_f32 v77, vcc, v73, v74, v73
	v_fma_f32 v78, -v75, v76, 1.0
	v_fmac_f32_e32 v76, v78, v76
	v_mul_f32_e32 v78, v77, v76
	v_fma_f32 v79, -v75, v78, v77
	v_fmac_f32_e32 v78, v79, v76
	v_fma_f32 v75, -v75, v78, v77
	v_div_fmas_f32 v75, v75, v76, v78
	v_div_fixup_f32 v73, v75, v74, v73
	v_fma_mixlo_f16 v73, v72, v73, 0
	v_add_u32_e32 v71, 0x8400, v69
	global_store_short v71, v73, s[0:1]
	s_waitcnt vmcnt(47)
;   __device__ __forceinline__ half_t* u() const { return (half_t*)(ws() + OFF_u); }
;   __device__ __forceinline__ half_t* ya() const { return (half_t*)(ws() + OFF_ya); }
; __device__ __forceinline__ float siluf_(float x) { return x / (1.f + __expf(-x)); }
; template <int NI, class LA, class LB, class EP>
; __device__ __forceinline__ void gemm_tile(int K, LA loadA, LB loadB, EP epi, char* smem) {
;     ...
; #pragma unroll
;   for (int mi = 0; mi < 2; ++mi)
; #pragma unroll
;     for (int ni = 0; ni < NI; ++ni)
; #pragma unroll
;       for (int r = 0; r < 16; ++r) {
;         const int row = wm * 64 + mi * 32 + (r & 3) + 8 * (r >> 2) + 4 * (lane >> 5);
;         const int col = wn * (NI * 32) + ni * 32 + (lane & 31);
;         epi(mi, ni, r, row, col, acc[mi][ni][r]);
;       }
; __device__ __forceinline__ void pool_item(const KP& p, int l, int item, char* smem) {
;     ...
;       [&](int mi, int ni, int r, int row, int col, float v) {
;         const int tok = m0 + row;
;         const float z = (float)p.u()[(size_t)tok * NU + C_AZ + g * 128 + col];
;         p.ya()[(size_t)tok * 512 + g * 128 + col] = (half_t)((v + pb[ni]) * ps[ni] * siluf_(z));
;       },
	v_add_f32_e32 v72, v189, v20
	v_mul_f32_e32 v72, v190, v72
	v_cvt_f32_f16_e32 v73, v107
	v_add_u32_e32 v70, 0xb5400, v68
	global_load_ushort v107, v70, s[2:3] offset:64
	v_mul_f32_e32 v74, 0xbfb8aa3b, v73
	v_exp_f32_e32 v74, v74
	s_nop 0
	v_add_f32_e32 v74, 1.0, v74
	v_div_scale_f32 v75, vcc, v74, v74, v73
	v_rcp_f32_e32 v76, v75
	v_div_scale_f32 v77, vcc, v73, v74, v73
	v_fma_f32 v78, -v75, v76, 1.0
	v_fmac_f32_e32 v76, v78, v76
	v_mul_f32_e32 v78, v77, v76
	v_fma_f32 v79, -v75, v78, v77
	v_fmac_f32_e32 v78, v79, v76
	v_fma_f32 v75, -v75, v78, v77
	v_div_fmas_f32 v75, v75, v76, v78
	v_div_fixup_f32 v73, v75, v74, v73
	v_fma_mixlo_f16 v73, v72, v73, 0
	v_add_u32_e32 v71, 0x8800, v69
	global_store_short v71, v73, s[0:1]
	s_waitcnt vmcnt(47)
	v_add_f32_e32 v72, v189, v21
	v_mul_f32_e32 v72, v190, v72
	v_cvt_f32_f16_e32 v73, v108
	v_add_u32_e32 v70, 0xb8e00, v68
	global_load_ushort v108, v70, s[2:3] offset:64
	v_mul_f32_e32 v74, 0xbfb8aa3b, v73
	v_exp_f32_e32 v74, v74
	s_nop 0
	v_add_f32_e32 v74, 1.0, v74
	v_div_scale_f32 v75, vcc, v74, v74, v73
	v_rcp_f32_e32 v76, v75
	v_div_scale_f32 v77, vcc, v73, v74, v73
	v_fma_f32 v78, -v75, v76, 1.0
	v_fmac_f32_e32 v76, v78, v76
	v_mul_f32_e32 v78, v77, v76
	v_fma_f32 v79, -v75, v78, v77
	v_fmac_f32_e32 v78, v79, v76
	v_fma_f32 v75, -v75, v78, v77
	v_div_fmas_f32 v75, v75, v76, v78
	v_div_fixup_f32 v73, v75, v74, v73
	v_fma_mixlo_f16 v73, v72, v73, 0
	v_add_u32_e32 v71, 0x8c00, v69
	global_store_short v71, v73, s[0:1]
	s_waitcnt vmcnt(47)
	v_add_f32_e32 v72, v189, v22
	v_mul_f32_e32 v72, v190, v72
	v_cvt_f32_f16_e32 v73, v109
	v_add_u32_e32 v70, 0xcb000, v68
	global_load_ushort v109, v70, s[2:3] offset:64
	v_mul_f32_e32 v74, 0xbfb8aa3b, v73
	v_exp_f32_e32 v74, v74
	s_nop 0
	v_add_f32_e32 v74, 1.0, v74
	v_div_scale_f32 v75, vcc, v74, v74, v73
	v_rcp_f32_e32 v76, v75
	v_div_scale_f32 v77, vcc, v73, v74, v73
	v_fma_f32 v78, -v75, v76, 1.0
	v_fmac_f32_e32 v76, v78, v76
	v_mul_f32_e32 v78, v77, v76
	v_fma_f32 v79, -v75, v78, v77
	v_fmac_f32_e32 v78, v79, v76
	v_fma_f32 v75, -v75, v78, v77
	v_div_fmas_f32 v75, v75, v76, v78
	v_div_fixup_f32 v73, v75, v74, v73
	v_fma_mixlo_f16 v73, v72, v73, 0
	v_add_u32_e32 v71, 0xa000, v69
	global_store_short v71, v73, s[0:1]
	s_waitcnt vmcnt(47)
	v_add_f32_e32 v72, v189, v23
	v_mul_f32_e32 v72, v190, v72
	v_cvt_f32_f16_e32 v73, v110
	v_add_u32_e32 v70, 0xcea00, v68
	global_load_ushort v110, v70, s[2:3] offset:64
	v_mul_f32_e32 v74, 0xbfb8aa3b, v73
	v_exp_f32_e32 v74, v74
	s_nop 0
	v_add_f32_e32 v74, 1.0, v74
	v_div_scale_f32 v75, vcc, v74, v74, v73
	v_rcp_f32_e32 v76, v75
	v_div_scale_f32 v77, vcc, v73, v74, v73
	v_fma_f32 v78, -v75, v76, 1.0
	v_fmac_f32_e32 v76, v78, v76
	v_mul_f32_e32 v78, v77, v76
	v_fma_f32 v79, -v75, v78, v77
	v_fmac_f32_e32 v78, v79, v76
	v_fma_f32 v75, -v75, v78, v77
	v_div_fmas_f32 v75, v75, v76, v78
	v_div_fixup_f32 v73, v75, v74, v73
	v_fma_mixlo_f16 v73, v72, v73, 0
	v_add_u32_e32 v71, 0xa400, v69
	global_store_short v71, v73, s[0:1]
	s_waitcnt vmcnt(47)
	v_add_f32_e32 v72, v189, v24
	v_mul_f32_e32 v72, v190, v72
	v_cvt_f32_f16_e32 v73, v111
	v_add_u32_e32 v70, 0xd2400, v68
	global_load_ushort v111, v70, s[2:3] offset:64
	v_mul_f32_e32 v74, 0xbfb8aa3b, v73
	v_exp_f32_e32 v74, v74
	s_nop 0
	v_add_f32_e32 v74, 1.0, v74
	v_div_scale_f32 v75, vcc, v74, v74, v73
	v_rcp_f32_e32 v76, v75
	v_div_scale_f32 v77, vcc, v73, v74, v73
	v_fma_f32 v78, -v75, v76, 1.0
	v_fmac_f32_e32 v76, v78, v76
	v_mul_f32_e32 v78, v77, v76
	v_fma_f32 v79, -v75, v78, v77
	v_fmac_f32_e32 v78, v79, v76
	v_fma_f32 v75, -v75, v78, v77
	v_div_fmas_f32 v75, v75, v76, v78
	v_div_fixup_f32 v73, v75, v74, v73
	v_fma_mixlo_f16 v73, v72, v73, 0
	v_add_u32_e32 v71, 0xa800, v69
	global_store_short v71, v73, s[0:1]
	s_waitcnt vmcnt(47)
	v_add_f32_e32 v72, v189, v25
	v_mul_f32_e32 v72, v190, v72
	v_cvt_f32_f16_e32 v73, v112
	v_add_u32_e32 v70, 0xd5e00, v68
	global_load_ushort v112, v70, s[2:3] offset:64
	v_mul_f32_e32 v74, 0xbfb8aa3b, v73
	v_exp_f32_e32 v74, v74
	s_nop 0
	v_add_f32_e32 v74, 1.0, v74
	v_div_scale_f32 v75, vcc, v74, v74, v73
	v_rcp_f32_e32 v76, v75
	v_div_scale_f32 v77, vcc, v73, v74, v73
	v_fma_f32 v78, -v75, v76, 1.0
	v_fmac_f32_e32 v76, v78, v76
	v_mul_f32_e32 v78, v77, v76
	v_fma_f32 v79, -v75, v78, v77
	v_fmac_f32_e32 v78, v79, v76
	v_fma_f32 v75, -v75, v78, v77
	v_div_fmas_f32 v75, v75, v76, v78
	v_div_fixup_f32 v73, v75, v74, v73
	v_fma_mixlo_f16 v73, v72, v73, 0
	v_add_u32_e32 v71, 0xac00, v69
	global_store_short v71, v73, s[0:1]
	s_waitcnt vmcnt(47)
	v_add_f32_e32 v72, v189, v26
	v_mul_f32_e32 v72, v190, v72
	v_cvt_f32_f16_e32 v73, v113
	v_mul_f32_e32 v74, 0xbfb8aa3b, v73
	v_exp_f32_e32 v74, v74
	s_nop 0
	v_add_f32_e32 v74, 1.0, v74
	v_div_scale_f32 v75, vcc, v74, v74, v73
	v_rcp_f32_e32 v76, v75
	v_div_scale_f32 v77, vcc, v73, v74, v73
	v_fma_f32 v78, -v75, v76, 1.0
	v_fmac_f32_e32 v76, v78, v76
	v_mul_f32_e32 v78, v77, v76
	v_fma_f32 v79, -v75, v78, v77
	v_fmac_f32_e32 v78, v79, v76
	v_fma_f32 v75, -v75, v78, v77
	v_div_fmas_f32 v75, v75, v76, v78
	v_div_fixup_f32 v73, v75, v74, v73
	v_fma_mixlo_f16 v73, v72, v73, 0
	v_add_u32_e32 v71, 0xc000, v69
	global_store_short v71, v73, s[0:1]
	s_waitcnt vmcnt(46)
	v_add_f32_e32 v72, v189, v27
	v_mul_f32_e32 v72, v190, v72
	v_cvt_f32_f16_e32 v73, v114
	v_mul_f32_e32 v74, 0xbfb8aa3b, v73
	v_exp_f32_e32 v74, v74
	s_nop 0
	v_add_f32_e32 v74, 1.0, v74
	v_div_scale_f32 v75, vcc, v74, v74, v73
	v_rcp_f32_e32 v76, v75
	v_div_scale_f32 v77, vcc, v73, v74, v73
	v_fma_f32 v78, -v75, v76, 1.0
	v_fmac_f32_e32 v76, v78, v76
	v_mul_f32_e32 v78, v77, v76
	v_fma_f32 v79, -v75, v78, v77
	v_fmac_f32_e32 v78, v79, v76
	v_fma_f32 v75, -v75, v78, v77
	v_div_fmas_f32 v75, v75, v76, v78
	v_div_fixup_f32 v73, v75, v74, v73
	v_fma_mixlo_f16 v73, v72, v73, 0
	v_add_u32_e32 v71, 0xc400, v69
	global_store_short v71, v73, s[0:1]
	s_waitcnt vmcnt(45)
;   __device__ __forceinline__ half_t* u() const { return (half_t*)(ws() + OFF_u); }
;   __device__ __forceinline__ half_t* ya() const { return (half_t*)(ws() + OFF_ya); }
; __device__ __forceinline__ float siluf_(float x) { return x / (1.f + __expf(-x)); }
; template <int NI, class LA, class LB, class EP>
; __device__ __forceinline__ void gemm_tile(int K, LA loadA, LB loadB, EP epi, char* smem) {
;     ...
; #pragma unroll
;   for (int mi = 0; mi < 2; ++mi)
; #pragma unroll
;     for (int ni = 0; ni < NI; ++ni)
; #pragma unroll
;       for (int r = 0; r < 16; ++r) {
;         const int row = wm * 64 + mi * 32 + (r & 3) + 8 * (r >> 2) + 4 * (lane >> 5);
;         const int col = wn * (NI * 32) + ni * 32 + (lane & 31);
;         epi(mi, ni, r, row, col, acc[mi][ni][r]);
;       }
; __device__ __forceinline__ void pool_item(const KP& p, int l, int item, char* smem) {
;     ...
;       [&](int mi, int ni, int r, int row, int col, float v) {
;         const int tok = m0 + row;
;         const float z = (float)p.u()[(size_t)tok * NU + C_AZ + g * 128 + col];
;         p.ya()[(size_t)tok * 512 + g * 128 + col] = (half_t)((v + pb[ni]) * ps[ni] * siluf_(z));
;       },
	v_add_f32_e32 v72, v189, v28
	v_mul_f32_e32 v72, v190, v72
	v_cvt_f32_f16_e32 v73, v115
	v_mul_f32_e32 v74, 0xbfb8aa3b, v73
	v_exp_f32_e32 v74, v74
	s_nop 0
	v_add_f32_e32 v74, 1.0, v74
	v_div_scale_f32 v75, vcc, v74, v74, v73
	v_rcp_f32_e32 v76, v75
	v_div_scale_f32 v77, vcc, v73, v74, v73
	v_fma_f32 v78, -v75, v76, 1.0
	v_fmac_f32_e32 v76, v78, v76
	v_mul_f32_e32 v78, v77, v76
	v_fma_f32 v79, -v75, v78, v77
	v_fmac_f32_e32 v78, v79, v76
	v_fma_f32 v75, -v75, v78, v77
	v_div_fmas_f32 v75, v75, v76, v78
	v_div_fixup_f32 v73, v75, v74, v73
	v_fma_mixlo_f16 v73, v72, v73, 0
	v_add_u32_e32 v71, 0xc800, v69
	global_store_short v71, v73, s[0:1]
	s_waitcnt vmcnt(44)
	v_add_f32_e32 v72, v189, v29
	v_mul_f32_e32 v72, v190, v72
	v_cvt_f32_f16_e32 v73, v116
	v_mul_f32_e32 v74, 0xbfb8aa3b, v73
	v_exp_f32_e32 v74, v74
	s_nop 0
	v_add_f32_e32 v74, 1.0, v74
	v_div_scale_f32 v75, vcc, v74, v74, v73
	v_rcp_f32_e32 v76, v75
	v_div_scale_f32 v77, vcc, v73, v74, v73
	v_fma_f32 v78, -v75, v76, 1.0
	v_fmac_f32_e32 v76, v78, v76
	v_mul_f32_e32 v78, v77, v76
	v_fma_f32 v79, -v75, v78, v77
	v_fmac_f32_e32 v78, v79, v76
	v_fma_f32 v75, -v75, v78, v77
	v_div_fmas_f32 v75, v75, v76, v78
	v_div_fixup_f32 v73, v75, v74, v73
	v_fma_mixlo_f16 v73, v72, v73, 0
	v_add_u32_e32 v71, 0xcc00, v69
	global_store_short v71, v73, s[0:1]
	s_waitcnt vmcnt(43)
	v_add_f32_e32 v72, v189, v30
	v_mul_f32_e32 v72, v190, v72
	v_cvt_f32_f16_e32 v73, v117
	v_mul_f32_e32 v74, 0xbfb8aa3b, v73
	v_exp_f32_e32 v74, v74
	s_nop 0
	v_add_f32_e32 v74, 1.0, v74
	v_div_scale_f32 v75, vcc, v74, v74, v73
	v_rcp_f32_e32 v76, v75
	v_div_scale_f32 v77, vcc, v73, v74, v73
	v_fma_f32 v78, -v75, v76, 1.0
	v_fmac_f32_e32 v76, v78, v76
	v_mul_f32_e32 v78, v77, v76
	v_fma_f32 v79, -v75, v78, v77
	v_fmac_f32_e32 v78, v79, v76
	v_fma_f32 v75, -v75, v78, v77
	v_div_fmas_f32 v75, v75, v76, v78
	v_div_fixup_f32 v73, v75, v74, v73
	v_fma_mixlo_f16 v73, v72, v73, 0
	v_add_u32_e32 v71, 0xe000, v69
	global_store_short v71, v73, s[0:1]
	s_waitcnt vmcnt(42)
	v_add_f32_e32 v72, v189, v31
	v_mul_f32_e32 v72, v190, v72
	v_cvt_f32_f16_e32 v73, v118
	v_mul_f32_e32 v74, 0xbfb8aa3b, v73
	v_exp_f32_e32 v74, v74
	s_nop 0
	v_add_f32_e32 v74, 1.0, v74
	v_div_scale_f32 v75, vcc, v74, v74, v73
	v_rcp_f32_e32 v76, v75
	v_div_scale_f32 v77, vcc, v73, v74, v73
	v_fma_f32 v78, -v75, v76, 1.0
	v_fmac_f32_e32 v76, v78, v76
	v_mul_f32_e32 v78, v77, v76
	v_fma_f32 v79, -v75, v78, v77
	v_fmac_f32_e32 v78, v79, v76
	v_fma_f32 v75, -v75, v78, v77
	v_div_fmas_f32 v75, v75, v76, v78
	v_div_fixup_f32 v73, v75, v74, v73
	v_fma_mixlo_f16 v73, v72, v73, 0
	v_add_u32_e32 v71, 0xe400, v69
	global_store_short v71, v73, s[0:1]
	s_waitcnt vmcnt(41)
	v_add_f32_e32 v72, v189, v32
	v_mul_f32_e32 v72, v190, v72
	v_cvt_f32_f16_e32 v73, v119
	v_mul_f32_e32 v74, 0xbfb8aa3b, v73
	v_exp_f32_e32 v74, v74
	s_nop 0
	v_add_f32_e32 v74, 1.0, v74
	v_div_scale_f32 v75, vcc, v74, v74, v73
	v_rcp_f32_e32 v76, v75
	v_div_scale_f32 v77, vcc, v73, v74, v73
	v_fma_f32 v78, -v75, v76, 1.0
	v_fmac_f32_e32 v76, v78, v76
	v_mul_f32_e32 v78, v77, v76
	v_fma_f32 v79, -v75, v78, v77
	v_fmac_f32_e32 v78, v79, v76
	v_fma_f32 v75, -v75, v78, v77
	v_div_fmas_f32 v75, v75, v76, v78
	v_div_fixup_f32 v73, v75, v74, v73
	v_fma_mixlo_f16 v73, v72, v73, 0
	v_add_u32_e32 v71, 0xe800, v69
	global_store_short v71, v73, s[0:1]
	s_waitcnt vmcnt(40)
	v_add_f32_e32 v72, v189, v33
	v_mul_f32_e32 v72, v190, v72
	v_cvt_f32_f16_e32 v73, v120
	v_mul_f32_e32 v74, 0xbfb8aa3b, v73
	v_exp_f32_e32 v74, v74
	s_nop 0
	v_add_f32_e32 v74, 1.0, v74
	v_div_scale_f32 v75, vcc, v74, v74, v73
	v_rcp_f32_e32 v76, v75
	v_div_scale_f32 v77, vcc, v73, v74, v73
	v_fma_f32 v78, -v75, v76, 1.0
	v_fmac_f32_e32 v76, v78, v76
	v_mul_f32_e32 v78, v77, v76
	v_fma_f32 v79, -v75, v78, v77
	v_fmac_f32_e32 v78, v79, v76
	v_fma_f32 v75, -v75, v78, v77
	v_div_fmas_f32 v75, v75, v76, v78
	v_div_fixup_f32 v73, v75, v74, v73
	v_fma_mixlo_f16 v73, v72, v73, 0
	v_add_u32_e32 v71, 0xec00, v69
	global_store_short v71, v73, s[0:1]
	s_waitcnt vmcnt(39)
	v_add_f32_e32 v72, v188, v2
	v_mul_f32_e32 v72, v187, v72
	v_cvt_f32_f16_e32 v73, v97
	v_mul_f32_e32 v74, 0xbfb8aa3b, v73
	v_exp_f32_e32 v74, v74
	s_nop 0
	v_add_f32_e32 v74, 1.0, v74
	v_div_scale_f32 v75, vcc, v74, v74, v73
	v_rcp_f32_e32 v76, v75
	v_div_scale_f32 v77, vcc, v73, v74, v73
	v_fma_f32 v78, -v75, v76, 1.0
	v_fmac_f32_e32 v76, v78, v76
	v_mul_f32_e32 v78, v77, v76
	v_fma_f32 v79, -v75, v78, v77
	v_fmac_f32_e32 v78, v79, v76
	v_fma_f32 v75, -v75, v78, v77
	v_div_fmas_f32 v75, v75, v76, v78
	v_div_fixup_f32 v73, v75, v74, v73
	v_fma_mixlo_f16 v73, v72, v73, 0
	v_add_u32_e32 v71, 0x8000, v69
	global_store_short v71, v73, s[0:1] offset:64
	s_waitcnt vmcnt(38)
	v_add_f32_e32 v72, v188, v3
	v_mul_f32_e32 v72, v187, v72
	v_cvt_f32_f16_e32 v73, v98
	v_mul_f32_e32 v74, 0xbfb8aa3b, v73
	v_exp_f32_e32 v74, v74
	s_nop 0
	v_add_f32_e32 v74, 1.0, v74
	v_div_scale_f32 v75, vcc, v74, v74, v73
	v_rcp_f32_e32 v76, v75
	v_div_scale_f32 v77, vcc, v73, v74, v73
	v_fma_f32 v78, -v75, v76, 1.0
	v_fmac_f32_e32 v76, v78, v76
	v_mul_f32_e32 v78, v77, v76
	v_fma_f32 v79, -v75, v78, v77
	v_fmac_f32_e32 v78, v79, v76
	v_fma_f32 v75, -v75, v78, v77
	v_div_fmas_f32 v75, v75, v76, v78
	v_div_fixup_f32 v73, v75, v74, v73
	v_fma_mixlo_f16 v73, v72, v73, 0
	v_add_u32_e32 v71, 0x8400, v69
	global_store_short v71, v73, s[0:1] offset:64
	s_waitcnt vmcnt(37)
;   __device__ __forceinline__ half_t* u() const { return (half_t*)(ws() + OFF_u); }
;   __device__ __forceinline__ half_t* ya() const { return (half_t*)(ws() + OFF_ya); }
; __device__ __forceinline__ float siluf_(float x) { return x / (1.f + __expf(-x)); }
; template <int NI, class LA, class LB, class EP>
; __device__ __forceinline__ void gemm_tile(int K, LA loadA, LB loadB, EP epi, char* smem) {
;     ...
; #pragma unroll
;   for (int mi = 0; mi < 2; ++mi)
; #pragma unroll
;     for (int ni = 0; ni < NI; ++ni)
; #pragma unroll
;       for (int r = 0; r < 16; ++r) {
;         const int row = wm * 64 + mi * 32 + (r & 3) + 8 * (r >> 2) + 4 * (lane >> 5);
;         const int col = wn * (NI * 32) + ni * 32 + (lane & 31);
;         epi(mi, ni, r, row, col, acc[mi][ni][r]);
;       }
; __device__ __forceinline__ void pool_item(const KP& p, int l, int item, char* smem) {
;     ...
;       [&](int mi, int ni, int r, int row, int col, float v) {
;         const int tok = m0 + row;
;         const float z = (float)p.u()[(size_t)tok * NU + C_AZ + g * 128 + col];
;         p.ya()[(size_t)tok * 512 + g * 128 + col] = (half_t)((v + pb[ni]) * ps[ni] * siluf_(z));
;       },
	v_add_f32_e32 v72, v188, v4
	v_mul_f32_e32 v72, v187, v72
	v_cvt_f32_f16_e32 v73, v99
	v_mul_f32_e32 v74, 0xbfb8aa3b, v73
	v_exp_f32_e32 v74, v74
	s_nop 0
	v_add_f32_e32 v74, 1.0, v74
	v_div_scale_f32 v75, vcc, v74, v74, v73
	v_rcp_f32_e32 v76, v75
	v_div_scale_f32 v77, vcc, v73, v74, v73
	v_fma_f32 v78, -v75, v76, 1.0
	v_fmac_f32_e32 v76, v78, v76
	v_mul_f32_e32 v78, v77, v76
	v_fma_f32 v79, -v75, v78, v77
	v_fmac_f32_e32 v78, v79, v76
	v_fma_f32 v75, -v75, v78, v77
	v_div_fmas_f32 v75, v75, v76, v78
	v_div_fixup_f32 v73, v75, v74, v73
	v_fma_mixlo_f16 v73, v72, v73, 0
	v_add_u32_e32 v71, 0x8800, v69
	global_store_short v71, v73, s[0:1] offset:64
	s_waitcnt vmcnt(36)
	v_add_f32_e32 v72, v188, v5
	v_mul_f32_e32 v72, v187, v72
	v_cvt_f32_f16_e32 v73, v100
	v_mul_f32_e32 v74, 0xbfb8aa3b, v73
	v_exp_f32_e32 v74, v74
	s_nop 0
	v_add_f32_e32 v74, 1.0, v74
	v_div_scale_f32 v75, vcc, v74, v74, v73
	v_rcp_f32_e32 v76, v75
	v_div_scale_f32 v77, vcc, v73, v74, v73
	v_fma_f32 v78, -v75, v76, 1.0
	v_fmac_f32_e32 v76, v78, v76
	v_mul_f32_e32 v78, v77, v76
	v_fma_f32 v79, -v75, v78, v77
	v_fmac_f32_e32 v78, v79, v76
	v_fma_f32 v75, -v75, v78, v77
	v_div_fmas_f32 v75, v75, v76, v78
	v_div_fixup_f32 v73, v75, v74, v73
	v_fma_mixlo_f16 v73, v72, v73, 0
	v_add_u32_e32 v71, 0x8c00, v69
	global_store_short v71, v73, s[0:1] offset:64
	s_waitcnt vmcnt(35)
	v_add_f32_e32 v72, v188, v6
	v_mul_f32_e32 v72, v187, v72
	v_cvt_f32_f16_e32 v73, v101
	v_mul_f32_e32 v74, 0xbfb8aa3b, v73
	v_exp_f32_e32 v74, v74
	s_nop 0
	v_add_f32_e32 v74, 1.0, v74
	v_div_scale_f32 v75, vcc, v74, v74, v73
	v_rcp_f32_e32 v76, v75
	v_div_scale_f32 v77, vcc, v73, v74, v73
	v_fma_f32 v78, -v75, v76, 1.0
	v_fmac_f32_e32 v76, v78, v76
	v_mul_f32_e32 v78, v77, v76
	v_fma_f32 v79, -v75, v78, v77
	v_fmac_f32_e32 v78, v79, v76
	v_fma_f32 v75, -v75, v78, v77
	v_div_fmas_f32 v75, v75, v76, v78
	v_div_fixup_f32 v73, v75, v74, v73
	v_fma_mixlo_f16 v73, v72, v73, 0
	v_add_u32_e32 v71, 0xa000, v69
	global_store_short v71, v73, s[0:1] offset:64
	s_waitcnt vmcnt(34)
	v_add_f32_e32 v72, v188, v7
	v_mul_f32_e32 v72, v187, v72
	v_cvt_f32_f16_e32 v73, v102
	v_mul_f32_e32 v74, 0xbfb8aa3b, v73
	v_exp_f32_e32 v74, v74
	s_nop 0
	v_add_f32_e32 v74, 1.0, v74
	v_div_scale_f32 v75, vcc, v74, v74, v73
	v_rcp_f32_e32 v76, v75
	v_div_scale_f32 v77, vcc, v73, v74, v73
	v_fma_f32 v78, -v75, v76, 1.0
	v_fmac_f32_e32 v76, v78, v76
	v_mul_f32_e32 v78, v77, v76
	v_fma_f32 v79, -v75, v78, v77
	v_fmac_f32_e32 v78, v79, v76
	v_fma_f32 v75, -v75, v78, v77
	v_div_fmas_f32 v75, v75, v76, v78
	v_div_fixup_f32 v73, v75, v74, v73
	v_fma_mixlo_f16 v73, v72, v73, 0
	v_add_u32_e32 v71, 0xa400, v69
	global_store_short v71, v73, s[0:1] offset:64
	s_waitcnt vmcnt(33)
	v_add_f32_e32 v72, v188, v8
	v_mul_f32_e32 v72, v187, v72
	v_cvt_f32_f16_e32 v73, v103
	v_mul_f32_e32 v74, 0xbfb8aa3b, v73
	v_exp_f32_e32 v74, v74
	s_nop 0
	v_add_f32_e32 v74, 1.0, v74
	v_div_scale_f32 v75, vcc, v74, v74, v73
	v_rcp_f32_e32 v76, v75
	v_div_scale_f32 v77, vcc, v73, v74, v73
	v_fma_f32 v78, -v75, v76, 1.0
	v_fmac_f32_e32 v76, v78, v76
	v_mul_f32_e32 v78, v77, v76
	v_fma_f32 v79, -v75, v78, v77
	v_fmac_f32_e32 v78, v79, v76
	v_fma_f32 v75, -v75, v78, v77
	v_div_fmas_f32 v75, v75, v76, v78
	v_div_fixup_f32 v73, v75, v74, v73
	v_fma_mixlo_f16 v73, v72, v73, 0
	v_add_u32_e32 v71, 0xa800, v69
	global_store_short v71, v73, s[0:1] offset:64
	s_waitcnt vmcnt(32)
	v_add_f32_e32 v72, v188, v9
	v_mul_f32_e32 v72, v187, v72
	v_cvt_f32_f16_e32 v73, v104
	v_mul_f32_e32 v74, 0xbfb8aa3b, v73
	v_exp_f32_e32 v74, v74
	s_nop 0
	v_add_f32_e32 v74, 1.0, v74
	v_div_scale_f32 v75, vcc, v74, v74, v73
	v_rcp_f32_e32 v76, v75
	v_div_scale_f32 v77, vcc, v73, v74, v73
	v_fma_f32 v78, -v75, v76, 1.0
	v_fmac_f32_e32 v76, v78, v76
	v_mul_f32_e32 v78, v77, v76
	v_fma_f32 v79, -v75, v78, v77
	v_fmac_f32_e32 v78, v79, v76
	v_fma_f32 v75, -v75, v78, v77
	v_div_fmas_f32 v75, v75, v76, v78
	v_div_fixup_f32 v73, v75, v74, v73
	v_fma_mixlo_f16 v73, v72, v73, 0
	v_add_u32_e32 v71, 0xac00, v69
	global_store_short v71, v73, s[0:1] offset:64
	s_waitcnt vmcnt(31)
	v_add_f32_e32 v72, v188, v10
	v_mul_f32_e32 v72, v187, v72
	v_cvt_f32_f16_e32 v73, v105
	v_mul_f32_e32 v74, 0xbfb8aa3b, v73
	v_exp_f32_e32 v74, v74
	s_nop 0
	v_add_f32_e32 v74, 1.0, v74
	v_div_scale_f32 v75, vcc, v74, v74, v73
	v_rcp_f32_e32 v76, v75
	v_div_scale_f32 v77, vcc, v73, v74, v73
	v_fma_f32 v78, -v75, v76, 1.0
	v_fmac_f32_e32 v76, v78, v76
	v_mul_f32_e32 v78, v77, v76
	v_fma_f32 v79, -v75, v78, v77
	v_fmac_f32_e32 v78, v79, v76
	v_fma_f32 v75, -v75, v78, v77
	v_div_fmas_f32 v75, v75, v76, v78
	v_div_fixup_f32 v73, v75, v74, v73
	v_fma_mixlo_f16 v73, v72, v73, 0
	v_add_u32_e32 v71, 0xc000, v69
	global_store_short v71, v73, s[0:1] offset:64
	s_waitcnt vmcnt(30)
;   __device__ __forceinline__ half_t* u() const { return (half_t*)(ws() + OFF_u); }
;   __device__ __forceinline__ half_t* ya() const { return (half_t*)(ws() + OFF_ya); }
; __device__ __forceinline__ float siluf_(float x) { return x / (1.f + __expf(-x)); }
; template <int NI, class LA, class LB, class EP>
; __device__ __forceinline__ void gemm_tile(int K, LA loadA, LB loadB, EP epi, char* smem) {
;     ...
; #pragma unroll
;   for (int mi = 0; mi < 2; ++mi)
; #pragma unroll
;     for (int ni = 0; ni < NI; ++ni)
; #pragma unroll
;       for (int r = 0; r < 16; ++r) {
;         const int row = wm * 64 + mi * 32 + (r & 3) + 8 * (r >> 2) + 4 * (lane >> 5);
;         const int col = wn * (NI * 32) + ni * 32 + (lane & 31);
;         epi(mi, ni, r, row, col, acc[mi][ni][r]);
;       }
; __device__ __forceinline__ void pool_item(const KP& p, int l, int item, char* smem) {
;     ...
;       [&](int mi, int ni, int r, int row, int col, float v) {
;         const int tok = m0 + row;
;         const float z = (float)p.u()[(size_t)tok * NU + C_AZ + g * 128 + col];
;         p.ya()[(size_t)tok * 512 + g * 128 + col] = (half_t)((v + pb[ni]) * ps[ni] * siluf_(z));
;       },
	v_add_f32_e32 v72, v188, v11
	v_mul_f32_e32 v72, v187, v72
	v_cvt_f32_f16_e32 v73, v106
	v_mul_f32_e32 v74, 0xbfb8aa3b, v73
	v_exp_f32_e32 v74, v74
	s_nop 0
	v_add_f32_e32 v74, 1.0, v74
	v_div_scale_f32 v75, vcc, v74, v74, v73
	v_rcp_f32_e32 v76, v75
	v_div_scale_f32 v77, vcc, v73, v74, v73
	v_fma_f32 v78, -v75, v76, 1.0
	v_fmac_f32_e32 v76, v78, v76
	v_mul_f32_e32 v78, v77, v76
	v_fma_f32 v79, -v75, v78, v77
	v_fmac_f32_e32 v78, v79, v76
	v_fma_f32 v75, -v75, v78, v77
	v_div_fmas_f32 v75, v75, v76, v78
	v_div_fixup_f32 v73, v75, v74, v73
	v_fma_mixlo_f16 v73, v72, v73, 0
	v_add_u32_e32 v71, 0xc400, v69
	global_store_short v71, v73, s[0:1] offset:64
	s_waitcnt vmcnt(29)
	v_add_f32_e32 v72, v188, v12
	v_mul_f32_e32 v72, v187, v72
	v_cvt_f32_f16_e32 v73, v107
	v_mul_f32_e32 v74, 0xbfb8aa3b, v73
	v_exp_f32_e32 v74, v74
	s_nop 0
	v_add_f32_e32 v74, 1.0, v74
	v_div_scale_f32 v75, vcc, v74, v74, v73
	v_rcp_f32_e32 v76, v75
	v_div_scale_f32 v77, vcc, v73, v74, v73
	v_fma_f32 v78, -v75, v76, 1.0
	v_fmac_f32_e32 v76, v78, v76
	v_mul_f32_e32 v78, v77, v76
	v_fma_f32 v79, -v75, v78, v77
	v_fmac_f32_e32 v78, v79, v76
	v_fma_f32 v75, -v75, v78, v77
	v_div_fmas_f32 v75, v75, v76, v78
	v_div_fixup_f32 v73, v75, v74, v73
	v_fma_mixlo_f16 v73, v72, v73, 0
	v_add_u32_e32 v71, 0xc800, v69
	global_store_short v71, v73, s[0:1] offset:64
	s_waitcnt vmcnt(28)
	v_add_f32_e32 v72, v188, v13
	v_mul_f32_e32 v72, v187, v72
	v_cvt_f32_f16_e32 v73, v108
	v_mul_f32_e32 v74, 0xbfb8aa3b, v73
	v_exp_f32_e32 v74, v74
	s_nop 0
	v_add_f32_e32 v74, 1.0, v74
	v_div_scale_f32 v75, vcc, v74, v74, v73
	v_rcp_f32_e32 v76, v75
	v_div_scale_f32 v77, vcc, v73, v74, v73
	v_fma_f32 v78, -v75, v76, 1.0
	v_fmac_f32_e32 v76, v78, v76
	v_mul_f32_e32 v78, v77, v76
	v_fma_f32 v79, -v75, v78, v77
	v_fmac_f32_e32 v78, v79, v76
	v_fma_f32 v75, -v75, v78, v77
	v_div_fmas_f32 v75, v75, v76, v78
	v_div_fixup_f32 v73, v75, v74, v73
	v_fma_mixlo_f16 v73, v72, v73, 0
	v_add_u32_e32 v71, 0xcc00, v69
	global_store_short v71, v73, s[0:1] offset:64
	s_waitcnt vmcnt(27)
	v_add_f32_e32 v72, v188, v14
	v_mul_f32_e32 v72, v187, v72
	v_cvt_f32_f16_e32 v73, v109
	v_mul_f32_e32 v74, 0xbfb8aa3b, v73
	v_exp_f32_e32 v74, v74
	s_nop 0
	v_add_f32_e32 v74, 1.0, v74
	v_div_scale_f32 v75, vcc, v74, v74, v73
	v_rcp_f32_e32 v76, v75
	v_div_scale_f32 v77, vcc, v73, v74, v73
	v_fma_f32 v78, -v75, v76, 1.0
	v_fmac_f32_e32 v76, v78, v76
	v_mul_f32_e32 v78, v77, v76
	v_fma_f32 v79, -v75, v78, v77
	v_fmac_f32_e32 v78, v79, v76
	v_fma_f32 v75, -v75, v78, v77
	v_div_fmas_f32 v75, v75, v76, v78
	v_div_fixup_f32 v73, v75, v74, v73
	v_fma_mixlo_f16 v73, v72, v73, 0
	v_add_u32_e32 v71, 0xe000, v69
	global_store_short v71, v73, s[0:1] offset:64
	s_waitcnt vmcnt(26)
	v_add_f32_e32 v72, v188, v15
	v_mul_f32_e32 v72, v187, v72
	v_cvt_f32_f16_e32 v73, v110
	v_mul_f32_e32 v74, 0xbfb8aa3b, v73
	v_exp_f32_e32 v74, v74
	s_nop 0
	v_add_f32_e32 v74, 1.0, v74
	v_div_scale_f32 v75, vcc, v74, v74, v73
	v_rcp_f32_e32 v76, v75
	v_div_scale_f32 v77, vcc, v73, v74, v73
	v_fma_f32 v78, -v75, v76, 1.0
	v_fmac_f32_e32 v76, v78, v76
	v_mul_f32_e32 v78, v77, v76
	v_fma_f32 v79, -v75, v78, v77
	v_fmac_f32_e32 v78, v79, v76
	v_fma_f32 v75, -v75, v78, v77
	v_div_fmas_f32 v75, v75, v76, v78
	v_div_fixup_f32 v73, v75, v74, v73
	v_fma_mixlo_f16 v73, v72, v73, 0
	v_add_u32_e32 v71, 0xe400, v69
	global_store_short v71, v73, s[0:1] offset:64
	s_waitcnt vmcnt(25)
	v_add_f32_e32 v72, v188, v16
	v_mul_f32_e32 v72, v187, v72
	v_cvt_f32_f16_e32 v73, v111
	v_mul_f32_e32 v74, 0xbfb8aa3b, v73
	v_exp_f32_e32 v74, v74
	s_nop 0
	v_add_f32_e32 v74, 1.0, v74
	v_div_scale_f32 v75, vcc, v74, v74, v73
	v_rcp_f32_e32 v76, v75
	v_div_scale_f32 v77, vcc, v73, v74, v73
	v_fma_f32 v78, -v75, v76, 1.0
	v_fmac_f32_e32 v76, v78, v76
	v_mul_f32_e32 v78, v77, v76
	v_fma_f32 v79, -v75, v78, v77
	v_fmac_f32_e32 v78, v79, v76
	v_fma_f32 v75, -v75, v78, v77
	v_div_fmas_f32 v75, v75, v76, v78
	v_div_fixup_f32 v73, v75, v74, v73
	v_fma_mixlo_f16 v73, v72, v73, 0
	v_add_u32_e32 v71, 0xe800, v69
	global_store_short v71, v73, s[0:1] offset:64
	s_waitcnt vmcnt(24)
	v_add_f32_e32 v72, v188, v17
	v_mul_f32_e32 v72, v187, v72
	v_cvt_f32_f16_e32 v73, v112
	v_mul_f32_e32 v74, 0xbfb8aa3b, v73
	v_exp_f32_e32 v74, v74
	s_nop 0
	v_add_f32_e32 v74, 1.0, v74
	v_div_scale_f32 v75, vcc, v74, v74, v73
	v_rcp_f32_e32 v76, v75
	v_div_scale_f32 v77, vcc, v73, v74, v73
	v_fma_f32 v78, -v75, v76, 1.0
	v_fmac_f32_e32 v76, v78, v76
	v_mul_f32_e32 v78, v77, v76
	v_fma_f32 v79, -v75, v78, v77
	v_fmac_f32_e32 v78, v79, v76
	v_fma_f32 v75, -v75, v78, v77
	v_div_fmas_f32 v75, v75, v76, v78
	v_div_fixup_f32 v73, v75, v74, v73
	v_fma_mixlo_f16 v73, v72, v73, 0
	v_add_u32_e32 v71, 0xec00, v69
	global_store_short v71, v73, s[0:1] offset:64
	v_readlane_b32 s0, v251, 7
	v_readlane_b32 s1, v251, 8
	v_readlane_b32 s8, v252, 61
	s_nop 3
	s_lshl_b32 s8, s8, 1
	s_mov_b64 s[2:3], 0

;   __device__ __forceinline__ half_t* mm() const { return (half_t*)(ws() + OFF_mm); }
; __device__ __forceinline__ void dsa_item(const KP& p, int b, int tile, char* smem) {
;     ...
;     for (int mg = 0; mg < 2; ++mg) {
; #pragma unroll
;       for (int mm = 0; mm < 8; ++mm) {
;         const int m = mg * 8 + mm;
;         const int pos = m * 16 + col;
;         const int s = (pos < nsel) ? (int)sel[tk * 256 + pos] : 0;
;         const half_t* kp = ub + (size_t)s * NU + C_BK + hq * 8;
;         const h8 a0 = *(const h8*)kp, a1 = *(const h8*)(kp + 32);
;         f32x4 d = {0.f, 0.f, 0.f, 0.f};
;         d = __builtin_amdgcn_mfma_f32_16x16x32_f16(a0, q0, d, 0, 0, 0);
;         d = __builtin_amdgcn_mfma_f32_16x16x32_f16(a1, q1, d, 0, 0, 0);
; #pragma unroll
;         for (int r = 0; r < 4; ++r) {
;           const int pp = m * 16 + hq * 4 + r;
;           const float v = (pp < nsel) ? d[r] * 0.125f : NEGF;
;           mx = fmaxf(mx, v);
;           if (col < 8) pbuf[pp * 8 + col] = v;
;         }
;       }
.LBB0_1427:
	s_or_b64 exec, exec, s[2:3]
	s_waitcnt lgkmcnt(0)
	v_min_i32_e32 v85, 0x100, v11
	v_lshlrev_b32_e32 v14, 9, v10
	v_mov_b32_e32 v15, 0xf149f2ca
	v_lshl_add_u32 v80, v157, 1, v14
	s_add_u32 s14, s78, 0x3800
	s_addc_u32 s15, s79, 0
	ds_read_u16 v172, v80 offset:32768
	ds_read_u16 v173, v80 offset:32800
	ds_read_u16 v174, v80 offset:32832
	ds_read_u16 v175, v80 offset:32864
	ds_read_u16 v176, v80 offset:32896
	ds_read_u16 v177, v80 offset:32928
	ds_read_u16 v178, v80 offset:32960
	ds_read_u16 v179, v80 offset:32992
	ds_read_u16 v180, v80 offset:33024
	ds_read_u16 v181, v80 offset:33056
	ds_read_u16 v188, v80 offset:33088
	ds_read_u16 v189, v80 offset:33120
	ds_read_u16 v190, v80 offset:33152
	ds_read_u16 v191, v80 offset:33184
	ds_read_u16 v192, v80 offset:33216
	ds_read_u16 v193, v80 offset:33248
	v_add_u32_e32 v171, -1, v85
	v_add_u32_e32 v156, -2, v85
	v_add_u32_e32 v158, -3, v85
	v_or_b32_e32 v81, 0, v157
	v_cmp_lt_i32_e32 vcc, v81, v85
	s_waitcnt lgkmcnt(15)
	s_nop 0
	v_cndmask_b32_e32 v172, 0, v172, vcc
	v_mul_u32_u24_e32 v172, 0x1d00, v172
	v_lshl_add_u32 v172, v172, 1, v126
	global_load_dwordx4 v[16:19], v172, s[14:15]
	global_load_dwordx4 v[20:23], v172, s[14:15] offset:64
	v_or_b32_e32 v81, 16, v157
	v_cmp_lt_i32_e32 vcc, v81, v85
	s_waitcnt lgkmcnt(14)
	s_nop 0
	v_cndmask_b32_e32 v173, 0, v173, vcc
	v_mul_u32_u24_e32 v173, 0x1d00, v173
	v_lshl_add_u32 v173, v173, 1, v126
	global_load_dwordx4 v[24:27], v173, s[14:15]
	global_load_dwordx4 v[28:31], v173, s[14:15] offset:64
	v_or_b32_e32 v81, 32, v157
	v_cmp_lt_i32_e32 vcc, v81, v85
	s_waitcnt lgkmcnt(13)
	s_nop 0
	v_cndmask_b32_e32 v174, 0, v174, vcc
	v_mul_u32_u24_e32 v174, 0x1d00, v174
	v_lshl_add_u32 v174, v174, 1, v126
	global_load_dwordx4 v[32:35], v174, s[14:15]
	global_load_dwordx4 v[36:39], v174, s[14:15] offset:64
	v_or_b32_e32 v81, 48, v157
	v_cmp_lt_i32_e32 vcc, v81, v85
	s_waitcnt lgkmcnt(12)
	s_nop 0
	v_cndmask_b32_e32 v175, 0, v175, vcc
	v_mul_u32_u24_e32 v175, 0x1d00, v175
	v_lshl_add_u32 v175, v175, 1, v126
	global_load_dwordx4 v[40:43], v175, s[14:15]
	global_load_dwordx4 v[44:47], v175, s[14:15] offset:64
	v_or_b32_e32 v81, 64, v157
	v_cmp_lt_i32_e32 vcc, v81, v85
	s_waitcnt lgkmcnt(11)
	s_nop 0
	v_cndmask_b32_e32 v176, 0, v176, vcc
	v_mul_u32_u24_e32 v176, 0x1d00, v176
	v_lshl_add_u32 v176, v176, 1, v126
	global_load_dwordx4 v[48:51], v176, s[14:15]
	global_load_dwordx4 v[52:55], v176, s[14:15] offset:64
	v_or_b32_e32 v81, 0x50, v157
	v_cmp_lt_i32_e32 vcc, v81, v85
	s_waitcnt lgkmcnt(10)
	s_nop 0
	v_cndmask_b32_e32 v177, 0, v177, vcc
	v_mul_u32_u24_e32 v177, 0x1d00, v177
	v_lshl_add_u32 v177, v177, 1, v126
	global_load_dwordx4 v[56:59], v177, s[14:15]
	global_load_dwordx4 v[60:63], v177, s[14:15] offset:64
	v_or_b32_e32 v81, 0x60, v157
	v_cmp_lt_i32_e32 vcc, v81, v85
	s_waitcnt lgkmcnt(9)
	s_nop 0
	v_cndmask_b32_e32 v178, 0, v178, vcc
	v_mul_u32_u24_e32 v178, 0x1d00, v178
	v_lshl_add_u32 v178, v178, 1, v126
	global_load_dwordx4 v[64:67], v178, s[14:15]
	global_load_dwordx4 v[68:71], v178, s[14:15] offset:64
	v_or_b32_e32 v81, 0x70, v157
	v_cmp_lt_i32_e32 vcc, v81, v85
	s_waitcnt lgkmcnt(8)
	s_nop 0
	v_cndmask_b32_e32 v179, 0, v179, vcc
	v_mul_u32_u24_e32 v179, 0x1d00, v179
	v_lshl_add_u32 v179, v179, 1, v126
	global_load_dwordx4 v[72:75], v179, s[14:15]
	global_load_dwordx4 v[76:79], v179, s[14:15] offset:64
	v_or_b32_e32 v81, 0x80, v157
	v_cmp_lt_i32_e32 vcc, v81, v85
	s_waitcnt lgkmcnt(7)
	s_nop 0
	v_cndmask_b32_e32 v180, 0, v180, vcc
	v_mul_u32_u24_e32 v180, 0x1d00, v180
	v_lshl_add_u32 v180, v180, 1, v126
	global_load_dwordx4 v[90:93], v180, s[14:15]
	global_load_dwordx4 v[94:97], v180, s[14:15] offset:64
	v_or_b32_e32 v81, 0x90, v157
	v_cmp_lt_i32_e32 vcc, v81, v85
	s_waitcnt lgkmcnt(6)
	s_nop 0
	v_cndmask_b32_e32 v181, 0, v181, vcc
	v_mul_u32_u24_e32 v181, 0x1d00, v181
	v_lshl_add_u32 v181, v181, 1, v126
	global_load_dwordx4 v[98:101], v181, s[14:15]
	global_load_dwordx4 v[102:105], v181, s[14:15] offset:64
	v_or_b32_e32 v81, 0xa0, v157
	v_cmp_lt_i32_e32 vcc, v81, v85
	s_waitcnt lgkmcnt(5)
	s_nop 0
	v_cndmask_b32_e32 v188, 0, v188, vcc
	v_mul_u32_u24_e32 v188, 0x1d00, v188
	v_lshl_add_u32 v188, v188, 1, v126
	global_load_dwordx4 v[106:109], v188, s[14:15]
	global_load_dwordx4 v[110:113], v188, s[14:15] offset:64
	v_or_b32_e32 v81, 0xb0, v157
	v_cmp_lt_i32_e32 vcc, v81, v85
	s_waitcnt lgkmcnt(4)
	s_nop 0
	v_cndmask_b32_e32 v189, 0, v189, vcc
	v_mul_u32_u24_e32 v189, 0x1d00, v189
	v_lshl_add_u32 v189, v189, 1, v126
	global_load_dwordx4 v[114:117], v189, s[14:15]
	global_load_dwordx4 v[118:121], v189, s[14:15] offset:64
	v_or_b32_e32 v81, 0xc0, v157
	v_cmp_lt_i32_e32 vcc, v81, v85
	s_waitcnt lgkmcnt(3)
	s_nop 0
	v_cndmask_b32_e32 v190, 0, v190, vcc
	v_mul_u32_u24_e32 v190, 0x1d00, v190
	v_lshl_add_u32 v190, v190, 1, v126
	global_load_dwordx4 v[122:125], v190, s[14:15]
	global_load_dwordx4 v[128:131], v190, s[14:15] offset:64
	v_or_b32_e32 v81, 0xd0, v157
	v_cmp_lt_i32_e32 vcc, v81, v85
	s_waitcnt lgkmcnt(2)
	s_nop 0
	v_cndmask_b32_e32 v191, 0, v191, vcc
	v_mul_u32_u24_e32 v191, 0x1d00, v191
	v_lshl_add_u32 v191, v191, 1, v126
	global_load_dwordx4 v[132:135], v191, s[14:15]
	global_load_dwordx4 v[136:139], v191, s[14:15] offset:64
	v_or_b32_e32 v81, 0xe0, v157
	v_cmp_lt_i32_e32 vcc, v81, v85
	s_waitcnt lgkmcnt(1)
	s_nop 0
	v_cndmask_b32_e32 v192, 0, v192, vcc
	v_mul_u32_u24_e32 v192, 0x1d00, v192
	v_lshl_add_u32 v192, v192, 1, v126
	global_load_dwordx4 v[140:143], v192, s[14:15]
	global_load_dwordx4 v[144:147], v192, s[14:15] offset:64
	v_or_b32_e32 v81, 0xf0, v157
	v_cmp_lt_i32_e32 vcc, v81, v85
	s_waitcnt lgkmcnt(0)
;   __device__ __forceinline__ half_t* mm() const { return (half_t*)(ws() + OFF_mm); }
; __device__ __forceinline__ void dsa_item(const KP& p, int b, int tile, char* smem) {
;     ...
;     for (int mg = 0; mg < 2; ++mg) {
; #pragma unroll
;       for (int mm = 0; mm < 8; ++mm) {
;         const int m = mg * 8 + mm;
;         const int pos = m * 16 + col;
;         const int s = (pos < nsel) ? (int)sel[tk * 256 + pos] : 0;
;         const half_t* kp = ub + (size_t)s * NU + C_BK + hq * 8;
;         const h8 a0 = *(const h8*)kp, a1 = *(const h8*)(kp + 32);
;         f32x4 d = {0.f, 0.f, 0.f, 0.f};
;         d = __builtin_amdgcn_mfma_f32_16x16x32_f16(a0, q0, d, 0, 0, 0);
;         d = __builtin_amdgcn_mfma_f32_16x16x32_f16(a1, q1, d, 0, 0, 0);
; #pragma unroll
;         for (int r = 0; r < 4; ++r) {
;           const int pp = m * 16 + hq * 4 + r;
;           const float v = (pp < nsel) ? d[r] * 0.125f : NEGF;
;           mx = fmaxf(mx, v);
;           if (col < 8) pbuf[pp * 8 + col] = v;
;         }
;       }
	s_nop 0
	v_cndmask_b32_e32 v193, 0, v193, vcc
	v_mul_u32_u24_e32 v193, 0x1d00, v193
	v_lshl_add_u32 v193, v193, 1, v126
	global_load_dwordx4 v[148:151], v193, s[14:15]
	global_load_dwordx4 v[152:155], v193, s[14:15] offset:64
	s_waitcnt vmcnt(30)
	v_mfma_f32_16x16x32_f16 v[10:13], v[16:19], v[6:9], 0
	v_mfma_f32_16x16x32_f16 v[10:13], v[20:23], v[2:5], v[10:13]
	s_nop 4
	s_waitcnt vmcnt(28)
	v_mfma_f32_16x16x32_f16 v[194:197], v[24:27], v[6:9], 0
	v_mfma_f32_16x16x32_f16 v[194:197], v[28:31], v[2:5], v[194:197]
	v_or_b32_e32 v80, 0, v160
	v_mul_f32_e32 v10, 0x3e000000, v10
	v_mul_f32_e32 v11, 0x3e000000, v11
	v_mul_f32_e32 v12, 0x3e000000, v12
	v_mul_f32_e32 v13, 0x3e000000, v13
	v_cmp_lt_i32_e32 vcc, v80, v85
	v_cmp_lt_i32_e64 s[46:47], v80, v171
	v_lshl_add_u32 v81, v80, 5, v167
	s_nop 0
	v_cndmask_b32_e32 v10, v242, v10, vcc
	v_cndmask_b32_e64 v11, v242, v11, s[46:47]
	v_cmp_lt_i32_e32 vcc, v80, v156
	v_cmp_lt_i32_e64 s[46:47], v80, v158
	v_max3_f32 v15, v15, v10, v11
	s_nop 0
	v_cndmask_b32_e32 v12, v242, v12, vcc
	v_cndmask_b32_e64 v13, v242, v13, s[46:47]
	v_max3_f32 v15, v15, v12, v13
	s_and_saveexec_b64 s[2:3], s[38:39]
	ds_write_b32 v81, v10
	ds_write_b32 v81, v11 offset:32
	ds_write_b32 v81, v12 offset:64
	ds_write_b32 v81, v13 offset:96
	s_or_b64 exec, exec, s[2:3]
	s_waitcnt vmcnt(26)
	v_mfma_f32_16x16x32_f16 v[10:13], v[32:35], v[6:9], 0
	v_mfma_f32_16x16x32_f16 v[10:13], v[36:39], v[2:5], v[10:13]
	v_or_b32_e32 v80, 16, v160
	v_mul_f32_e32 v194, 0x3e000000, v194
	v_mul_f32_e32 v195, 0x3e000000, v195
	v_mul_f32_e32 v196, 0x3e000000, v196
	v_mul_f32_e32 v197, 0x3e000000, v197
	v_cmp_lt_i32_e32 vcc, v80, v85
	v_cmp_lt_i32_e64 s[46:47], v80, v171
	v_lshl_add_u32 v81, v80, 5, v167
	s_nop 0
	v_cndmask_b32_e32 v194, v242, v194, vcc
	v_cndmask_b32_e64 v195, v242, v195, s[46:47]
	v_cmp_lt_i32_e32 vcc, v80, v156
	v_cmp_lt_i32_e64 s[46:47], v80, v158
	v_max3_f32 v15, v15, v194, v195
	s_nop 0
	v_cndmask_b32_e32 v196, v242, v196, vcc
	v_cndmask_b32_e64 v197, v242, v197, s[46:47]
	v_max3_f32 v15, v15, v196, v197
	s_and_saveexec_b64 s[2:3], s[38:39]
	ds_write_b32 v81, v194
	ds_write_b32 v81, v195 offset:32
	ds_write_b32 v81, v196 offset:64
	ds_write_b32 v81, v197 offset:96
	s_or_b64 exec, exec, s[2:3]
	s_waitcnt vmcnt(24)
	v_mfma_f32_16x16x32_f16 v[194:197], v[40:43], v[6:9], 0
	v_mfma_f32_16x16x32_f16 v[194:197], v[44:47], v[2:5], v[194:197]
	v_or_b32_e32 v80, 32, v160
	v_mul_f32_e32 v10, 0x3e000000, v10
	v_mul_f32_e32 v11, 0x3e000000, v11
	v_mul_f32_e32 v12, 0x3e000000, v12
	v_mul_f32_e32 v13, 0x3e000000, v13
	v_cmp_lt_i32_e32 vcc, v80, v85
	v_cmp_lt_i32_e64 s[46:47], v80, v171
	v_lshl_add_u32 v81, v80, 5, v167
	s_nop 0
	v_cndmask_b32_e32 v10, v242, v10, vcc
	v_cndmask_b32_e64 v11, v242, v11, s[46:47]
	v_cmp_lt_i32_e32 vcc, v80, v156
	v_cmp_lt_i32_e64 s[46:47], v80, v158
	v_max3_f32 v15, v15, v10, v11
	s_nop 0
	v_cndmask_b32_e32 v12, v242, v12, vcc
	v_cndmask_b32_e64 v13, v242, v13, s[46:47]
	v_max3_f32 v15, v15, v12, v13
	s_and_saveexec_b64 s[2:3], s[38:39]
	ds_write_b32 v81, v10
	ds_write_b32 v81, v11 offset:32
	ds_write_b32 v81, v12 offset:64
	ds_write_b32 v81, v13 offset:96
	s_or_b64 exec, exec, s[2:3]
	s_waitcnt vmcnt(22)
	v_mfma_f32_16x16x32_f16 v[10:13], v[48:51], v[6:9], 0
	v_mfma_f32_16x16x32_f16 v[10:13], v[52:55], v[2:5], v[10:13]
	v_or_b32_e32 v80, 48, v160
	v_mul_f32_e32 v194, 0x3e000000, v194
	v_mul_f32_e32 v195, 0x3e000000, v195
	v_mul_f32_e32 v196, 0x3e000000, v196
	v_mul_f32_e32 v197, 0x3e000000, v197
	v_cmp_lt_i32_e32 vcc, v80, v85
	v_cmp_lt_i32_e64 s[46:47], v80, v171
	v_lshl_add_u32 v81, v80, 5, v167
	s_nop 0
	v_cndmask_b32_e32 v194, v242, v194, vcc
	v_cndmask_b32_e64 v195, v242, v195, s[46:47]
	v_cmp_lt_i32_e32 vcc, v80, v156
	v_cmp_lt_i32_e64 s[46:47], v80, v158
	v_max3_f32 v15, v15, v194, v195
	s_nop 0
	v_cndmask_b32_e32 v196, v242, v196, vcc
	v_cndmask_b32_e64 v197, v242, v197, s[46:47]
	v_max3_f32 v15, v15, v196, v197
	s_and_saveexec_b64 s[2:3], s[38:39]
	ds_write_b32 v81, v194
	ds_write_b32 v81, v195 offset:32
	ds_write_b32 v81, v196 offset:64
	ds_write_b32 v81, v197 offset:96
	s_or_b64 exec, exec, s[2:3]
	s_waitcnt vmcnt(20)
	v_mfma_f32_16x16x32_f16 v[194:197], v[56:59], v[6:9], 0
	v_mfma_f32_16x16x32_f16 v[194:197], v[60:63], v[2:5], v[194:197]
	v_or_b32_e32 v80, 64, v160
	v_mul_f32_e32 v10, 0x3e000000, v10
	v_mul_f32_e32 v11, 0x3e000000, v11
	v_mul_f32_e32 v12, 0x3e000000, v12
	v_mul_f32_e32 v13, 0x3e000000, v13
	v_cmp_lt_i32_e32 vcc, v80, v85
	v_cmp_lt_i32_e64 s[46:47], v80, v171
	v_lshl_add_u32 v81, v80, 5, v167
	s_nop 0
	v_cndmask_b32_e32 v10, v242, v10, vcc
	v_cndmask_b32_e64 v11, v242, v11, s[46:47]
	v_cmp_lt_i32_e32 vcc, v80, v156
	v_cmp_lt_i32_e64 s[46:47], v80, v158
	v_max3_f32 v15, v15, v10, v11
	s_nop 0
	v_cndmask_b32_e32 v12, v242, v12, vcc
	v_cndmask_b32_e64 v13, v242, v13, s[46:47]
	v_max3_f32 v15, v15, v12, v13
	s_and_saveexec_b64 s[2:3], s[38:39]
	ds_write_b32 v81, v10
	ds_write_b32 v81, v11 offset:32
	ds_write_b32 v81, v12 offset:64
	ds_write_b32 v81, v13 offset:96
	s_or_b64 exec, exec, s[2:3]
	s_waitcnt vmcnt(18)
	v_mfma_f32_16x16x32_f16 v[10:13], v[64:67], v[6:9], 0
	v_mfma_f32_16x16x32_f16 v[10:13], v[68:71], v[2:5], v[10:13]
	v_or_b32_e32 v80, 0x50, v160
	v_mul_f32_e32 v194, 0x3e000000, v194
	v_mul_f32_e32 v195, 0x3e000000, v195
	v_mul_f32_e32 v196, 0x3e000000, v196
	v_mul_f32_e32 v197, 0x3e000000, v197
	v_cmp_lt_i32_e32 vcc, v80, v85
	v_cmp_lt_i32_e64 s[46:47], v80, v171
	v_lshl_add_u32 v81, v80, 5, v167
	s_nop 0
	v_cndmask_b32_e32 v194, v242, v194, vcc
	v_cndmask_b32_e64 v195, v242, v195, s[46:47]
	v_cmp_lt_i32_e32 vcc, v80, v156
	v_cmp_lt_i32_e64 s[46:47], v80, v158
	v_max3_f32 v15, v15, v194, v195
	s_nop 0
	v_cndmask_b32_e32 v196, v242, v196, vcc
	v_cndmask_b32_e64 v197, v242, v197, s[46:47]
	v_max3_f32 v15, v15, v196, v197
	s_and_saveexec_b64 s[2:3], s[38:39]
	ds_write_b32 v81, v194
	ds_write_b32 v81, v195 offset:32
	ds_write_b32 v81, v196 offset:64
	ds_write_b32 v81, v197 offset:96
	s_or_b64 exec, exec, s[2:3]
	s_waitcnt vmcnt(16)
;   __device__ __forceinline__ half_t* mm() const { return (half_t*)(ws() + OFF_mm); }
; __device__ __forceinline__ void dsa_item(const KP& p, int b, int tile, char* smem) {
;     ...
;     for (int mg = 0; mg < 2; ++mg) {
; #pragma unroll
;       for (int mm = 0; mm < 8; ++mm) {
;         const int m = mg * 8 + mm;
;         const int pos = m * 16 + col;
;         const int s = (pos < nsel) ? (int)sel[tk * 256 + pos] : 0;
;         const half_t* kp = ub + (size_t)s * NU + C_BK + hq * 8;
;         const h8 a0 = *(const h8*)kp, a1 = *(const h8*)(kp + 32);
;         f32x4 d = {0.f, 0.f, 0.f, 0.f};
;         d = __builtin_amdgcn_mfma_f32_16x16x32_f16(a0, q0, d, 0, 0, 0);
;         d = __builtin_amdgcn_mfma_f32_16x16x32_f16(a1, q1, d, 0, 0, 0);
; #pragma unroll
;         for (int r = 0; r < 4; ++r) {
;           const int pp = m * 16 + hq * 4 + r;
;           const float v = (pp < nsel) ? d[r] * 0.125f : NEGF;
;           mx = fmaxf(mx, v);
;           if (col < 8) pbuf[pp * 8 + col] = v;
;         }
;       }
	v_mfma_f32_16x16x32_f16 v[194:197], v[72:75], v[6:9], 0
	v_mfma_f32_16x16x32_f16 v[194:197], v[76:79], v[2:5], v[194:197]
	v_or_b32_e32 v80, 0x60, v160
	v_mul_f32_e32 v10, 0x3e000000, v10
	v_mul_f32_e32 v11, 0x3e000000, v11
	v_mul_f32_e32 v12, 0x3e000000, v12
	v_mul_f32_e32 v13, 0x3e000000, v13
	v_cmp_lt_i32_e32 vcc, v80, v85
	v_cmp_lt_i32_e64 s[46:47], v80, v171
	v_lshl_add_u32 v81, v80, 5, v167
	s_nop 0
	v_cndmask_b32_e32 v10, v242, v10, vcc
	v_cndmask_b32_e64 v11, v242, v11, s[46:47]
	v_cmp_lt_i32_e32 vcc, v80, v156
	v_cmp_lt_i32_e64 s[46:47], v80, v158
	v_max3_f32 v15, v15, v10, v11
	s_nop 0
	v_cndmask_b32_e32 v12, v242, v12, vcc
	v_cndmask_b32_e64 v13, v242, v13, s[46:47]
	v_max3_f32 v15, v15, v12, v13
	s_and_saveexec_b64 s[2:3], s[38:39]
	ds_write_b32 v81, v10
	ds_write_b32 v81, v11 offset:32
	ds_write_b32 v81, v12 offset:64
	ds_write_b32 v81, v13 offset:96
	s_or_b64 exec, exec, s[2:3]
	s_waitcnt vmcnt(14)
	v_mfma_f32_16x16x32_f16 v[10:13], v[90:93], v[6:9], 0
	v_mfma_f32_16x16x32_f16 v[10:13], v[94:97], v[2:5], v[10:13]
	v_or_b32_e32 v80, 0x70, v160
	v_mul_f32_e32 v194, 0x3e000000, v194
	v_mul_f32_e32 v195, 0x3e000000, v195
	v_mul_f32_e32 v196, 0x3e000000, v196
	v_mul_f32_e32 v197, 0x3e000000, v197
	v_cmp_lt_i32_e32 vcc, v80, v85
	v_cmp_lt_i32_e64 s[46:47], v80, v171
	v_lshl_add_u32 v81, v80, 5, v167
	s_nop 0
	v_cndmask_b32_e32 v194, v242, v194, vcc
	v_cndmask_b32_e64 v195, v242, v195, s[46:47]
	v_cmp_lt_i32_e32 vcc, v80, v156
	v_cmp_lt_i32_e64 s[46:47], v80, v158
	v_max3_f32 v15, v15, v194, v195
	s_nop 0
	v_cndmask_b32_e32 v196, v242, v196, vcc
	v_cndmask_b32_e64 v197, v242, v197, s[46:47]
	v_max3_f32 v15, v15, v196, v197
	s_and_saveexec_b64 s[2:3], s[38:39]
	ds_write_b32 v81, v194
	ds_write_b32 v81, v195 offset:32
	ds_write_b32 v81, v196 offset:64
	ds_write_b32 v81, v197 offset:96
	s_or_b64 exec, exec, s[2:3]
	s_waitcnt vmcnt(12)
	v_mfma_f32_16x16x32_f16 v[194:197], v[98:101], v[6:9], 0
	v_mfma_f32_16x16x32_f16 v[194:197], v[102:105], v[2:5], v[194:197]
	v_or_b32_e32 v80, 0x80, v160
	v_mul_f32_e32 v10, 0x3e000000, v10
	v_mul_f32_e32 v11, 0x3e000000, v11
	v_mul_f32_e32 v12, 0x3e000000, v12
	v_mul_f32_e32 v13, 0x3e000000, v13
	v_cmp_lt_i32_e32 vcc, v80, v85
	v_cmp_lt_i32_e64 s[46:47], v80, v171
	v_lshl_add_u32 v81, v80, 5, v167
	s_nop 0
	v_cndmask_b32_e32 v10, v242, v10, vcc
	v_cndmask_b32_e64 v11, v242, v11, s[46:47]
	v_cmp_lt_i32_e32 vcc, v80, v156
	v_cmp_lt_i32_e64 s[46:47], v80, v158
	v_max3_f32 v15, v15, v10, v11
	s_nop 0
	v_cndmask_b32_e32 v12, v242, v12, vcc
	v_cndmask_b32_e64 v13, v242, v13, s[46:47]
	v_max3_f32 v15, v15, v12, v13
	s_and_saveexec_b64 s[2:3], s[38:39]
	ds_write_b32 v81, v10
	ds_write_b32 v81, v11 offset:32
	ds_write_b32 v81, v12 offset:64
	ds_write_b32 v81, v13 offset:96
	s_or_b64 exec, exec, s[2:3]
	s_waitcnt vmcnt(10)
	v_mfma_f32_16x16x32_f16 v[10:13], v[106:109], v[6:9], 0
	v_mfma_f32_16x16x32_f16 v[10:13], v[110:113], v[2:5], v[10:13]
	v_or_b32_e32 v80, 0x90, v160
	v_mul_f32_e32 v194, 0x3e000000, v194
	v_mul_f32_e32 v195, 0x3e000000, v195
	v_mul_f32_e32 v196, 0x3e000000, v196
	v_mul_f32_e32 v197, 0x3e000000, v197
	v_cmp_lt_i32_e32 vcc, v80, v85
	v_cmp_lt_i32_e64 s[46:47], v80, v171
	v_lshl_add_u32 v81, v80, 5, v167
	s_nop 0
	v_cndmask_b32_e32 v194, v242, v194, vcc
	v_cndmask_b32_e64 v195, v242, v195, s[46:47]
	v_cmp_lt_i32_e32 vcc, v80, v156
	v_cmp_lt_i32_e64 s[46:47], v80, v158
	v_max3_f32 v15, v15, v194, v195
	s_nop 0
	v_cndmask_b32_e32 v196, v242, v196, vcc
	v_cndmask_b32_e64 v197, v242, v197, s[46:47]
	v_max3_f32 v15, v15, v196, v197
	s_and_saveexec_b64 s[2:3], s[38:39]
	ds_write_b32 v81, v194
	ds_write_b32 v81, v195 offset:32
	ds_write_b32 v81, v196 offset:64
	ds_write_b32 v81, v197 offset:96
	s_or_b64 exec, exec, s[2:3]
	s_waitcnt vmcnt(8)
	v_mfma_f32_16x16x32_f16 v[194:197], v[114:117], v[6:9], 0
	v_mfma_f32_16x16x32_f16 v[194:197], v[118:121], v[2:5], v[194:197]
	v_or_b32_e32 v80, 0xa0, v160
	v_mul_f32_e32 v10, 0x3e000000, v10
	v_mul_f32_e32 v11, 0x3e000000, v11
	v_mul_f32_e32 v12, 0x3e000000, v12
	v_mul_f32_e32 v13, 0x3e000000, v13
	v_cmp_lt_i32_e32 vcc, v80, v85
	v_cmp_lt_i32_e64 s[46:47], v80, v171
	v_lshl_add_u32 v81, v80, 5, v167
	s_nop 0
	v_cndmask_b32_e32 v10, v242, v10, vcc
	v_cndmask_b32_e64 v11, v242, v11, s[46:47]
	v_cmp_lt_i32_e32 vcc, v80, v156
	v_cmp_lt_i32_e64 s[46:47], v80, v158
	v_max3_f32 v15, v15, v10, v11
	s_nop 0
	v_cndmask_b32_e32 v12, v242, v12, vcc
	v_cndmask_b32_e64 v13, v242, v13, s[46:47]
	v_max3_f32 v15, v15, v12, v13
	s_and_saveexec_b64 s[2:3], s[38:39]
	ds_write_b32 v81, v10
	ds_write_b32 v81, v11 offset:32
	ds_write_b32 v81, v12 offset:64
	ds_write_b32 v81, v13 offset:96
	s_or_b64 exec, exec, s[2:3]
	s_waitcnt vmcnt(6)
;   __device__ __forceinline__ half_t* mm() const { return (half_t*)(ws() + OFF_mm); }
; __device__ __forceinline__ void dsa_item(const KP& p, int b, int tile, char* smem) {
;     ...
;     for (int mg = 0; mg < 2; ++mg) {
; #pragma unroll
;       for (int mm = 0; mm < 8; ++mm) {
;         const int m = mg * 8 + mm;
;         const int pos = m * 16 + col;
;         const int s = (pos < nsel) ? (int)sel[tk * 256 + pos] : 0;
;         const half_t* kp = ub + (size_t)s * NU + C_BK + hq * 8;
;         const h8 a0 = *(const h8*)kp, a1 = *(const h8*)(kp + 32);
;         f32x4 d = {0.f, 0.f, 0.f, 0.f};
;         d = __builtin_amdgcn_mfma_f32_16x16x32_f16(a0, q0, d, 0, 0, 0);
;         d = __builtin_amdgcn_mfma_f32_16x16x32_f16(a1, q1, d, 0, 0, 0);
; #pragma unroll
;         for (int r = 0; r < 4; ++r) {
;           const int pp = m * 16 + hq * 4 + r;
;           const float v = (pp < nsel) ? d[r] * 0.125f : NEGF;
;           mx = fmaxf(mx, v);
;           if (col < 8) pbuf[pp * 8 + col] = v;
;         }
;       }
	v_mfma_f32_16x16x32_f16 v[10:13], v[122:125], v[6:9], 0
	v_mfma_f32_16x16x32_f16 v[10:13], v[128:131], v[2:5], v[10:13]
	v_or_b32_e32 v80, 0xb0, v160
	v_mul_f32_e32 v194, 0x3e000000, v194
	v_mul_f32_e32 v195, 0x3e000000, v195
	v_mul_f32_e32 v196, 0x3e000000, v196
	v_mul_f32_e32 v197, 0x3e000000, v197
	v_cmp_lt_i32_e32 vcc, v80, v85
	v_cmp_lt_i32_e64 s[46:47], v80, v171
	v_lshl_add_u32 v81, v80, 5, v167
	s_nop 0
	v_cndmask_b32_e32 v194, v242, v194, vcc
	v_cndmask_b32_e64 v195, v242, v195, s[46:47]
	v_cmp_lt_i32_e32 vcc, v80, v156
	v_cmp_lt_i32_e64 s[46:47], v80, v158
	v_max3_f32 v15, v15, v194, v195
	s_nop 0
	v_cndmask_b32_e32 v196, v242, v196, vcc
	v_cndmask_b32_e64 v197, v242, v197, s[46:47]
	v_max3_f32 v15, v15, v196, v197
	s_and_saveexec_b64 s[2:3], s[38:39]
	ds_write_b32 v81, v194
	ds_write_b32 v81, v195 offset:32
	ds_write_b32 v81, v196 offset:64
	ds_write_b32 v81, v197 offset:96
	s_or_b64 exec, exec, s[2:3]
	s_waitcnt vmcnt(4)
	v_mfma_f32_16x16x32_f16 v[194:197], v[132:135], v[6:9], 0
	v_mfma_f32_16x16x32_f16 v[194:197], v[136:139], v[2:5], v[194:197]
	v_or_b32_e32 v80, 0xc0, v160
	v_mul_f32_e32 v10, 0x3e000000, v10
	v_mul_f32_e32 v11, 0x3e000000, v11
	v_mul_f32_e32 v12, 0x3e000000, v12
	v_mul_f32_e32 v13, 0x3e000000, v13
	v_cmp_lt_i32_e32 vcc, v80, v85
	v_cmp_lt_i32_e64 s[46:47], v80, v171
	v_lshl_add_u32 v81, v80, 5, v167
	s_nop 0
	v_cndmask_b32_e32 v10, v242, v10, vcc
	v_cndmask_b32_e64 v11, v242, v11, s[46:47]
	v_cmp_lt_i32_e32 vcc, v80, v156
	v_cmp_lt_i32_e64 s[46:47], v80, v158
	v_max3_f32 v15, v15, v10, v11
	s_nop 0
	v_cndmask_b32_e32 v12, v242, v12, vcc
	v_cndmask_b32_e64 v13, v242, v13, s[46:47]
	v_max3_f32 v15, v15, v12, v13
	s_and_saveexec_b64 s[2:3], s[38:39]
	ds_write_b32 v81, v10
	ds_write_b32 v81, v11 offset:32
	ds_write_b32 v81, v12 offset:64
	ds_write_b32 v81, v13 offset:96
	s_or_b64 exec, exec, s[2:3]
	s_waitcnt vmcnt(2)
	v_mfma_f32_16x16x32_f16 v[10:13], v[140:143], v[6:9], 0
	v_mfma_f32_16x16x32_f16 v[10:13], v[144:147], v[2:5], v[10:13]
	v_or_b32_e32 v80, 0xd0, v160
	v_mul_f32_e32 v194, 0x3e000000, v194
	v_mul_f32_e32 v195, 0x3e000000, v195
	v_mul_f32_e32 v196, 0x3e000000, v196
	v_mul_f32_e32 v197, 0x3e000000, v197
	v_cmp_lt_i32_e32 vcc, v80, v85
	v_cmp_lt_i32_e64 s[46:47], v80, v171
	v_lshl_add_u32 v81, v80, 5, v167
	s_nop 0
	v_cndmask_b32_e32 v194, v242, v194, vcc
	v_cndmask_b32_e64 v195, v242, v195, s[46:47]
	v_cmp_lt_i32_e32 vcc, v80, v156
	v_cmp_lt_i32_e64 s[46:47], v80, v158
	v_max3_f32 v15, v15, v194, v195
	s_nop 0
	v_cndmask_b32_e32 v196, v242, v196, vcc
	v_cndmask_b32_e64 v197, v242, v197, s[46:47]
	v_max3_f32 v15, v15, v196, v197
	s_and_saveexec_b64 s[2:3], s[38:39]
	ds_write_b32 v81, v194
	ds_write_b32 v81, v195 offset:32
	ds_write_b32 v81, v196 offset:64
	ds_write_b32 v81, v197 offset:96
	s_or_b64 exec, exec, s[2:3]
	s_waitcnt vmcnt(0)
	v_mfma_f32_16x16x32_f16 v[194:197], v[148:151], v[6:9], 0
	v_mfma_f32_16x16x32_f16 v[194:197], v[152:155], v[2:5], v[194:197]
	v_or_b32_e32 v80, 0xe0, v160
	v_mul_f32_e32 v10, 0x3e000000, v10
	v_mul_f32_e32 v11, 0x3e000000, v11
	v_mul_f32_e32 v12, 0x3e000000, v12
	v_mul_f32_e32 v13, 0x3e000000, v13
	v_cmp_lt_i32_e32 vcc, v80, v85
	v_cmp_lt_i32_e64 s[46:47], v80, v171
	v_lshl_add_u32 v81, v80, 5, v167
	s_nop 0
	v_cndmask_b32_e32 v10, v242, v10, vcc
	v_cndmask_b32_e64 v11, v242, v11, s[46:47]
	v_cmp_lt_i32_e32 vcc, v80, v156
	v_cmp_lt_i32_e64 s[46:47], v80, v158
	v_max3_f32 v15, v15, v10, v11
	s_nop 0
	v_cndmask_b32_e32 v12, v242, v12, vcc
	v_cndmask_b32_e64 v13, v242, v13, s[46:47]
	v_max3_f32 v15, v15, v12, v13
	s_and_saveexec_b64 s[2:3], s[38:39]
	ds_write_b32 v81, v10
	ds_write_b32 v81, v11 offset:32
	ds_write_b32 v81, v12 offset:64
	ds_write_b32 v81, v13 offset:96
	s_or_b64 exec, exec, s[2:3]
	s_nop 7
	v_or_b32_e32 v80, 0xf0, v160
	v_mul_f32_e32 v194, 0x3e000000, v194
	v_mul_f32_e32 v195, 0x3e000000, v195
	v_mul_f32_e32 v196, 0x3e000000, v196
	v_mul_f32_e32 v197, 0x3e000000, v197
	v_cmp_lt_i32_e32 vcc, v80, v85
	v_cmp_lt_i32_e64 s[46:47], v80, v171
	v_lshl_add_u32 v81, v80, 5, v167
	s_nop 0
	v_cndmask_b32_e32 v194, v242, v194, vcc
	v_cndmask_b32_e64 v195, v242, v195, s[46:47]
	v_cmp_lt_i32_e32 vcc, v80, v156
	v_cmp_lt_i32_e64 s[46:47], v80, v158
	v_max3_f32 v15, v15, v194, v195
	s_nop 0
	v_cndmask_b32_e32 v196, v242, v196, vcc
	v_cndmask_b32_e64 v197, v242, v197, s[46:47]
	v_max3_f32 v15, v15, v196, v197
	s_and_saveexec_b64 s[2:3], s[38:39]
	ds_write_b32 v81, v194
	ds_write_b32 v81, v195 offset:32
	ds_write_b32 v81, v196 offset:64
	ds_write_b32 v81, v197 offset:96
	s_or_b64 exec, exec, s[2:3]

; template <int NI, class LA, class LB, class EP>
; __device__ __forceinline__ void gemm_tile(int K, LA loadA, LB loadB, EP epi, char* smem) {
;     ...
;   for (int kt = 0; kt < nk; ++kt) {
;     __syncthreads();
; #pragma unroll
;     for (int i = 0; i < 4; ++i) *(uint4*)&sA[(lr + 32 * i) * 72 + lc] = ra[i];
; #pragma unroll
;     for (int i = 0; i < NB; ++i) *(uint4*)&sB[(lr + 32 * i) * 72 + lc] = rb[i];
;     __syncthreads();
;     if (kt + 1 < nk) {
;       const int kk = (kt + 1) * 64 + lc;
; #pragma unroll
;       for (int i = 0; i < 4; ++i) ra[i] = loadA(lr + 32 * i, kk);
; #pragma unroll
;       for (int i = 0; i < NB; ++i) rb[i] = loadB(lr + 32 * i, kk);
;     }
; #pragma unroll
;     for (int s = 0; s < 4; ++s) {
;       h8 af[2], bf[NI];
; #pragma unroll
;       for (int mi = 0; mi < 2; ++mi)
;         af[mi] = *(const h8*)&sA[(wm * 64 + mi * 32 + (lane & 31)) * 72 + s * 16 + (lane >> 5) * 8];
; #pragma unroll
;       for (int ni = 0; ni < NI; ++ni)
;         bf[ni] = *(const h8*)&sB[(wn * (NI * 32) + ni * 32 + (lane & 31)) * 72 + s * 16 + (lane >> 5) * 8];
; #pragma unroll
;       for (int mi = 0; mi < 2; ++mi)
; #pragma unroll
;         for (int ni = 0; ni < NI; ++ni)
;           acc[mi][ni] = __builtin_amdgcn_mfma_f32_32x32x16_f16(af[mi], bf[ni], acc[mi][ni], 0, 0, 0);
;     }
.LBB0_1743:
	s_waitcnt vmcnt(63) expcnt(7) lgkmcnt(15)
	s_barrier
	s_waitcnt vmcnt(7)
	ds_write_b128 v172, v[66:69]
	s_waitcnt vmcnt(6)
	ds_write_b128 v172, v[70:73] offset:4608
	s_waitcnt vmcnt(5)
	ds_write_b128 v172, v[94:97] offset:9216
	s_waitcnt vmcnt(4)
	ds_write_b128 v172, v[78:81] offset:13824
	s_waitcnt vmcnt(3)
	ds_write_b128 v172, v[90:93] offset:18432
	s_waitcnt vmcnt(2)
	ds_write_b128 v172, v[74:77] offset:23040
	s_waitcnt vmcnt(1)
	ds_write_b128 v172, v[86:89] offset:27648
	s_waitcnt vmcnt(0)
	ds_write_b128 v172, v[82:85] offset:32256
	s_waitcnt lgkmcnt(0)
	s_barrier
	ds_read_b128 v[66:69], v162
	ds_read_b128 v[70:73], v163 offset:18432
	ds_read_b128 v[74:77], v162 offset:32
	ds_read_b128 v[78:81], v163 offset:18464
	ds_read_b128 v[82:85], v171 offset:18432
	ds_read_b128 v[174:177], v163 offset:23136
	s_waitcnt lgkmcnt(4)
	v_mfma_f32_32x32x16_f16 v[50:65], v[66:69], v[70:73], v[50:65]
	s_mov_b32 s2, 0x15680000
	s_waitcnt lgkmcnt(1)
	v_mfma_f32_32x32x16_f16 v[34:49], v[66:69], v[82:85], v[34:49]
	ds_read_b128 v[66:69], v162 offset:4608
	ds_read_b128 v[86:89], v162 offset:4640
	s_waitcnt lgkmcnt(1)
	v_mfma_f32_32x32x16_f16 v[18:33], v[66:69], v[70:73], v[18:33]
	v_mfma_f32_32x32x16_f16 v[2:17], v[66:69], v[82:85], v[2:17]
	ds_read_b128 v[66:69], v163 offset:23072
	ds_read_b128 v[70:73], v163 offset:23104
	v_mfma_f32_32x32x16_f16 v[50:65], v[74:77], v[78:81], v[50:65]
	s_waitcnt lgkmcnt(1)
	v_mfma_f32_32x32x16_f16 v[34:49], v[74:77], v[66:69], v[34:49]
	v_mfma_f32_32x32x16_f16 v[18:33], v[86:89], v[78:81], v[18:33]
	v_mfma_f32_32x32x16_f16 v[2:17], v[86:89], v[66:69], v[2:17]
	ds_read_b128 v[66:69], v162 offset:64
	ds_read_b128 v[74:77], v163 offset:18496
	ds_read_b128 v[78:81], v162 offset:96
	ds_read_b128 v[82:85], v163 offset:18528
	ds_read_b128 v[86:89], v162 offset:4672
	ds_read_b128 v[178:181], v162 offset:4704
	s_waitcnt lgkmcnt(4)
	v_mfma_f32_32x32x16_f16 v[50:65], v[66:69], v[74:77], v[50:65]
	v_mfma_f32_32x32x16_f16 v[34:49], v[66:69], v[70:73], v[34:49]
	v_lshl_add_u64 v[66:67], v[166:167], 0, s[40:41]
	v_add_co_u32_e32 v90, vcc, s73, v66
	v_lshl_add_u64 v[68:69], v[164:165], 0, s[40:41]
	s_nop 0
	v_addc_co_u32_e32 v91, vcc, 0, v67, vcc
	s_add_u32 s40, s40, 0x80
	s_waitcnt lgkmcnt(1)
	v_mfma_f32_32x32x16_f16 v[18:33], v[86:89], v[74:77], v[18:33]
	v_add_co_u32_e32 v74, vcc, s72, v66
	s_addc_u32 s41, s41, 0
	s_nop 0
	v_addc_co_u32_e32 v75, vcc, 0, v67, vcc
	v_add_co_u32_e32 v76, vcc, s77, v66
	v_mfma_f32_32x32x16_f16 v[2:17], v[86:89], v[70:73], v[2:17]
	s_nop 0
	v_addc_co_u32_e32 v77, vcc, 0, v67, vcc
	v_add_co_u32_e32 v86, vcc, s2, v68
	s_mov_b32 s2, 0x15688000
	s_nop 0
	v_addc_co_u32_e32 v87, vcc, 0, v69, vcc
	v_add_co_u32_e32 v88, vcc, s2, v68
	s_mov_b32 s2, 0x15690000
	s_nop 0
	v_addc_co_u32_e32 v89, vcc, 0, v69, vcc
	v_add_co_u32_e32 v188, vcc, s2, v68
	s_mov_b32 s2, 0x15698000
	s_nop 0
	v_addc_co_u32_e32 v189, vcc, 0, v69, vcc
	v_add_co_u32_e32 v190, vcc, s2, v68
	v_mfma_f32_32x32x16_f16 v[50:65], v[78:81], v[82:85], v[50:65]
	s_nop 0
	v_addc_co_u32_e32 v191, vcc, 0, v69, vcc
	s_cmpk_lg_i32 s40, 0x380
	v_mfma_f32_32x32x16_f16 v[34:49], v[78:81], v[174:177], v[34:49]
	global_load_dwordx4 v[66:69], v[66:67], off offset:128
	s_nop 0
	global_load_dwordx4 v[70:73], v[90:91], off offset:128
	global_load_dwordx4 v[94:97], v[74:75], off offset:128
	global_load_dwordx4 v[78:81], v[76:77], off offset:128
	s_nop 0
	global_load_dwordx4 v[90:93], v[86:87], off offset:128
	global_load_dwordx4 v[74:77], v[88:89], off offset:128
	s_nop 0
	global_load_dwordx4 v[86:89], v[188:189], off offset:128
	s_waitcnt lgkmcnt(0)
	v_mfma_f32_32x32x16_f16 v[18:33], v[178:181], v[82:85], v[18:33]
	global_load_dwordx4 v[82:85], v[190:191], off offset:128
	v_mfma_f32_32x32x16_f16 v[2:17], v[178:181], v[174:177], v[2:17]
	s_cbranch_scc1 .LBB0_1743
	s_barrier
	s_waitcnt vmcnt(7)
	ds_write_b128 v172, v[66:69]
	s_waitcnt vmcnt(6)
	ds_write_b128 v172, v[70:73] offset:4608
	s_waitcnt vmcnt(5)
	ds_write_b128 v172, v[94:97] offset:9216
	s_waitcnt vmcnt(4)
	ds_write_b128 v172, v[78:81] offset:13824
	s_waitcnt vmcnt(3)
	ds_write_b128 v172, v[90:93] offset:18432
	s_waitcnt vmcnt(2)
	ds_write_b128 v172, v[74:77] offset:23040
	s_waitcnt vmcnt(1)
	ds_write_b128 v172, v[86:89] offset:27648
	s_waitcnt vmcnt(0)
	ds_write_b128 v172, v[82:85] offset:32256
	s_waitcnt lgkmcnt(0)
	s_barrier
; __device__ __forceinline__ float sigmoidf_(float x) { return 1.f / (1.f + __expf(-x)); }
; template <int NI, class LA, class LB, class EP>
; __device__ __forceinline__ void gemm_tile(int K, LA loadA, LB loadB, EP epi, char* smem) {
;     ...
; #pragma unroll
;     for (int s = 0; s < 4; ++s) {
;       h8 af[2], bf[NI];
; #pragma unroll
;       for (int mi = 0; mi < 2; ++mi)
;         af[mi] = *(const h8*)&sA[(wm * 64 + mi * 32 + (lane & 31)) * 72 + s * 16 + (lane >> 5) * 8];
; #pragma unroll
;       for (int ni = 0; ni < NI; ++ni)
;         bf[ni] = *(const h8*)&sB[(wn * (NI * 32) + ni * 32 + (lane & 31)) * 72 + s * 16 + (lane >> 5) * 8];
; #pragma unroll
;       for (int mi = 0; mi < 2; ++mi)
; #pragma unroll
;         for (int ni = 0; ni < NI; ++ni)
;           acc[mi][ni] = __builtin_amdgcn_mfma_f32_32x32x16_f16(af[mi], bf[ni], acc[mi][ni], 0, 0, 0);
;     }
;   }
; #pragma unroll
;   for (int mi = 0; mi < 2; ++mi)
; #pragma unroll
;     for (int ni = 0; ni < NI; ++ni)
; #pragma unroll
;       for (int r = 0; r < 16; ++r) {
;         const int row = wm * 64 + mi * 32 + (r & 3) + 8 * (r >> 2) + 4 * (lane >> 5);
;         const int col = wn * (NI * 32) + ni * 32 + (lane & 31);
;         epi(mi, ni, r, row, col, acc[mi][ni][r]);
;       }
; __device__ __forceinline__ void phase_merge(const KP& p, char* smem, int* q, int xcc) {
;     ...
;           [&](int mi, int ni, int r, int row, int col, float v) {
;             const float gz = (float)G[(size_t)row * NU + col];
;             tot[mi][ni][r] += sigmoidf_(gz) * v;
;           },
	ds_read_b128 v[66:69], v162 offset:4608
	ds_read_b128 v[70:73], v171 offset:18432
	ds_read_b128 v[74:77], v162
	ds_read_b128 v[78:81], v162 offset:32
	ds_read_b128 v[82:85], v163 offset:18432
	ds_read_b128 v[86:89], v163 offset:18464
	s_waitcnt lgkmcnt(1)
	v_mfma_f32_32x32x16_f16 v[50:65], v[74:77], v[82:85], v[50:65]
	s_lshl_b32 s2, s56, 11
	s_add_u32 s2, s52, s2
	s_addc_u32 s3, s53, 0
	v_lshlrev_b32_e32 v0, 1, v0
	s_add_i32 s56, s56, 1
	s_add_u32 s38, s38, 0x100000
	s_addc_u32 s39, s39, 0
	v_mfma_f32_32x32x16_f16 v[34:49], v[74:77], v[70:73], v[34:49]
	s_cmp_lg_u32 s56, 3
	v_mfma_f32_32x32x16_f16 v[18:33], v[66:69], v[82:85], v[18:33]
	v_mfma_f32_32x32x16_f16 v[2:17], v[66:69], v[70:73], v[2:17]
	ds_read_b128 v[66:69], v162 offset:4640
	ds_read_b128 v[70:73], v163 offset:23072
	s_waitcnt lgkmcnt(2)
	v_mfma_f32_32x32x16_f16 v[50:65], v[78:81], v[86:89], v[50:65]
	s_waitcnt lgkmcnt(0)
	v_mfma_f32_32x32x16_f16 v[34:49], v[78:81], v[70:73], v[34:49]
	v_mfma_f32_32x32x16_f16 v[18:33], v[66:69], v[86:89], v[18:33]
	v_mfma_f32_32x32x16_f16 v[2:17], v[66:69], v[70:73], v[2:17]
	ds_read_b128 v[66:69], v162 offset:64
	ds_read_b128 v[70:73], v162 offset:4672
	ds_read_b128 v[74:77], v163 offset:18496
	ds_read_b128 v[78:81], v163 offset:23104
	s_waitcnt lgkmcnt(1)
	v_mfma_f32_32x32x16_f16 v[50:65], v[66:69], v[74:77], v[50:65]
	s_waitcnt lgkmcnt(0)
	v_mfma_f32_32x32x16_f16 v[34:49], v[66:69], v[78:81], v[34:49]
	v_mfma_f32_32x32x16_f16 v[18:33], v[70:73], v[74:77], v[18:33]
	v_mfma_f32_32x32x16_f16 v[2:17], v[70:73], v[78:81], v[2:17]
	ds_read_b128 v[66:69], v162 offset:96
	ds_read_b128 v[70:73], v162 offset:4704
	ds_read_b128 v[74:77], v163 offset:18528
	ds_read_b128 v[78:81], v163 offset:23136
	s_waitcnt lgkmcnt(1)
	v_mfma_f32_32x32x16_f16 v[50:65], v[66:69], v[74:77], v[50:65]
	s_waitcnt lgkmcnt(0)
	v_mfma_f32_32x32x16_f16 v[34:49], v[66:69], v[78:81], v[34:49]
	v_mfma_f32_32x32x16_f16 v[18:33], v[70:73], v[74:77], v[18:33]
	v_mfma_f32_32x32x16_f16 v[2:17], v[70:73], v[78:81], v[2:17]
	v_lshrrev_b32_e32 v94, 7, v224
	v_lshlrev_b32_e32 v94, 4, v94
	v_bfe_u32 v95, v224, 5, 1
	v_add_u32_e32 v94, v94, v95
	v_mul_u32_u24_e32 v94, 0xe800, v94
	v_bfe_u32 v95, v224, 6, 1
	v_lshl_add_u32 v94, v95, 7, v94
	v_and_b32_e32 v95, 31, v224
	v_lshl_add_u32 v94, v95, 1, v94
	s_mov_b64 s[40:41], s[2:3]
	v_mov_b32_e32 v96, v94
	global_load_ushort v192, v96, s[40:41]
	v_add_u32_e32 v96, 0x3a00, v94
	global_load_ushort v193, v96, s[40:41]
	v_add_u32_e32 v96, 0x7400, v94
	global_load_ushort v194, v96, s[40:41]
	v_add_u32_e32 v96, 0xae00, v94
	global_load_ushort v195, v96, s[40:41]
	v_add_u32_e32 v96, 0x1d000, v94
	global_load_ushort v196, v96, s[40:41]
	v_add_u32_e32 v96, 0x20a00, v94
	global_load_ushort v197, v96, s[40:41]
	v_add_u32_e32 v96, 0x24400, v94
	global_load_ushort v198, v96, s[40:41]
	v_add_u32_e32 v96, 0x27e00, v94
	global_load_ushort v199, v96, s[40:41]
	v_add_u32_e32 v96, 0x3a000, v94
	global_load_ushort v200, v96, s[40:41]
	v_add_u32_e32 v96, 0x3da00, v94
	global_load_ushort v201, v96, s[40:41]
	v_add_u32_e32 v96, 0x41400, v94
	global_load_ushort v202, v96, s[40:41]
	v_add_u32_e32 v96, 0x44e00, v94
	global_load_ushort v203, v96, s[40:41]
	v_add_u32_e32 v96, 0x57000, v94
	global_load_ushort v204, v96, s[40:41]
	v_add_u32_e32 v96, 0x5aa00, v94
	global_load_ushort v205, v96, s[40:41]
	v_add_u32_e32 v96, 0x5e400, v94
	global_load_ushort v206, v96, s[40:41]
	v_add_u32_e32 v96, 0x61e00, v94
	global_load_ushort v207, v96, s[40:41]
	v_mov_b32_e32 v96, v94
	global_load_ushort v208, v96, s[40:41] offset:64
	v_add_u32_e32 v96, 0x3a00, v94
	global_load_ushort v209, v96, s[40:41] offset:64
	v_add_u32_e32 v96, 0x7400, v94
	global_load_ushort v210, v96, s[40:41] offset:64
	v_add_u32_e32 v96, 0xae00, v94
	global_load_ushort v211, v96, s[40:41] offset:64
	v_add_u32_e32 v96, 0x1d000, v94
	global_load_ushort v212, v96, s[40:41] offset:64
	v_add_u32_e32 v96, 0x20a00, v94
	global_load_ushort v213, v96, s[40:41] offset:64
	v_add_u32_e32 v96, 0x24400, v94
	global_load_ushort v214, v96, s[40:41] offset:64
	v_add_u32_e32 v96, 0x27e00, v94
	global_load_ushort v215, v96, s[40:41] offset:64
	v_add_u32_e32 v96, 0x3a000, v94
	global_load_ushort v216, v96, s[40:41] offset:64
	v_add_u32_e32 v96, 0x3da00, v94
	global_load_ushort v217, v96, s[40:41] offset:64
	v_add_u32_e32 v96, 0x41400, v94
	global_load_ushort v218, v96, s[40:41] offset:64
	v_add_u32_e32 v96, 0x44e00, v94
	global_load_ushort v219, v96, s[40:41] offset:64
	v_add_u32_e32 v96, 0x57000, v94
	global_load_ushort v220, v96, s[40:41] offset:64
	v_add_u32_e32 v96, 0x5aa00, v94
	global_load_ushort v221, v96, s[40:41] offset:64
	v_add_u32_e32 v96, 0x5e400, v94
	global_load_ushort v222, v96, s[40:41] offset:64
	v_add_u32_e32 v96, 0x61e00, v94
	global_load_ushort v223, v96, s[40:41] offset:64
	s_nop 7
	s_waitcnt vmcnt(30)
	v_cvt_f32_f16_e32 v68, v192
	v_cvt_f32_f16_e32 v69, v193
	v_add_u32_e32 v96, 0x74000, v94
	global_load_ushort v192, v96, s[40:41]
	v_add_u32_e32 v96, 0x77a00, v94
	global_load_ushort v193, v96, s[40:41]
	v_mul_f32_e32 v68, 0xbfb8aa3b, v68
	v_mul_f32_e32 v69, 0xbfb8aa3b, v69
	v_exp_f32_e32 v68, v68
	v_exp_f32_e32 v69, v69
	s_nop 0
	v_pk_add_f32 v[68:69], v[68:69], 1.0 op_sel_hi:[1,0]
	s_nop 0
	v_div_scale_f32 v70, s[2:3], v69, v69, 1.0
	v_rcp_f32_e32 v71, v70
	s_nop 0
	v_fma_f32 v72, -v70, v71, 1.0
	v_fmac_f32_e32 v71, v72, v71
	v_div_scale_f32 v72, vcc, 1.0, v69, 1.0
	v_mul_f32_e32 v73, v72, v71
	v_fma_f32 v74, -v70, v73, v72
	v_fmac_f32_e32 v73, v74, v71
	v_fma_f32 v70, -v70, v73, v72
	v_div_fmas_f32 v70, v70, v71, v73
	v_div_fixup_f32 v69, v70, v69, 1.0
	v_div_scale_f32 v70, s[2:3], v68, v68, 1.0
	v_rcp_f32_e32 v71, v70
	s_nop 0
	v_fma_f32 v72, -v70, v71, 1.0
	v_fmac_f32_e32 v71, v72, v71
	v_div_scale_f32 v72, vcc, 1.0, v68, 1.0
	v_mul_f32_e32 v73, v72, v71
	v_fma_f32 v74, -v70, v73, v72
	v_fmac_f32_e32 v73, v74, v71
	v_fma_f32 v70, -v70, v73, v72
	v_div_fmas_f32 v70, v70, v71, v73
	v_div_fixup_f32 v68, v70, v68, 1.0
	v_pk_fma_f32 v[160:161], v[50:51], v[68:69], v[160:161]
	s_waitcnt vmcnt(30)
; __device__ __forceinline__ float sigmoidf_(float x) { return 1.f / (1.f + __expf(-x)); }
; template <int NI, class LA, class LB, class EP>
; __device__ __forceinline__ void gemm_tile(int K, LA loadA, LB loadB, EP epi, char* smem) {
;     ...
; #pragma unroll
;   for (int mi = 0; mi < 2; ++mi)
; #pragma unroll
;     for (int ni = 0; ni < NI; ++ni)
; #pragma unroll
;       for (int r = 0; r < 16; ++r) {
;         const int row = wm * 64 + mi * 32 + (r & 3) + 8 * (r >> 2) + 4 * (lane >> 5);
;         const int col = wn * (NI * 32) + ni * 32 + (lane & 31);
;         epi(mi, ni, r, row, col, acc[mi][ni][r]);
;       }
; __device__ __forceinline__ void phase_merge(const KP& p, char* smem, int* q, int xcc) {
;     ...
;           [&](int mi, int ni, int r, int row, int col, float v) {
;             const float gz = (float)G[(size_t)row * NU + col];
;             tot[mi][ni][r] += sigmoidf_(gz) * v;
;           },
	v_cvt_f32_f16_e32 v68, v194
	v_cvt_f32_f16_e32 v69, v195
	v_add_u32_e32 v96, 0x7b400, v94
	global_load_ushort v194, v96, s[40:41]
	v_add_u32_e32 v96, 0x7ee00, v94
	global_load_ushort v195, v96, s[40:41]
	v_mul_f32_e32 v68, 0xbfb8aa3b, v68
	v_mul_f32_e32 v69, 0xbfb8aa3b, v69
	v_exp_f32_e32 v68, v68
	v_exp_f32_e32 v69, v69
	s_nop 0
	v_pk_add_f32 v[68:69], v[68:69], 1.0 op_sel_hi:[1,0]
	s_nop 0
	v_div_scale_f32 v70, s[2:3], v69, v69, 1.0
	v_rcp_f32_e32 v71, v70
	s_nop 0
	v_fma_f32 v72, -v70, v71, 1.0
	v_fmac_f32_e32 v71, v72, v71
	v_div_scale_f32 v72, vcc, 1.0, v69, 1.0
	v_mul_f32_e32 v73, v72, v71
	v_fma_f32 v74, -v70, v73, v72
	v_fmac_f32_e32 v73, v74, v71
	v_fma_f32 v70, -v70, v73, v72
	v_div_fmas_f32 v70, v70, v71, v73
	v_div_fixup_f32 v69, v70, v69, 1.0
	v_div_scale_f32 v70, s[2:3], v68, v68, 1.0
	v_rcp_f32_e32 v71, v70
	s_nop 0
	v_fma_f32 v72, -v70, v71, 1.0
	v_fmac_f32_e32 v71, v72, v71
	v_div_scale_f32 v72, vcc, 1.0, v68, 1.0
	v_mul_f32_e32 v73, v72, v71
	v_fma_f32 v74, -v70, v73, v72
	v_fmac_f32_e32 v73, v74, v71
	v_fma_f32 v70, -v70, v73, v72
	v_div_fmas_f32 v70, v70, v71, v73
	v_div_fixup_f32 v68, v70, v68, 1.0
	v_pk_fma_f32 v[158:159], v[52:53], v[68:69], v[158:159]
	s_waitcnt vmcnt(30)
	v_cvt_f32_f16_e32 v68, v196
	v_cvt_f32_f16_e32 v69, v197
	v_add_u32_e32 v96, 0x91000, v94
	global_load_ushort v196, v96, s[40:41]
	v_add_u32_e32 v96, 0x94a00, v94
	global_load_ushort v197, v96, s[40:41]
	v_mul_f32_e32 v68, 0xbfb8aa3b, v68
	v_mul_f32_e32 v69, 0xbfb8aa3b, v69
	v_exp_f32_e32 v68, v68
	v_exp_f32_e32 v69, v69
	s_nop 0
	v_pk_add_f32 v[68:69], v[68:69], 1.0 op_sel_hi:[1,0]
	s_nop 0
	v_div_scale_f32 v70, s[2:3], v69, v69, 1.0
	v_rcp_f32_e32 v71, v70
	s_nop 0
	v_fma_f32 v72, -v70, v71, 1.0
	v_fmac_f32_e32 v71, v72, v71
	v_div_scale_f32 v72, vcc, 1.0, v69, 1.0
	v_mul_f32_e32 v73, v72, v71
	v_fma_f32 v74, -v70, v73, v72
	v_fmac_f32_e32 v73, v74, v71
	v_fma_f32 v70, -v70, v73, v72
	v_div_fmas_f32 v70, v70, v71, v73
	v_div_fixup_f32 v69, v70, v69, 1.0
	v_div_scale_f32 v70, s[2:3], v68, v68, 1.0
	v_rcp_f32_e32 v71, v70
	s_nop 0
	v_fma_f32 v72, -v70, v71, 1.0
	v_fmac_f32_e32 v71, v72, v71
	v_div_scale_f32 v72, vcc, 1.0, v68, 1.0
	v_mul_f32_e32 v73, v72, v71
	v_fma_f32 v74, -v70, v73, v72
	v_fmac_f32_e32 v73, v74, v71
	v_fma_f32 v70, -v70, v73, v72
	v_div_fmas_f32 v70, v70, v71, v73
	v_div_fixup_f32 v68, v70, v68, 1.0
	v_pk_fma_f32 v[156:157], v[54:55], v[68:69], v[156:157]
	s_waitcnt vmcnt(30)
	v_cvt_f32_f16_e32 v68, v198
	v_cvt_f32_f16_e32 v69, v199
	v_add_u32_e32 v96, 0x98400, v94
	global_load_ushort v198, v96, s[40:41]
	v_add_u32_e32 v96, 0x9be00, v94
	global_load_ushort v199, v96, s[40:41]
	v_mul_f32_e32 v68, 0xbfb8aa3b, v68
	v_mul_f32_e32 v69, 0xbfb8aa3b, v69
	v_exp_f32_e32 v68, v68
	v_exp_f32_e32 v69, v69
	s_nop 0
	v_pk_add_f32 v[68:69], v[68:69], 1.0 op_sel_hi:[1,0]
	s_nop 0
	v_div_scale_f32 v70, s[2:3], v69, v69, 1.0
	v_rcp_f32_e32 v71, v70
	s_nop 0
	v_fma_f32 v72, -v70, v71, 1.0
	v_fmac_f32_e32 v71, v72, v71
	v_div_scale_f32 v72, vcc, 1.0, v69, 1.0
	v_mul_f32_e32 v73, v72, v71
	v_fma_f32 v74, -v70, v73, v72
	v_fmac_f32_e32 v73, v74, v71
	v_fma_f32 v70, -v70, v73, v72
	v_div_fmas_f32 v70, v70, v71, v73
	v_div_fixup_f32 v69, v70, v69, 1.0
	v_div_scale_f32 v70, s[2:3], v68, v68, 1.0
	v_rcp_f32_e32 v71, v70
	s_nop 0
	v_fma_f32 v72, -v70, v71, 1.0
	v_fmac_f32_e32 v71, v72, v71
	v_div_scale_f32 v72, vcc, 1.0, v68, 1.0
	v_mul_f32_e32 v73, v72, v71
	v_fma_f32 v74, -v70, v73, v72
	v_fmac_f32_e32 v73, v74, v71
	v_fma_f32 v70, -v70, v73, v72
	v_div_fmas_f32 v70, v70, v71, v73
	v_div_fixup_f32 v68, v70, v68, 1.0
	v_pk_fma_f32 v[154:155], v[56:57], v[68:69], v[154:155]
	s_waitcnt vmcnt(30)
	v_cvt_f32_f16_e32 v68, v200
	v_cvt_f32_f16_e32 v69, v201
	v_add_u32_e32 v96, 0xae000, v94
	global_load_ushort v200, v96, s[40:41]
	v_add_u32_e32 v96, 0xb1a00, v94
	global_load_ushort v201, v96, s[40:41]
	v_mul_f32_e32 v68, 0xbfb8aa3b, v68
	v_mul_f32_e32 v69, 0xbfb8aa3b, v69
	v_exp_f32_e32 v68, v68
	v_exp_f32_e32 v69, v69
	s_nop 0
	v_pk_add_f32 v[68:69], v[68:69], 1.0 op_sel_hi:[1,0]
	s_nop 0
	v_div_scale_f32 v70, s[2:3], v69, v69, 1.0
	v_rcp_f32_e32 v71, v70
	s_nop 0
	v_fma_f32 v72, -v70, v71, 1.0
	v_fmac_f32_e32 v71, v72, v71
	v_div_scale_f32 v72, vcc, 1.0, v69, 1.0
	v_mul_f32_e32 v73, v72, v71
	v_fma_f32 v74, -v70, v73, v72
	v_fmac_f32_e32 v73, v74, v71
	v_fma_f32 v70, -v70, v73, v72
	v_div_fmas_f32 v70, v70, v71, v73
	v_div_fixup_f32 v69, v70, v69, 1.0
	v_div_scale_f32 v70, s[2:3], v68, v68, 1.0
	v_rcp_f32_e32 v71, v70
	s_nop 0
	v_fma_f32 v72, -v70, v71, 1.0
	v_fmac_f32_e32 v71, v72, v71
	v_div_scale_f32 v72, vcc, 1.0, v68, 1.0
	v_mul_f32_e32 v73, v72, v71
	v_fma_f32 v74, -v70, v73, v72
	v_fmac_f32_e32 v73, v74, v71
	v_fma_f32 v70, -v70, v73, v72
	v_div_fmas_f32 v70, v70, v71, v73
	v_div_fixup_f32 v68, v70, v68, 1.0
	v_pk_fma_f32 v[152:153], v[58:59], v[68:69], v[152:153]
	s_waitcnt vmcnt(30)
	v_cvt_f32_f16_e32 v68, v202
	v_cvt_f32_f16_e32 v69, v203
	v_add_u32_e32 v96, 0xb5400, v94
	global_load_ushort v202, v96, s[40:41]
	v_add_u32_e32 v96, 0xb8e00, v94
	global_load_ushort v203, v96, s[40:41]
	v_mul_f32_e32 v68, 0xbfb8aa3b, v68
	v_mul_f32_e32 v69, 0xbfb8aa3b, v69
	v_exp_f32_e32 v68, v68
	v_exp_f32_e32 v69, v69
	s_nop 0
	v_pk_add_f32 v[68:69], v[68:69], 1.0 op_sel_hi:[1,0]
	s_nop 0
	v_div_scale_f32 v70, s[2:3], v69, v69, 1.0
	v_rcp_f32_e32 v71, v70
	s_nop 0
	v_fma_f32 v72, -v70, v71, 1.0
	v_fmac_f32_e32 v71, v72, v71
	v_div_scale_f32 v72, vcc, 1.0, v69, 1.0
	v_mul_f32_e32 v73, v72, v71
	v_fma_f32 v74, -v70, v73, v72
	v_fmac_f32_e32 v73, v74, v71
	v_fma_f32 v70, -v70, v73, v72
	v_div_fmas_f32 v70, v70, v71, v73
	v_div_fixup_f32 v69, v70, v69, 1.0
	v_div_scale_f32 v70, s[2:3], v68, v68, 1.0
	v_rcp_f32_e32 v71, v70
	s_nop 0
	v_fma_f32 v72, -v70, v71, 1.0
	v_fmac_f32_e32 v71, v72, v71
	v_div_scale_f32 v72, vcc, 1.0, v68, 1.0
	v_mul_f32_e32 v73, v72, v71
	v_fma_f32 v74, -v70, v73, v72
	v_fmac_f32_e32 v73, v74, v71
	v_fma_f32 v70, -v70, v73, v72
	v_div_fmas_f32 v70, v70, v71, v73
	v_div_fixup_f32 v68, v70, v68, 1.0
	v_pk_fma_f32 v[150:151], v[60:61], v[68:69], v[150:151]
	s_waitcnt vmcnt(30)
; __device__ __forceinline__ float sigmoidf_(float x) { return 1.f / (1.f + __expf(-x)); }
; template <int NI, class LA, class LB, class EP>
; __device__ __forceinline__ void gemm_tile(int K, LA loadA, LB loadB, EP epi, char* smem) {
;     ...
; #pragma unroll
;   for (int mi = 0; mi < 2; ++mi)
; #pragma unroll
;     for (int ni = 0; ni < NI; ++ni)
; #pragma unroll
;       for (int r = 0; r < 16; ++r) {
;         const int row = wm * 64 + mi * 32 + (r & 3) + 8 * (r >> 2) + 4 * (lane >> 5);
;         const int col = wn * (NI * 32) + ni * 32 + (lane & 31);
;         epi(mi, ni, r, row, col, acc[mi][ni][r]);
;       }
; __device__ __forceinline__ void phase_merge(const KP& p, char* smem, int* q, int xcc) {
;     ...
;           [&](int mi, int ni, int r, int row, int col, float v) {
;             const float gz = (float)G[(size_t)row * NU + col];
;             tot[mi][ni][r] += sigmoidf_(gz) * v;
;           },
	v_cvt_f32_f16_e32 v68, v204
	v_cvt_f32_f16_e32 v69, v205
	v_add_u32_e32 v96, 0xcb000, v94
	global_load_ushort v204, v96, s[40:41]
	v_add_u32_e32 v96, 0xcea00, v94
	global_load_ushort v205, v96, s[40:41]
	v_mul_f32_e32 v68, 0xbfb8aa3b, v68
	v_mul_f32_e32 v69, 0xbfb8aa3b, v69
	v_exp_f32_e32 v68, v68
	v_exp_f32_e32 v69, v69
	s_nop 0
	v_pk_add_f32 v[68:69], v[68:69], 1.0 op_sel_hi:[1,0]
	s_nop 0
	v_div_scale_f32 v70, s[2:3], v69, v69, 1.0
	v_rcp_f32_e32 v71, v70
	s_nop 0
	v_fma_f32 v72, -v70, v71, 1.0
	v_fmac_f32_e32 v71, v72, v71
	v_div_scale_f32 v72, vcc, 1.0, v69, 1.0
	v_mul_f32_e32 v73, v72, v71
	v_fma_f32 v74, -v70, v73, v72
	v_fmac_f32_e32 v73, v74, v71
	v_fma_f32 v70, -v70, v73, v72
	v_div_fmas_f32 v70, v70, v71, v73
	v_div_fixup_f32 v69, v70, v69, 1.0
	v_div_scale_f32 v70, s[2:3], v68, v68, 1.0
	v_rcp_f32_e32 v71, v70
	s_nop 0
	v_fma_f32 v72, -v70, v71, 1.0
	v_fmac_f32_e32 v71, v72, v71
	v_div_scale_f32 v72, vcc, 1.0, v68, 1.0
	v_mul_f32_e32 v73, v72, v71
	v_fma_f32 v74, -v70, v73, v72
	v_fmac_f32_e32 v73, v74, v71
	v_fma_f32 v70, -v70, v73, v72
	v_div_fmas_f32 v70, v70, v71, v73
	v_div_fixup_f32 v68, v70, v68, 1.0
	v_pk_fma_f32 v[148:149], v[62:63], v[68:69], v[148:149]
	s_waitcnt vmcnt(30)
	v_cvt_f32_f16_e32 v68, v206
	v_cvt_f32_f16_e32 v69, v207
	v_add_u32_e32 v96, 0xd2400, v94
	global_load_ushort v206, v96, s[40:41]
	v_add_u32_e32 v96, 0xd5e00, v94
	global_load_ushort v207, v96, s[40:41]
	v_mul_f32_e32 v68, 0xbfb8aa3b, v68
	v_mul_f32_e32 v69, 0xbfb8aa3b, v69
	v_exp_f32_e32 v68, v68
	v_exp_f32_e32 v69, v69
	s_nop 0
	v_pk_add_f32 v[68:69], v[68:69], 1.0 op_sel_hi:[1,0]
	s_nop 0
	v_div_scale_f32 v70, s[2:3], v69, v69, 1.0
	v_rcp_f32_e32 v71, v70
	s_nop 0
	v_fma_f32 v72, -v70, v71, 1.0
	v_fmac_f32_e32 v71, v72, v71
	v_div_scale_f32 v72, vcc, 1.0, v69, 1.0
	v_mul_f32_e32 v73, v72, v71
	v_fma_f32 v74, -v70, v73, v72
	v_fmac_f32_e32 v73, v74, v71
	v_fma_f32 v70, -v70, v73, v72
	v_div_fmas_f32 v70, v70, v71, v73
	v_div_fixup_f32 v69, v70, v69, 1.0
	v_div_scale_f32 v70, s[2:3], v68, v68, 1.0
	v_rcp_f32_e32 v71, v70
	s_nop 0
	v_fma_f32 v72, -v70, v71, 1.0
	v_fmac_f32_e32 v71, v72, v71
	v_div_scale_f32 v72, vcc, 1.0, v68, 1.0
	v_mul_f32_e32 v73, v72, v71
	v_fma_f32 v74, -v70, v73, v72
	v_fmac_f32_e32 v73, v74, v71
	v_fma_f32 v70, -v70, v73, v72
	v_div_fmas_f32 v70, v70, v71, v73
	v_div_fixup_f32 v68, v70, v68, 1.0
	v_pk_fma_f32 v[146:147], v[64:65], v[68:69], v[146:147]
	s_waitcnt vmcnt(30)
	v_cvt_f32_f16_e32 v68, v208
	v_cvt_f32_f16_e32 v69, v209
	v_add_u32_e32 v96, 0x74000, v94
	global_load_ushort v208, v96, s[40:41] offset:64
	v_add_u32_e32 v96, 0x77a00, v94
	global_load_ushort v209, v96, s[40:41] offset:64
	v_mul_f32_e32 v68, 0xbfb8aa3b, v68
	v_mul_f32_e32 v69, 0xbfb8aa3b, v69
	v_exp_f32_e32 v68, v68
	v_exp_f32_e32 v69, v69
	s_nop 0
	v_pk_add_f32 v[68:69], v[68:69], 1.0 op_sel_hi:[1,0]
	s_nop 0
	v_div_scale_f32 v70, s[2:3], v69, v69, 1.0
	v_rcp_f32_e32 v71, v70
	s_nop 0
	v_fma_f32 v72, -v70, v71, 1.0
	v_fmac_f32_e32 v71, v72, v71
	v_div_scale_f32 v72, vcc, 1.0, v69, 1.0
	v_mul_f32_e32 v73, v72, v71
	v_fma_f32 v74, -v70, v73, v72
	v_fmac_f32_e32 v73, v74, v71
	v_fma_f32 v70, -v70, v73, v72
	v_div_fmas_f32 v70, v70, v71, v73
	v_div_fixup_f32 v69, v70, v69, 1.0
	v_div_scale_f32 v70, s[2:3], v68, v68, 1.0
	v_rcp_f32_e32 v71, v70
	s_nop 0
	v_fma_f32 v72, -v70, v71, 1.0
	v_fmac_f32_e32 v71, v72, v71
	v_div_scale_f32 v72, vcc, 1.0, v68, 1.0
	v_mul_f32_e32 v73, v72, v71
	v_fma_f32 v74, -v70, v73, v72
	v_fmac_f32_e32 v73, v74, v71
	v_fma_f32 v70, -v70, v73, v72
	v_div_fmas_f32 v70, v70, v71, v73
	v_div_fixup_f32 v68, v70, v68, 1.0
	v_pk_fma_f32 v[144:145], v[34:35], v[68:69], v[144:145]
	s_waitcnt vmcnt(30)
	v_cvt_f32_f16_e32 v68, v210
	v_cvt_f32_f16_e32 v69, v211
	v_add_u32_e32 v96, 0x7b400, v94
	global_load_ushort v210, v96, s[40:41] offset:64
	v_add_u32_e32 v96, 0x7ee00, v94
	global_load_ushort v211, v96, s[40:41] offset:64
	v_mul_f32_e32 v68, 0xbfb8aa3b, v68
	v_mul_f32_e32 v69, 0xbfb8aa3b, v69
	v_exp_f32_e32 v68, v68
	v_exp_f32_e32 v69, v69
	s_nop 0
	v_pk_add_f32 v[68:69], v[68:69], 1.0 op_sel_hi:[1,0]
	s_nop 0
	v_div_scale_f32 v70, s[2:3], v69, v69, 1.0
	v_rcp_f32_e32 v71, v70
	s_nop 0
	v_fma_f32 v72, -v70, v71, 1.0
	v_fmac_f32_e32 v71, v72, v71
	v_div_scale_f32 v72, vcc, 1.0, v69, 1.0
	v_mul_f32_e32 v73, v72, v71
	v_fma_f32 v74, -v70, v73, v72
	v_fmac_f32_e32 v73, v74, v71
	v_fma_f32 v70, -v70, v73, v72
	v_div_fmas_f32 v70, v70, v71, v73
	v_div_fixup_f32 v69, v70, v69, 1.0
	v_div_scale_f32 v70, s[2:3], v68, v68, 1.0
	v_rcp_f32_e32 v71, v70
	s_nop 0
	v_fma_f32 v72, -v70, v71, 1.0
	v_fmac_f32_e32 v71, v72, v71
	v_div_scale_f32 v72, vcc, 1.0, v68, 1.0
	v_mul_f32_e32 v73, v72, v71
	v_fma_f32 v74, -v70, v73, v72
	v_fmac_f32_e32 v73, v74, v71
	v_fma_f32 v70, -v70, v73, v72
	v_div_fmas_f32 v70, v70, v71, v73
	v_div_fixup_f32 v68, v70, v68, 1.0
	v_pk_fma_f32 v[142:143], v[36:37], v[68:69], v[142:143]
	s_waitcnt vmcnt(30)
	v_cvt_f32_f16_e32 v68, v212
	v_cvt_f32_f16_e32 v69, v213
	v_add_u32_e32 v96, 0x91000, v94
	global_load_ushort v212, v96, s[40:41] offset:64
	v_add_u32_e32 v96, 0x94a00, v94
	global_load_ushort v213, v96, s[40:41] offset:64
	v_mul_f32_e32 v68, 0xbfb8aa3b, v68
	v_mul_f32_e32 v69, 0xbfb8aa3b, v69
	v_exp_f32_e32 v68, v68
	v_exp_f32_e32 v69, v69
	s_nop 0
	v_pk_add_f32 v[68:69], v[68:69], 1.0 op_sel_hi:[1,0]
	s_nop 0
	v_div_scale_f32 v70, s[2:3], v69, v69, 1.0
	v_rcp_f32_e32 v71, v70
	s_nop 0
	v_fma_f32 v72, -v70, v71, 1.0
	v_fmac_f32_e32 v71, v72, v71
	v_div_scale_f32 v72, vcc, 1.0, v69, 1.0
	v_mul_f32_e32 v73, v72, v71
	v_fma_f32 v74, -v70, v73, v72
	v_fmac_f32_e32 v73, v74, v71
	v_fma_f32 v70, -v70, v73, v72
	v_div_fmas_f32 v70, v70, v71, v73
	v_div_fixup_f32 v69, v70, v69, 1.0
	v_div_scale_f32 v70, s[2:3], v68, v68, 1.0
	v_rcp_f32_e32 v71, v70
	s_nop 0
	v_fma_f32 v72, -v70, v71, 1.0
	v_fmac_f32_e32 v71, v72, v71
	v_div_scale_f32 v72, vcc, 1.0, v68, 1.0
	v_mul_f32_e32 v73, v72, v71
	v_fma_f32 v74, -v70, v73, v72
	v_fmac_f32_e32 v73, v74, v71
	v_fma_f32 v70, -v70, v73, v72
	v_div_fmas_f32 v70, v70, v71, v73
	v_div_fixup_f32 v68, v70, v68, 1.0
	v_pk_fma_f32 v[140:141], v[38:39], v[68:69], v[140:141]
	s_waitcnt vmcnt(30)
; __device__ __forceinline__ float sigmoidf_(float x) { return 1.f / (1.f + __expf(-x)); }
; template <int NI, class LA, class LB, class EP>
; __device__ __forceinline__ void gemm_tile(int K, LA loadA, LB loadB, EP epi, char* smem) {
;     ...
; #pragma unroll
;   for (int mi = 0; mi < 2; ++mi)
; #pragma unroll
;     for (int ni = 0; ni < NI; ++ni)
; #pragma unroll
;       for (int r = 0; r < 16; ++r) {
;         const int row = wm * 64 + mi * 32 + (r & 3) + 8 * (r >> 2) + 4 * (lane >> 5);
;         const int col = wn * (NI * 32) + ni * 32 + (lane & 31);
;         epi(mi, ni, r, row, col, acc[mi][ni][r]);
;       }
; __device__ __forceinline__ void phase_merge(const KP& p, char* smem, int* q, int xcc) {
;     ...
;           [&](int mi, int ni, int r, int row, int col, float v) {
;             const float gz = (float)G[(size_t)row * NU + col];
;             tot[mi][ni][r] += sigmoidf_(gz) * v;
;           },
	v_cvt_f32_f16_e32 v68, v214
	v_cvt_f32_f16_e32 v69, v215
	v_add_u32_e32 v96, 0x98400, v94
	global_load_ushort v214, v96, s[40:41] offset:64
	v_add_u32_e32 v96, 0x9be00, v94
	global_load_ushort v215, v96, s[40:41] offset:64
	v_mul_f32_e32 v68, 0xbfb8aa3b, v68
	v_mul_f32_e32 v69, 0xbfb8aa3b, v69
	v_exp_f32_e32 v68, v68
	v_exp_f32_e32 v69, v69
	s_nop 0
	v_pk_add_f32 v[68:69], v[68:69], 1.0 op_sel_hi:[1,0]
	s_nop 0
	v_div_scale_f32 v70, s[2:3], v69, v69, 1.0
	v_rcp_f32_e32 v71, v70
	s_nop 0
	v_fma_f32 v72, -v70, v71, 1.0
	v_fmac_f32_e32 v71, v72, v71
	v_div_scale_f32 v72, vcc, 1.0, v69, 1.0
	v_mul_f32_e32 v73, v72, v71
	v_fma_f32 v74, -v70, v73, v72
	v_fmac_f32_e32 v73, v74, v71
	v_fma_f32 v70, -v70, v73, v72
	v_div_fmas_f32 v70, v70, v71, v73
	v_div_fixup_f32 v69, v70, v69, 1.0
	v_div_scale_f32 v70, s[2:3], v68, v68, 1.0
	v_rcp_f32_e32 v71, v70
	s_nop 0
	v_fma_f32 v72, -v70, v71, 1.0
	v_fmac_f32_e32 v71, v72, v71
	v_div_scale_f32 v72, vcc, 1.0, v68, 1.0
	v_mul_f32_e32 v73, v72, v71
	v_fma_f32 v74, -v70, v73, v72
	v_fmac_f32_e32 v73, v74, v71
	v_fma_f32 v70, -v70, v73, v72
	v_div_fmas_f32 v70, v70, v71, v73
	v_div_fixup_f32 v68, v70, v68, 1.0
	v_pk_fma_f32 v[138:139], v[40:41], v[68:69], v[138:139]
	s_waitcnt vmcnt(30)
	v_cvt_f32_f16_e32 v68, v216
	v_cvt_f32_f16_e32 v69, v217
	v_add_u32_e32 v96, 0xae000, v94
	global_load_ushort v216, v96, s[40:41] offset:64
	v_add_u32_e32 v96, 0xb1a00, v94
	global_load_ushort v217, v96, s[40:41] offset:64
	v_mul_f32_e32 v68, 0xbfb8aa3b, v68
	v_mul_f32_e32 v69, 0xbfb8aa3b, v69
	v_exp_f32_e32 v68, v68
	v_exp_f32_e32 v69, v69
	s_nop 0
	v_pk_add_f32 v[68:69], v[68:69], 1.0 op_sel_hi:[1,0]
	s_nop 0
	v_div_scale_f32 v70, s[2:3], v69, v69, 1.0
	v_rcp_f32_e32 v71, v70
	s_nop 0
	v_fma_f32 v72, -v70, v71, 1.0
	v_fmac_f32_e32 v71, v72, v71
	v_div_scale_f32 v72, vcc, 1.0, v69, 1.0
	v_mul_f32_e32 v73, v72, v71
	v_fma_f32 v74, -v70, v73, v72
	v_fmac_f32_e32 v73, v74, v71
	v_fma_f32 v70, -v70, v73, v72
	v_div_fmas_f32 v70, v70, v71, v73
	v_div_fixup_f32 v69, v70, v69, 1.0
	v_div_scale_f32 v70, s[2:3], v68, v68, 1.0
	v_rcp_f32_e32 v71, v70
	s_nop 0
	v_fma_f32 v72, -v70, v71, 1.0
	v_fmac_f32_e32 v71, v72, v71
	v_div_scale_f32 v72, vcc, 1.0, v68, 1.0
	v_mul_f32_e32 v73, v72, v71
	v_fma_f32 v74, -v70, v73, v72
	v_fmac_f32_e32 v73, v74, v71
	v_fma_f32 v70, -v70, v73, v72
	v_div_fmas_f32 v70, v70, v71, v73
	v_div_fixup_f32 v68, v70, v68, 1.0
	v_pk_fma_f32 v[136:137], v[42:43], v[68:69], v[136:137]
	s_waitcnt vmcnt(30)
	v_cvt_f32_f16_e32 v68, v218
	v_cvt_f32_f16_e32 v69, v219
	v_add_u32_e32 v96, 0xb5400, v94
	global_load_ushort v218, v96, s[40:41] offset:64
	v_add_u32_e32 v96, 0xb8e00, v94
	global_load_ushort v219, v96, s[40:41] offset:64
	v_mul_f32_e32 v68, 0xbfb8aa3b, v68
	v_mul_f32_e32 v69, 0xbfb8aa3b, v69
	v_exp_f32_e32 v68, v68
	v_exp_f32_e32 v69, v69
	s_nop 0
	v_pk_add_f32 v[68:69], v[68:69], 1.0 op_sel_hi:[1,0]
	s_nop 0
	v_div_scale_f32 v70, s[2:3], v69, v69, 1.0
	v_rcp_f32_e32 v71, v70
	s_nop 0
	v_fma_f32 v72, -v70, v71, 1.0
	v_fmac_f32_e32 v71, v72, v71
	v_div_scale_f32 v72, vcc, 1.0, v69, 1.0
	v_mul_f32_e32 v73, v72, v71
	v_fma_f32 v74, -v70, v73, v72
	v_fmac_f32_e32 v73, v74, v71
	v_fma_f32 v70, -v70, v73, v72
	v_div_fmas_f32 v70, v70, v71, v73
	v_div_fixup_f32 v69, v70, v69, 1.0
	v_div_scale_f32 v70, s[2:3], v68, v68, 1.0
	v_rcp_f32_e32 v71, v70
	s_nop 0
	v_fma_f32 v72, -v70, v71, 1.0
	v_fmac_f32_e32 v71, v72, v71
	v_div_scale_f32 v72, vcc, 1.0, v68, 1.0
	v_mul_f32_e32 v73, v72, v71
	v_fma_f32 v74, -v70, v73, v72
	v_fmac_f32_e32 v73, v74, v71
	v_fma_f32 v70, -v70, v73, v72
	v_div_fmas_f32 v70, v70, v71, v73
	v_div_fixup_f32 v68, v70, v68, 1.0
	v_pk_fma_f32 v[134:135], v[44:45], v[68:69], v[134:135]
	s_waitcnt vmcnt(30)
	v_cvt_f32_f16_e32 v68, v220
	v_cvt_f32_f16_e32 v69, v221
	v_add_u32_e32 v96, 0xcb000, v94
	global_load_ushort v220, v96, s[40:41] offset:64
	v_add_u32_e32 v96, 0xcea00, v94
	global_load_ushort v221, v96, s[40:41] offset:64
	v_mul_f32_e32 v68, 0xbfb8aa3b, v68
	v_mul_f32_e32 v69, 0xbfb8aa3b, v69
	v_exp_f32_e32 v68, v68
	v_exp_f32_e32 v69, v69
	s_nop 0
	v_pk_add_f32 v[68:69], v[68:69], 1.0 op_sel_hi:[1,0]
	s_nop 0
	v_div_scale_f32 v70, s[2:3], v69, v69, 1.0
	v_rcp_f32_e32 v71, v70
	s_nop 0
	v_fma_f32 v72, -v70, v71, 1.0
	v_fmac_f32_e32 v71, v72, v71
	v_div_scale_f32 v72, vcc, 1.0, v69, 1.0
	v_mul_f32_e32 v73, v72, v71
	v_fma_f32 v74, -v70, v73, v72
	v_fmac_f32_e32 v73, v74, v71
	v_fma_f32 v70, -v70, v73, v72
	v_div_fmas_f32 v70, v70, v71, v73
	v_div_fixup_f32 v69, v70, v69, 1.0
	v_div_scale_f32 v70, s[2:3], v68, v68, 1.0
	v_rcp_f32_e32 v71, v70
	s_nop 0
	v_fma_f32 v72, -v70, v71, 1.0
	v_fmac_f32_e32 v71, v72, v71
	v_div_scale_f32 v72, vcc, 1.0, v68, 1.0
	v_mul_f32_e32 v73, v72, v71
	v_fma_f32 v74, -v70, v73, v72
	v_fmac_f32_e32 v73, v74, v71
	v_fma_f32 v70, -v70, v73, v72
	v_div_fmas_f32 v70, v70, v71, v73
	v_div_fixup_f32 v68, v70, v68, 1.0
	v_pk_fma_f32 v[132:133], v[46:47], v[68:69], v[132:133]
	s_waitcnt vmcnt(30)
	v_cvt_f32_f16_e32 v68, v222
	v_cvt_f32_f16_e32 v69, v223
	v_add_u32_e32 v96, 0xd2400, v94
	global_load_ushort v222, v96, s[40:41] offset:64
	v_add_u32_e32 v96, 0xd5e00, v94
	global_load_ushort v223, v96, s[40:41] offset:64
	v_mul_f32_e32 v68, 0xbfb8aa3b, v68
	v_mul_f32_e32 v69, 0xbfb8aa3b, v69
	v_exp_f32_e32 v68, v68
	v_exp_f32_e32 v69, v69
	s_nop 0
	v_pk_add_f32 v[68:69], v[68:69], 1.0 op_sel_hi:[1,0]
	s_nop 0
	v_div_scale_f32 v70, s[2:3], v69, v69, 1.0
	v_rcp_f32_e32 v71, v70
	s_nop 0
	v_fma_f32 v72, -v70, v71, 1.0
	v_fmac_f32_e32 v71, v72, v71
	v_div_scale_f32 v72, vcc, 1.0, v69, 1.0
	v_mul_f32_e32 v73, v72, v71
	v_fma_f32 v74, -v70, v73, v72
	v_fmac_f32_e32 v73, v74, v71
	v_fma_f32 v70, -v70, v73, v72
	v_div_fmas_f32 v70, v70, v71, v73
	v_div_fixup_f32 v69, v70, v69, 1.0
	v_div_scale_f32 v70, s[2:3], v68, v68, 1.0
	v_rcp_f32_e32 v71, v70
	s_nop 0
	v_fma_f32 v72, -v70, v71, 1.0
	v_fmac_f32_e32 v71, v72, v71
	v_div_scale_f32 v72, vcc, 1.0, v68, 1.0
	v_mul_f32_e32 v73, v72, v71
	v_fma_f32 v74, -v70, v73, v72
	v_fmac_f32_e32 v73, v74, v71
	v_fma_f32 v70, -v70, v73, v72
	v_div_fmas_f32 v70, v70, v71, v73
	v_div_fixup_f32 v68, v70, v68, 1.0
	v_pk_fma_f32 v[130:131], v[48:49], v[68:69], v[130:131]
	s_waitcnt vmcnt(30)
; __device__ __forceinline__ float sigmoidf_(float x) { return 1.f / (1.f + __expf(-x)); }
; __device__ __forceinline__ void phase_merge(const KP& p, char* smem, int* q, int xcc) {
;     ...
;       gemm_tile<2>(
;           512, [&](int r, int k) { return *(const uint4*)(A + (size_t)r * 512 + k); },
;           [&](int r, int k) { return *(const uint4*)(B + (size_t)r * 512 + k); },
;           [&](int mi, int ni, int r, int row, int col, float v) {
;             const float gz = (float)G[(size_t)row * NU + col];
;             tot[mi][ni][r] += sigmoidf_(gz) * v;
;           },
;           smem);
;     }
	v_cvt_f32_f16_e32 v68, v192
	v_cvt_f32_f16_e32 v69, v193
	v_mul_f32_e32 v68, 0xbfb8aa3b, v68
	v_mul_f32_e32 v69, 0xbfb8aa3b, v69
	v_exp_f32_e32 v68, v68
	v_exp_f32_e32 v69, v69
	s_nop 0
	v_pk_add_f32 v[68:69], v[68:69], 1.0 op_sel_hi:[1,0]
	s_nop 0
	v_div_scale_f32 v70, s[2:3], v69, v69, 1.0
	v_rcp_f32_e32 v71, v70
	s_nop 0
	v_fma_f32 v72, -v70, v71, 1.0
	v_fmac_f32_e32 v71, v72, v71
	v_div_scale_f32 v72, vcc, 1.0, v69, 1.0
	v_mul_f32_e32 v73, v72, v71
	v_fma_f32 v74, -v70, v73, v72
	v_fmac_f32_e32 v73, v74, v71
	v_fma_f32 v70, -v70, v73, v72
	v_div_fmas_f32 v70, v70, v71, v73
	v_div_fixup_f32 v69, v70, v69, 1.0
	v_div_scale_f32 v70, s[2:3], v68, v68, 1.0
	v_rcp_f32_e32 v71, v70
	s_nop 0
	v_fma_f32 v72, -v70, v71, 1.0
	v_fmac_f32_e32 v71, v72, v71
	v_div_scale_f32 v72, vcc, 1.0, v68, 1.0
	v_mul_f32_e32 v73, v72, v71
	v_fma_f32 v74, -v70, v73, v72
	v_fmac_f32_e32 v73, v74, v71
	v_fma_f32 v70, -v70, v73, v72
	v_div_fmas_f32 v70, v70, v71, v73
	v_div_fixup_f32 v68, v70, v68, 1.0
	v_pk_fma_f32 v[128:129], v[18:19], v[68:69], v[128:129]
	s_waitcnt vmcnt(28)
	v_cvt_f32_f16_e32 v68, v194
	v_cvt_f32_f16_e32 v69, v195
	v_mul_f32_e32 v68, 0xbfb8aa3b, v68
	v_mul_f32_e32 v69, 0xbfb8aa3b, v69
	v_exp_f32_e32 v68, v68
	v_exp_f32_e32 v69, v69
	s_nop 0
	v_pk_add_f32 v[68:69], v[68:69], 1.0 op_sel_hi:[1,0]
	s_nop 0
	v_div_scale_f32 v70, s[2:3], v69, v69, 1.0
	v_rcp_f32_e32 v71, v70
	s_nop 0
	v_fma_f32 v72, -v70, v71, 1.0
	v_fmac_f32_e32 v71, v72, v71
	v_div_scale_f32 v72, vcc, 1.0, v69, 1.0
	v_mul_f32_e32 v73, v72, v71
	v_fma_f32 v74, -v70, v73, v72
	v_fmac_f32_e32 v73, v74, v71
	v_fma_f32 v70, -v70, v73, v72
	v_div_fmas_f32 v70, v70, v71, v73
	v_div_fixup_f32 v69, v70, v69, 1.0
	v_div_scale_f32 v70, s[2:3], v68, v68, 1.0
	v_rcp_f32_e32 v71, v70
	s_nop 0
	v_fma_f32 v72, -v70, v71, 1.0
	v_fmac_f32_e32 v71, v72, v71
	v_div_scale_f32 v72, vcc, 1.0, v68, 1.0
	v_mul_f32_e32 v73, v72, v71
	v_fma_f32 v74, -v70, v73, v72
	v_fmac_f32_e32 v73, v74, v71
	v_fma_f32 v70, -v70, v73, v72
	v_div_fmas_f32 v70, v70, v71, v73
	v_div_fixup_f32 v68, v70, v68, 1.0
	v_pk_fma_f32 v[126:127], v[20:21], v[68:69], v[126:127]
	s_waitcnt vmcnt(26)
	v_cvt_f32_f16_e32 v68, v196
	v_cvt_f32_f16_e32 v69, v197
	v_mul_f32_e32 v68, 0xbfb8aa3b, v68
	v_mul_f32_e32 v69, 0xbfb8aa3b, v69
	v_exp_f32_e32 v68, v68
	v_exp_f32_e32 v69, v69
	s_nop 0
	v_pk_add_f32 v[68:69], v[68:69], 1.0 op_sel_hi:[1,0]
	s_nop 0
	v_div_scale_f32 v70, s[2:3], v69, v69, 1.0
	v_rcp_f32_e32 v71, v70
	s_nop 0
	v_fma_f32 v72, -v70, v71, 1.0
	v_fmac_f32_e32 v71, v72, v71
	v_div_scale_f32 v72, vcc, 1.0, v69, 1.0
	v_mul_f32_e32 v73, v72, v71
	v_fma_f32 v74, -v70, v73, v72
	v_fmac_f32_e32 v73, v74, v71
	v_fma_f32 v70, -v70, v73, v72
	v_div_fmas_f32 v70, v70, v71, v73
	v_div_fixup_f32 v69, v70, v69, 1.0
	v_div_scale_f32 v70, s[2:3], v68, v68, 1.0
	v_rcp_f32_e32 v71, v70
	s_nop 0
	v_fma_f32 v72, -v70, v71, 1.0
	v_fmac_f32_e32 v71, v72, v71
	v_div_scale_f32 v72, vcc, 1.0, v68, 1.0
	v_mul_f32_e32 v73, v72, v71
	v_fma_f32 v74, -v70, v73, v72
	v_fmac_f32_e32 v73, v74, v71
	v_fma_f32 v70, -v70, v73, v72
	v_div_fmas_f32 v70, v70, v71, v73
	v_div_fixup_f32 v68, v70, v68, 1.0
	v_pk_fma_f32 v[124:125], v[22:23], v[68:69], v[124:125]
	s_waitcnt vmcnt(24)
	v_cvt_f32_f16_e32 v68, v198
	v_cvt_f32_f16_e32 v69, v199
	v_mul_f32_e32 v68, 0xbfb8aa3b, v68
	v_mul_f32_e32 v69, 0xbfb8aa3b, v69
	v_exp_f32_e32 v68, v68
	v_exp_f32_e32 v69, v69
	s_nop 0
	v_pk_add_f32 v[68:69], v[68:69], 1.0 op_sel_hi:[1,0]
	s_nop 0
	v_div_scale_f32 v70, s[2:3], v69, v69, 1.0
	v_rcp_f32_e32 v71, v70
	s_nop 0
	v_fma_f32 v72, -v70, v71, 1.0
	v_fmac_f32_e32 v71, v72, v71
	v_div_scale_f32 v72, vcc, 1.0, v69, 1.0
	v_mul_f32_e32 v73, v72, v71
	v_fma_f32 v74, -v70, v73, v72
	v_fmac_f32_e32 v73, v74, v71
	v_fma_f32 v70, -v70, v73, v72
	v_div_fmas_f32 v70, v70, v71, v73
	v_div_fixup_f32 v69, v70, v69, 1.0
	v_div_scale_f32 v70, s[2:3], v68, v68, 1.0
	v_rcp_f32_e32 v71, v70
	s_nop 0
	v_fma_f32 v72, -v70, v71, 1.0
	v_fmac_f32_e32 v71, v72, v71
	v_div_scale_f32 v72, vcc, 1.0, v68, 1.0
	v_mul_f32_e32 v73, v72, v71
	v_fma_f32 v74, -v70, v73, v72
	v_fmac_f32_e32 v73, v74, v71
	v_fma_f32 v70, -v70, v73, v72
	v_div_fmas_f32 v70, v70, v71, v73
	v_div_fixup_f32 v68, v70, v68, 1.0
	v_pk_fma_f32 v[122:123], v[24:25], v[68:69], v[122:123]
	s_waitcnt vmcnt(22)
	v_cvt_f32_f16_e32 v68, v200
	v_cvt_f32_f16_e32 v69, v201
	v_mul_f32_e32 v68, 0xbfb8aa3b, v68
	v_mul_f32_e32 v69, 0xbfb8aa3b, v69
	v_exp_f32_e32 v68, v68
	v_exp_f32_e32 v69, v69
	s_nop 0
	v_pk_add_f32 v[68:69], v[68:69], 1.0 op_sel_hi:[1,0]
	s_nop 0
	v_div_scale_f32 v70, s[2:3], v69, v69, 1.0
	v_rcp_f32_e32 v71, v70
	s_nop 0
	v_fma_f32 v72, -v70, v71, 1.0
	v_fmac_f32_e32 v71, v72, v71
	v_div_scale_f32 v72, vcc, 1.0, v69, 1.0
	v_mul_f32_e32 v73, v72, v71
	v_fma_f32 v74, -v70, v73, v72
	v_fmac_f32_e32 v73, v74, v71
	v_fma_f32 v70, -v70, v73, v72
	v_div_fmas_f32 v70, v70, v71, v73
	v_div_fixup_f32 v69, v70, v69, 1.0
	v_div_scale_f32 v70, s[2:3], v68, v68, 1.0
	v_rcp_f32_e32 v71, v70
	s_nop 0
	v_fma_f32 v72, -v70, v71, 1.0
	v_fmac_f32_e32 v71, v72, v71
	v_div_scale_f32 v72, vcc, 1.0, v68, 1.0
	v_mul_f32_e32 v73, v72, v71
	v_fma_f32 v74, -v70, v73, v72
	v_fmac_f32_e32 v73, v74, v71
	v_fma_f32 v70, -v70, v73, v72
	v_div_fmas_f32 v70, v70, v71, v73
	v_div_fixup_f32 v68, v70, v68, 1.0
	v_pk_fma_f32 v[120:121], v[26:27], v[68:69], v[120:121]
	s_waitcnt vmcnt(20)
; __device__ __forceinline__ float sigmoidf_(float x) { return 1.f / (1.f + __expf(-x)); }
; __device__ __forceinline__ void phase_merge(const KP& p, char* smem, int* q, int xcc) {
;     ...
;       gemm_tile<2>(
;           512, [&](int r, int k) { return *(const uint4*)(A + (size_t)r * 512 + k); },
;           [&](int r, int k) { return *(const uint4*)(B + (size_t)r * 512 + k); },
;           [&](int mi, int ni, int r, int row, int col, float v) {
;             const float gz = (float)G[(size_t)row * NU + col];
;             tot[mi][ni][r] += sigmoidf_(gz) * v;
;           },
;           smem);
;     }
	v_cvt_f32_f16_e32 v68, v202
	v_cvt_f32_f16_e32 v69, v203
	v_mul_f32_e32 v68, 0xbfb8aa3b, v68
	v_mul_f32_e32 v69, 0xbfb8aa3b, v69
	v_exp_f32_e32 v68, v68
	v_exp_f32_e32 v69, v69
	s_nop 0
	v_pk_add_f32 v[68:69], v[68:69], 1.0 op_sel_hi:[1,0]
	s_nop 0
	v_div_scale_f32 v70, s[2:3], v69, v69, 1.0
	v_rcp_f32_e32 v71, v70
	s_nop 0
	v_fma_f32 v72, -v70, v71, 1.0
	v_fmac_f32_e32 v71, v72, v71
	v_div_scale_f32 v72, vcc, 1.0, v69, 1.0
	v_mul_f32_e32 v73, v72, v71
	v_fma_f32 v74, -v70, v73, v72
	v_fmac_f32_e32 v73, v74, v71
	v_fma_f32 v70, -v70, v73, v72
	v_div_fmas_f32 v70, v70, v71, v73
	v_div_fixup_f32 v69, v70, v69, 1.0
	v_div_scale_f32 v70, s[2:3], v68, v68, 1.0
	v_rcp_f32_e32 v71, v70
	s_nop 0
	v_fma_f32 v72, -v70, v71, 1.0
	v_fmac_f32_e32 v71, v72, v71
	v_div_scale_f32 v72, vcc, 1.0, v68, 1.0
	v_mul_f32_e32 v73, v72, v71
	v_fma_f32 v74, -v70, v73, v72
	v_fmac_f32_e32 v73, v74, v71
	v_fma_f32 v70, -v70, v73, v72
	v_div_fmas_f32 v70, v70, v71, v73
	v_div_fixup_f32 v68, v70, v68, 1.0
	v_pk_fma_f32 v[118:119], v[28:29], v[68:69], v[118:119]
	s_waitcnt vmcnt(18)
	v_cvt_f32_f16_e32 v68, v204
	v_cvt_f32_f16_e32 v69, v205
	v_mul_f32_e32 v68, 0xbfb8aa3b, v68
	v_mul_f32_e32 v69, 0xbfb8aa3b, v69
	v_exp_f32_e32 v68, v68
	v_exp_f32_e32 v69, v69
	s_nop 0
	v_pk_add_f32 v[68:69], v[68:69], 1.0 op_sel_hi:[1,0]
	s_nop 0
	v_div_scale_f32 v70, s[2:3], v69, v69, 1.0
	v_rcp_f32_e32 v71, v70
	s_nop 0
	v_fma_f32 v72, -v70, v71, 1.0
	v_fmac_f32_e32 v71, v72, v71
	v_div_scale_f32 v72, vcc, 1.0, v69, 1.0
	v_mul_f32_e32 v73, v72, v71
	v_fma_f32 v74, -v70, v73, v72
	v_fmac_f32_e32 v73, v74, v71
	v_fma_f32 v70, -v70, v73, v72
	v_div_fmas_f32 v70, v70, v71, v73
	v_div_fixup_f32 v69, v70, v69, 1.0
	v_div_scale_f32 v70, s[2:3], v68, v68, 1.0
	v_rcp_f32_e32 v71, v70
	s_nop 0
	v_fma_f32 v72, -v70, v71, 1.0
	v_fmac_f32_e32 v71, v72, v71
	v_div_scale_f32 v72, vcc, 1.0, v68, 1.0
	v_mul_f32_e32 v73, v72, v71
	v_fma_f32 v74, -v70, v73, v72
	v_fmac_f32_e32 v73, v74, v71
	v_fma_f32 v70, -v70, v73, v72
	v_div_fmas_f32 v70, v70, v71, v73
	v_div_fixup_f32 v68, v70, v68, 1.0
	v_pk_fma_f32 v[116:117], v[30:31], v[68:69], v[116:117]
	s_waitcnt vmcnt(16)
	v_cvt_f32_f16_e32 v68, v206
	v_cvt_f32_f16_e32 v69, v207
	v_mul_f32_e32 v68, 0xbfb8aa3b, v68
	v_mul_f32_e32 v69, 0xbfb8aa3b, v69
	v_exp_f32_e32 v68, v68
	v_exp_f32_e32 v69, v69
	s_nop 0
	v_pk_add_f32 v[68:69], v[68:69], 1.0 op_sel_hi:[1,0]
	s_nop 0
	v_div_scale_f32 v70, s[2:3], v69, v69, 1.0
	v_rcp_f32_e32 v71, v70
	s_nop 0
	v_fma_f32 v72, -v70, v71, 1.0
	v_fmac_f32_e32 v71, v72, v71
	v_div_scale_f32 v72, vcc, 1.0, v69, 1.0
	v_mul_f32_e32 v73, v72, v71
	v_fma_f32 v74, -v70, v73, v72
	v_fmac_f32_e32 v73, v74, v71
	v_fma_f32 v70, -v70, v73, v72
	v_div_fmas_f32 v70, v70, v71, v73
	v_div_fixup_f32 v69, v70, v69, 1.0
	v_div_scale_f32 v70, s[2:3], v68, v68, 1.0
	v_rcp_f32_e32 v71, v70
	s_nop 0
	v_fma_f32 v72, -v70, v71, 1.0
	v_fmac_f32_e32 v71, v72, v71
	v_div_scale_f32 v72, vcc, 1.0, v68, 1.0
	v_mul_f32_e32 v73, v72, v71
	v_fma_f32 v74, -v70, v73, v72
	v_fmac_f32_e32 v73, v74, v71
	v_fma_f32 v70, -v70, v73, v72
	v_div_fmas_f32 v70, v70, v71, v73
	v_div_fixup_f32 v68, v70, v68, 1.0
	v_pk_fma_f32 v[114:115], v[32:33], v[68:69], v[114:115]
	s_waitcnt vmcnt(14)
	v_cvt_f32_f16_e32 v68, v208
	v_cvt_f32_f16_e32 v69, v209
	v_mul_f32_e32 v68, 0xbfb8aa3b, v68
	v_mul_f32_e32 v69, 0xbfb8aa3b, v69
	v_exp_f32_e32 v68, v68
	v_exp_f32_e32 v69, v69
	s_nop 0
	v_pk_add_f32 v[68:69], v[68:69], 1.0 op_sel_hi:[1,0]
	s_nop 0
	v_div_scale_f32 v70, s[2:3], v69, v69, 1.0
	v_rcp_f32_e32 v71, v70
	s_nop 0
	v_fma_f32 v72, -v70, v71, 1.0
	v_fmac_f32_e32 v71, v72, v71
	v_div_scale_f32 v72, vcc, 1.0, v69, 1.0
	v_mul_f32_e32 v73, v72, v71
	v_fma_f32 v74, -v70, v73, v72
	v_fmac_f32_e32 v73, v74, v71
	v_fma_f32 v70, -v70, v73, v72
	v_div_fmas_f32 v70, v70, v71, v73
	v_div_fixup_f32 v69, v70, v69, 1.0
	v_div_scale_f32 v70, s[2:3], v68, v68, 1.0
	v_rcp_f32_e32 v71, v70
	s_nop 0
	v_fma_f32 v72, -v70, v71, 1.0
	v_fmac_f32_e32 v71, v72, v71
	v_div_scale_f32 v72, vcc, 1.0, v68, 1.0
	v_mul_f32_e32 v73, v72, v71
	v_fma_f32 v74, -v70, v73, v72
	v_fmac_f32_e32 v73, v74, v71
	v_fma_f32 v70, -v70, v73, v72
	v_div_fmas_f32 v70, v70, v71, v73
	v_div_fixup_f32 v68, v70, v68, 1.0
	v_pk_fma_f32 v[112:113], v[2:3], v[68:69], v[112:113]
	s_waitcnt vmcnt(12)
	v_cvt_f32_f16_e32 v68, v210
	v_cvt_f32_f16_e32 v69, v211
	v_mul_f32_e32 v68, 0xbfb8aa3b, v68
	v_mul_f32_e32 v69, 0xbfb8aa3b, v69
	v_exp_f32_e32 v68, v68
	v_exp_f32_e32 v69, v69
	s_nop 0
	v_pk_add_f32 v[68:69], v[68:69], 1.0 op_sel_hi:[1,0]
	s_nop 0
	v_div_scale_f32 v70, s[2:3], v69, v69, 1.0
	v_rcp_f32_e32 v71, v70
	s_nop 0
	v_fma_f32 v72, -v70, v71, 1.0
	v_fmac_f32_e32 v71, v72, v71
	v_div_scale_f32 v72, vcc, 1.0, v69, 1.0
	v_mul_f32_e32 v73, v72, v71
	v_fma_f32 v74, -v70, v73, v72
	v_fmac_f32_e32 v73, v74, v71
	v_fma_f32 v70, -v70, v73, v72
	v_div_fmas_f32 v70, v70, v71, v73
	v_div_fixup_f32 v69, v70, v69, 1.0
	v_div_scale_f32 v70, s[2:3], v68, v68, 1.0
	v_rcp_f32_e32 v71, v70
	s_nop 0
	v_fma_f32 v72, -v70, v71, 1.0
	v_fmac_f32_e32 v71, v72, v71
	v_div_scale_f32 v72, vcc, 1.0, v68, 1.0
	v_mul_f32_e32 v73, v72, v71
	v_fma_f32 v74, -v70, v73, v72
	v_fmac_f32_e32 v73, v74, v71
	v_fma_f32 v70, -v70, v73, v72
	v_div_fmas_f32 v70, v70, v71, v73
	v_div_fixup_f32 v68, v70, v68, 1.0
	v_pk_fma_f32 v[110:111], v[4:5], v[68:69], v[110:111]
	s_waitcnt vmcnt(10)
;   __device__ __forceinline__ half_t* u() const { return (half_t*)(ws() + OFF_u); }
;   __device__ __forceinline__ half_t* wpT() const { return (half_t*)(ws() + OFF_wpT); }
;   __device__ __forceinline__ half_t* ya() const { return (half_t*)(ws() + OFF_ya); }
;   __device__ __forceinline__ half_t* yb() const { return (half_t*)(ws() + OFF_yb); }
;   __device__ __forceinline__ half_t* yc() const { return (half_t*)(ws() + OFF_yc); }
; __device__ __forceinline__ float sigmoidf_(float x) { return 1.f / (1.f + __expf(-x)); }
; __device__ __forceinline__ void phase_merge(const KP& p, char* smem, int* q, int xcc) {
;     ...
;     for (int br = 0; br < 3; ++br) {
;       const half_t* A = (br == 0 ? p.ya() : (br == 1 ? p.yb() : p.yc())) + (size_t)m0 * 512;
;       const half_t* B = p.wpT() + (size_t)br * DM * 512 + (size_t)n0 * 512;
;       const half_t* G = p.u() + (size_t)m0 * NU + C_GM + br * 1024 + n0;
;       gemm_tile<2>(
;           512, [&](int r, int k) { return *(const uint4*)(A + (size_t)r * 512 + k); },
;           [&](int r, int k) { return *(const uint4*)(B + (size_t)r * 512 + k); },
;           [&](int mi, int ni, int r, int row, int col, float v) {
;             const float gz = (float)G[(size_t)row * NU + col];
;             tot[mi][ni][r] += sigmoidf_(gz) * v;
;           },
;           smem);
;     }
	v_cvt_f32_f16_e32 v68, v212
	v_cvt_f32_f16_e32 v69, v213
	v_mul_f32_e32 v68, 0xbfb8aa3b, v68
	v_mul_f32_e32 v69, 0xbfb8aa3b, v69
	v_exp_f32_e32 v68, v68
	v_exp_f32_e32 v69, v69
	s_nop 0
	v_pk_add_f32 v[68:69], v[68:69], 1.0 op_sel_hi:[1,0]
	s_nop 0
	v_div_scale_f32 v70, s[2:3], v69, v69, 1.0
	v_rcp_f32_e32 v71, v70
	s_nop 0
	v_fma_f32 v72, -v70, v71, 1.0
	v_fmac_f32_e32 v71, v72, v71
	v_div_scale_f32 v72, vcc, 1.0, v69, 1.0
	v_mul_f32_e32 v73, v72, v71
	v_fma_f32 v74, -v70, v73, v72
	v_fmac_f32_e32 v73, v74, v71
	v_fma_f32 v70, -v70, v73, v72
	v_div_fmas_f32 v70, v70, v71, v73
	v_div_fixup_f32 v69, v70, v69, 1.0
	v_div_scale_f32 v70, s[2:3], v68, v68, 1.0
	v_rcp_f32_e32 v71, v70
	s_nop 0
	v_fma_f32 v72, -v70, v71, 1.0
	v_fmac_f32_e32 v71, v72, v71
	v_div_scale_f32 v72, vcc, 1.0, v68, 1.0
	v_mul_f32_e32 v73, v72, v71
	v_fma_f32 v74, -v70, v73, v72
	v_fmac_f32_e32 v73, v74, v71
	v_fma_f32 v70, -v70, v73, v72
	v_div_fmas_f32 v70, v70, v71, v73
	v_div_fixup_f32 v68, v70, v68, 1.0
	v_pk_fma_f32 v[108:109], v[6:7], v[68:69], v[108:109]
	s_waitcnt vmcnt(8)
	v_cvt_f32_f16_e32 v68, v214
	v_cvt_f32_f16_e32 v69, v215
	v_mul_f32_e32 v68, 0xbfb8aa3b, v68
	v_mul_f32_e32 v69, 0xbfb8aa3b, v69
	v_exp_f32_e32 v68, v68
	v_exp_f32_e32 v69, v69
	s_nop 0
	v_pk_add_f32 v[68:69], v[68:69], 1.0 op_sel_hi:[1,0]
	s_nop 0
	v_div_scale_f32 v70, s[2:3], v69, v69, 1.0
	v_rcp_f32_e32 v71, v70
	s_nop 0
	v_fma_f32 v72, -v70, v71, 1.0
	v_fmac_f32_e32 v71, v72, v71
	v_div_scale_f32 v72, vcc, 1.0, v69, 1.0
	v_mul_f32_e32 v73, v72, v71
	v_fma_f32 v74, -v70, v73, v72
	v_fmac_f32_e32 v73, v74, v71
	v_fma_f32 v70, -v70, v73, v72
	v_div_fmas_f32 v70, v70, v71, v73
	v_div_fixup_f32 v69, v70, v69, 1.0
	v_div_scale_f32 v70, s[2:3], v68, v68, 1.0
	v_rcp_f32_e32 v71, v70
	s_nop 0
	v_fma_f32 v72, -v70, v71, 1.0
	v_fmac_f32_e32 v71, v72, v71
	v_div_scale_f32 v72, vcc, 1.0, v68, 1.0
	v_mul_f32_e32 v73, v72, v71
	v_fma_f32 v74, -v70, v73, v72
	v_fmac_f32_e32 v73, v74, v71
	v_fma_f32 v70, -v70, v73, v72
	v_div_fmas_f32 v70, v70, v71, v73
	v_div_fixup_f32 v68, v70, v68, 1.0
	v_pk_fma_f32 v[106:107], v[8:9], v[68:69], v[106:107]
	s_waitcnt vmcnt(6)
	v_cvt_f32_f16_e32 v68, v216
	v_cvt_f32_f16_e32 v69, v217
	v_mul_f32_e32 v68, 0xbfb8aa3b, v68
	v_mul_f32_e32 v69, 0xbfb8aa3b, v69
	v_exp_f32_e32 v68, v68
	v_exp_f32_e32 v69, v69
	s_nop 0
	v_pk_add_f32 v[68:69], v[68:69], 1.0 op_sel_hi:[1,0]
	s_nop 0
	v_div_scale_f32 v70, s[2:3], v69, v69, 1.0
	v_rcp_f32_e32 v71, v70
	s_nop 0
	v_fma_f32 v72, -v70, v71, 1.0
	v_fmac_f32_e32 v71, v72, v71
	v_div_scale_f32 v72, vcc, 1.0, v69, 1.0
	v_mul_f32_e32 v73, v72, v71
	v_fma_f32 v74, -v70, v73, v72
	v_fmac_f32_e32 v73, v74, v71
	v_fma_f32 v70, -v70, v73, v72
	v_div_fmas_f32 v70, v70, v71, v73
	v_div_fixup_f32 v69, v70, v69, 1.0
	v_div_scale_f32 v70, s[2:3], v68, v68, 1.0
	v_rcp_f32_e32 v71, v70
	s_nop 0
	v_fma_f32 v72, -v70, v71, 1.0
	v_fmac_f32_e32 v71, v72, v71
	v_div_scale_f32 v72, vcc, 1.0, v68, 1.0
	v_mul_f32_e32 v73, v72, v71
	v_fma_f32 v74, -v70, v73, v72
	v_fmac_f32_e32 v73, v74, v71
	v_fma_f32 v70, -v70, v73, v72
	v_div_fmas_f32 v70, v70, v71, v73
	v_div_fixup_f32 v68, v70, v68, 1.0
	v_pk_fma_f32 v[104:105], v[10:11], v[68:69], v[104:105]
	s_waitcnt vmcnt(4)
	v_cvt_f32_f16_e32 v68, v218
	v_cvt_f32_f16_e32 v69, v219
	v_mul_f32_e32 v68, 0xbfb8aa3b, v68
	v_mul_f32_e32 v69, 0xbfb8aa3b, v69
	v_exp_f32_e32 v68, v68
	v_exp_f32_e32 v69, v69
	s_nop 0
	v_pk_add_f32 v[68:69], v[68:69], 1.0 op_sel_hi:[1,0]
	s_nop 0
	v_div_scale_f32 v70, s[2:3], v69, v69, 1.0
	v_rcp_f32_e32 v71, v70
	s_nop 0
	v_fma_f32 v72, -v70, v71, 1.0
	v_fmac_f32_e32 v71, v72, v71
	v_div_scale_f32 v72, vcc, 1.0, v69, 1.0
	v_mul_f32_e32 v73, v72, v71
	v_fma_f32 v74, -v70, v73, v72
	v_fmac_f32_e32 v73, v74, v71
	v_fma_f32 v70, -v70, v73, v72
	v_div_fmas_f32 v70, v70, v71, v73
	v_div_fixup_f32 v69, v70, v69, 1.0
	v_div_scale_f32 v70, s[2:3], v68, v68, 1.0
	v_rcp_f32_e32 v71, v70
	s_nop 0
	v_fma_f32 v72, -v70, v71, 1.0
	v_fmac_f32_e32 v71, v72, v71
	v_div_scale_f32 v72, vcc, 1.0, v68, 1.0
	v_mul_f32_e32 v73, v72, v71
	v_fma_f32 v74, -v70, v73, v72
	v_fmac_f32_e32 v73, v74, v71
	v_fma_f32 v70, -v70, v73, v72
	v_div_fmas_f32 v70, v70, v71, v73
	v_div_fixup_f32 v68, v70, v68, 1.0
	v_pk_fma_f32 v[102:103], v[12:13], v[68:69], v[102:103]
	s_waitcnt vmcnt(2)
	v_cvt_f32_f16_e32 v68, v220
	v_cvt_f32_f16_e32 v69, v221
	v_mul_f32_e32 v68, 0xbfb8aa3b, v68
	v_mul_f32_e32 v69, 0xbfb8aa3b, v69
	v_exp_f32_e32 v68, v68
	v_exp_f32_e32 v69, v69
	s_nop 0
	v_pk_add_f32 v[68:69], v[68:69], 1.0 op_sel_hi:[1,0]
	s_nop 0
	v_div_scale_f32 v70, s[2:3], v69, v69, 1.0
	v_rcp_f32_e32 v71, v70
	s_nop 0
	v_fma_f32 v72, -v70, v71, 1.0
	v_fmac_f32_e32 v71, v72, v71
	v_div_scale_f32 v72, vcc, 1.0, v69, 1.0
	v_mul_f32_e32 v73, v72, v71
	v_fma_f32 v74, -v70, v73, v72
	v_fmac_f32_e32 v73, v74, v71
	v_fma_f32 v70, -v70, v73, v72
	v_div_fmas_f32 v70, v70, v71, v73
	v_div_fixup_f32 v69, v70, v69, 1.0
	v_div_scale_f32 v70, s[2:3], v68, v68, 1.0
	v_rcp_f32_e32 v71, v70
	s_nop 0
	v_fma_f32 v72, -v70, v71, 1.0
	v_fmac_f32_e32 v71, v72, v71
	v_div_scale_f32 v72, vcc, 1.0, v68, 1.0
	v_mul_f32_e32 v73, v72, v71
	v_fma_f32 v74, -v70, v73, v72
	v_fmac_f32_e32 v73, v74, v71
	v_fma_f32 v70, -v70, v73, v72
	v_div_fmas_f32 v70, v70, v71, v73
	v_div_fixup_f32 v68, v70, v68, 1.0
	v_pk_fma_f32 v[100:101], v[14:15], v[68:69], v[100:101]
	s_waitcnt vmcnt(0)
	v_cvt_f32_f16_e32 v68, v222
	v_cvt_f32_f16_e32 v69, v223
	v_mul_f32_e32 v68, 0xbfb8aa3b, v68
	v_mul_f32_e32 v69, 0xbfb8aa3b, v69
	v_exp_f32_e32 v68, v68
	v_exp_f32_e32 v69, v69
	s_nop 0
	v_pk_add_f32 v[68:69], v[68:69], 1.0 op_sel_hi:[1,0]
	s_nop 0
	v_div_scale_f32 v70, s[2:3], v69, v69, 1.0
	v_rcp_f32_e32 v71, v70
	s_nop 0
	v_fma_f32 v72, -v70, v71, 1.0
	v_fmac_f32_e32 v71, v72, v71
	v_div_scale_f32 v72, vcc, 1.0, v69, 1.0
	v_mul_f32_e32 v73, v72, v71
	v_fma_f32 v74, -v70, v73, v72
	v_fmac_f32_e32 v73, v74, v71
	v_fma_f32 v70, -v70, v73, v72
	v_div_fmas_f32 v70, v70, v71, v73
	v_div_fixup_f32 v69, v70, v69, 1.0
	v_div_scale_f32 v70, s[2:3], v68, v68, 1.0
	v_rcp_f32_e32 v71, v70
	s_nop 0
	v_fma_f32 v72, -v70, v71, 1.0
	v_fmac_f32_e32 v71, v72, v71
	v_div_scale_f32 v72, vcc, 1.0, v68, 1.0
	v_mul_f32_e32 v73, v72, v71
	v_fma_f32 v74, -v70, v73, v72
	v_fmac_f32_e32 v73, v74, v71
	v_fma_f32 v70, -v70, v73, v72
	v_div_fmas_f32 v70, v70, v71, v73
	v_div_fixup_f32 v68, v70, v68, 1.0
	v_pk_fma_f32 v[98:99], v[16:17], v[68:69], v[98:99]
	s_cmp_lg_u32 s56, 3
	s_cbranch_scc1 .LBB0_1742
;   __device__ __forceinline__ const float* x() const { return (const float*)(const __attribute__((address_space(1))) float*)kp[0]; }
;   __device__ __forceinline__ half_t* mm() const { return (half_t*)(ws() + OFF_mm); }
; __device__ __forceinline__ void phase_merge(const KP& p, char* smem, int* q, int xcc) {
;     ...
;     int tidx = threadIdx.x;
;     asm volatile("" : "+v"(tidx));
;     const int lane = tidx & 63, wid = tidx >> 6, wm = wid >> 1, wn = wid & 1;
; #pragma unroll
;     for (int mi = 0; mi < 2; ++mi)
; #pragma unroll
;       for (int ni = 0; ni < 2; ++ni)
; #pragma unroll
;         for (int r = 0; r < 16; ++r) {
;           const int row = wm * 64 + mi * 32 + (r & 3) + 8 * (r >> 2) + 4 * (lane >> 5);
;           const int col = wn * 64 + ni * 32 + (lane & 31);
;           p.mm()[(size_t)(m0 + row) * DM + n0 + col] = (half_t)tot[mi][ni][r];
;         }
	v_mov_b32_e32 v0, v224
	s_add_u32 s2, s44, s18
	v_ashrrev_i32_e32 v2, 1, v0
	v_and_b32_e32 v2, 0xffffffc0, v2
	v_lshrrev_b32_e32 v3, 3, v0
	v_and_b32_e32 v0, 0x5f, v0
	v_add_u32_e32 v2, s14, v2
	s_addc_u32 s3, s45, s19
	v_lshlrev_b32_e32 v0, 1, v0
	v_and_or_b32 v2, v3, 4, v2
	v_lshl_add_u64 v[4:5], s[2:3], 0, v[0:1]
	v_cvt_f16_f32_e32 v0, v160
	v_ashrrev_i32_e32 v3, 31, v2
	v_lshlrev_b64 v[6:7], 11, v[2:3]
	v_lshl_add_u64 v[6:7], v[4:5], 0, v[6:7]
	global_store_short v[6:7], v0, off
	v_cvt_f16_f32_e32 v0, v161
	v_or_b32_e32 v8, 1, v2
	v_ashrrev_i32_e32 v9, 31, v8
	v_lshlrev_b64 v[8:9], 11, v[8:9]
	v_lshl_add_u64 v[8:9], v[4:5], 0, v[8:9]
	global_store_short v[8:9], v0, off
	v_cvt_f16_f32_e32 v0, v158
	v_or_b32_e32 v10, 2, v2
	v_ashrrev_i32_e32 v11, 31, v10
	v_lshlrev_b64 v[10:11], 11, v[10:11]
	v_lshl_add_u64 v[10:11], v[4:5], 0, v[10:11]
	global_store_short v[10:11], v0, off
	v_cvt_f16_f32_e32 v0, v159
	v_or_b32_e32 v12, 3, v2
	v_ashrrev_i32_e32 v13, 31, v12
	v_lshlrev_b64 v[12:13], 11, v[12:13]
	v_lshl_add_u64 v[12:13], v[4:5], 0, v[12:13]
	global_store_short v[12:13], v0, off
	v_cvt_f16_f32_e32 v0, v156
	v_or_b32_e32 v14, 8, v2
	v_ashrrev_i32_e32 v15, 31, v14
	v_lshlrev_b64 v[14:15], 11, v[14:15]
	v_lshl_add_u64 v[14:15], v[4:5], 0, v[14:15]
	global_store_short v[14:15], v0, off
	v_cvt_f16_f32_e32 v0, v157
	v_or_b32_e32 v16, 9, v2
	v_ashrrev_i32_e32 v17, 31, v16
	v_lshlrev_b64 v[16:17], 11, v[16:17]
	v_lshl_add_u64 v[16:17], v[4:5], 0, v[16:17]
	global_store_short v[16:17], v0, off
	v_cvt_f16_f32_e32 v0, v154
	v_or_b32_e32 v18, 10, v2
	v_ashrrev_i32_e32 v19, 31, v18
	v_lshlrev_b64 v[18:19], 11, v[18:19]
	v_lshl_add_u64 v[18:19], v[4:5], 0, v[18:19]
	global_store_short v[18:19], v0, off
	v_cvt_f16_f32_e32 v0, v155
	v_or_b32_e32 v20, 11, v2
	v_ashrrev_i32_e32 v21, 31, v20
	v_lshlrev_b64 v[20:21], 11, v[20:21]
	v_lshl_add_u64 v[20:21], v[4:5], 0, v[20:21]
	global_store_short v[20:21], v0, off
	v_cvt_f16_f32_e32 v0, v152
	v_or_b32_e32 v22, 16, v2
	v_ashrrev_i32_e32 v23, 31, v22
	v_lshlrev_b64 v[22:23], 11, v[22:23]
	v_lshl_add_u64 v[22:23], v[4:5], 0, v[22:23]
	global_store_short v[22:23], v0, off
	v_cvt_f16_f32_e32 v0, v153
	v_or_b32_e32 v24, 17, v2
	v_ashrrev_i32_e32 v25, 31, v24
	v_lshlrev_b64 v[24:25], 11, v[24:25]
	v_lshl_add_u64 v[24:25], v[4:5], 0, v[24:25]
	global_store_short v[24:25], v0, off
	v_cvt_f16_f32_e32 v0, v150
	v_or_b32_e32 v26, 18, v2
	v_ashrrev_i32_e32 v27, 31, v26
	v_lshlrev_b64 v[26:27], 11, v[26:27]
	v_lshl_add_u64 v[26:27], v[4:5], 0, v[26:27]
	global_store_short v[26:27], v0, off
	v_cvt_f16_f32_e32 v0, v151
	v_or_b32_e32 v28, 19, v2
	v_ashrrev_i32_e32 v29, 31, v28
	v_lshlrev_b64 v[28:29], 11, v[28:29]
	v_lshl_add_u64 v[28:29], v[4:5], 0, v[28:29]
	global_store_short v[28:29], v0, off
	v_cvt_f16_f32_e32 v0, v148
	v_or_b32_e32 v30, 24, v2
	v_ashrrev_i32_e32 v31, 31, v30
	v_lshlrev_b64 v[30:31], 11, v[30:31]
	v_lshl_add_u64 v[30:31], v[4:5], 0, v[30:31]
	global_store_short v[30:31], v0, off
	v_cvt_f16_f32_e32 v0, v149
	v_or_b32_e32 v32, 25, v2
	v_ashrrev_i32_e32 v33, 31, v32
	v_lshlrev_b64 v[32:33], 11, v[32:33]
	v_lshl_add_u64 v[32:33], v[4:5], 0, v[32:33]
	global_store_short v[32:33], v0, off
	v_cvt_f16_f32_e32 v0, v146
	v_or_b32_e32 v34, 26, v2
	v_ashrrev_i32_e32 v35, 31, v34
	v_lshlrev_b64 v[34:35], 11, v[34:35]
	v_lshl_add_u64 v[34:35], v[4:5], 0, v[34:35]
	global_store_short v[34:35], v0, off
	v_cvt_f16_f32_e32 v0, v147
	v_or_b32_e32 v36, 27, v2
	v_ashrrev_i32_e32 v37, 31, v36
	v_lshlrev_b64 v[36:37], 11, v[36:37]
	v_lshl_add_u64 v[36:37], v[4:5], 0, v[36:37]
	global_store_short v[36:37], v0, off
	v_cvt_f16_f32_e32 v0, v144
	v_cvt_f16_f32_e32 v3, v145
	v_cvt_f16_f32_e32 v38, v142
	v_cvt_f16_f32_e32 v39, v143
	global_store_short v[6:7], v0, off offset:64
	global_store_short v[8:9], v3, off offset:64
	global_store_short v[10:11], v38, off offset:64
	global_store_short v[12:13], v39, off offset:64
	v_cvt_f16_f32_e32 v0, v140
	v_cvt_f16_f32_e32 v3, v141
	v_cvt_f16_f32_e32 v6, v138
	v_cvt_f16_f32_e32 v7, v139
	global_store_short v[14:15], v0, off offset:64
	global_store_short v[16:17], v3, off offset:64
	global_store_short v[18:19], v6, off offset:64
	global_store_short v[20:21], v7, off offset:64
	v_cvt_f16_f32_e32 v0, v136
	v_cvt_f16_f32_e32 v3, v137
	v_cvt_f16_f32_e32 v6, v134
	v_cvt_f16_f32_e32 v7, v135
	global_store_short v[22:23], v0, off offset:64
	global_store_short v[24:25], v3, off offset:64
	global_store_short v[26:27], v6, off offset:64
	global_store_short v[28:29], v7, off offset:64
	v_cvt_f16_f32_e32 v0, v132
	v_cvt_f16_f32_e32 v3, v133
	v_cvt_f16_f32_e32 v6, v130
	v_cvt_f16_f32_e32 v7, v131
	global_store_short v[30:31], v0, off offset:64
;   __device__ __forceinline__ const float* x() const { return (const float*)(const __attribute__((address_space(1))) float*)kp[0]; }
;   __device__ __forceinline__ half_t* mm() const { return (half_t*)(ws() + OFF_mm); }
; __device__ __forceinline__ void phase_merge(const KP& p, char* smem, int* q, int xcc) {
;     ...
;     int tidx = threadIdx.x;
;     asm volatile("" : "+v"(tidx));
;     const int lane = tidx & 63, wid = tidx >> 6, wm = wid >> 1, wn = wid & 1;
; #pragma unroll
;     for (int mi = 0; mi < 2; ++mi)
; #pragma unroll
;       for (int ni = 0; ni < 2; ++ni)
; #pragma unroll
;         for (int r = 0; r < 16; ++r) {
;           const int row = wm * 64 + mi * 32 + (r & 3) + 8 * (r >> 2) + 4 * (lane >> 5);
;           const int col = wn * 64 + ni * 32 + (lane & 31);
;           p.mm()[(size_t)(m0 + row) * DM + n0 + col] = (half_t)tot[mi][ni][r];
;         }
	global_store_short v[32:33], v3, off offset:64
	global_store_short v[34:35], v6, off offset:64
	global_store_short v[36:37], v7, off offset:64
	v_or_b32_e32 v6, 32, v2
	v_cvt_f16_f32_e32 v0, v128
	v_ashrrev_i32_e32 v7, 31, v6
	v_lshlrev_b64 v[6:7], 11, v[6:7]
	v_lshl_add_u64 v[6:7], v[4:5], 0, v[6:7]
	global_store_short v[6:7], v0, off
	v_cvt_f16_f32_e32 v0, v129
	v_or_b32_e32 v8, 33, v2
	v_ashrrev_i32_e32 v9, 31, v8
	v_lshlrev_b64 v[8:9], 11, v[8:9]
	v_lshl_add_u64 v[8:9], v[4:5], 0, v[8:9]
	global_store_short v[8:9], v0, off
	v_cvt_f16_f32_e32 v0, v126
	v_or_b32_e32 v10, 34, v2
	v_ashrrev_i32_e32 v11, 31, v10
	v_lshlrev_b64 v[10:11], 11, v[10:11]
	v_lshl_add_u64 v[10:11], v[4:5], 0, v[10:11]
	global_store_short v[10:11], v0, off
	v_cvt_f16_f32_e32 v0, v127
	v_or_b32_e32 v12, 35, v2
	v_ashrrev_i32_e32 v13, 31, v12
	v_lshlrev_b64 v[12:13], 11, v[12:13]
	v_lshl_add_u64 v[12:13], v[4:5], 0, v[12:13]
	global_store_short v[12:13], v0, off
	v_cvt_f16_f32_e32 v0, v124
	v_or_b32_e32 v14, 40, v2
	v_ashrrev_i32_e32 v15, 31, v14
	v_lshlrev_b64 v[14:15], 11, v[14:15]
	v_lshl_add_u64 v[14:15], v[4:5], 0, v[14:15]
	global_store_short v[14:15], v0, off
	v_cvt_f16_f32_e32 v0, v125
	v_or_b32_e32 v16, 41, v2
	v_ashrrev_i32_e32 v17, 31, v16
	v_lshlrev_b64 v[16:17], 11, v[16:17]
	v_lshl_add_u64 v[16:17], v[4:5], 0, v[16:17]
	global_store_short v[16:17], v0, off
	v_cvt_f16_f32_e32 v0, v122
	v_or_b32_e32 v18, 42, v2
	v_ashrrev_i32_e32 v19, 31, v18
	v_lshlrev_b64 v[18:19], 11, v[18:19]
	v_lshl_add_u64 v[18:19], v[4:5], 0, v[18:19]
	global_store_short v[18:19], v0, off
	v_cvt_f16_f32_e32 v0, v123
	v_or_b32_e32 v20, 43, v2
	v_ashrrev_i32_e32 v21, 31, v20
	v_lshlrev_b64 v[20:21], 11, v[20:21]
	v_lshl_add_u64 v[20:21], v[4:5], 0, v[20:21]
	global_store_short v[20:21], v0, off
	v_cvt_f16_f32_e32 v0, v120
	v_or_b32_e32 v22, 48, v2
	v_ashrrev_i32_e32 v23, 31, v22
	v_lshlrev_b64 v[22:23], 11, v[22:23]
	v_lshl_add_u64 v[22:23], v[4:5], 0, v[22:23]
	global_store_short v[22:23], v0, off
	v_cvt_f16_f32_e32 v0, v121
	v_or_b32_e32 v24, 49, v2
	v_ashrrev_i32_e32 v25, 31, v24
	v_lshlrev_b64 v[24:25], 11, v[24:25]
	v_lshl_add_u64 v[24:25], v[4:5], 0, v[24:25]
	global_store_short v[24:25], v0, off
	v_cvt_f16_f32_e32 v0, v118
	v_or_b32_e32 v26, 50, v2
	v_ashrrev_i32_e32 v27, 31, v26
	v_lshlrev_b64 v[26:27], 11, v[26:27]
	v_lshl_add_u64 v[26:27], v[4:5], 0, v[26:27]
	global_store_short v[26:27], v0, off
	v_cvt_f16_f32_e32 v0, v119
	v_or_b32_e32 v28, 51, v2
	v_ashrrev_i32_e32 v29, 31, v28
	v_lshlrev_b64 v[28:29], 11, v[28:29]
	v_lshl_add_u64 v[28:29], v[4:5], 0, v[28:29]
	global_store_short v[28:29], v0, off
	v_cvt_f16_f32_e32 v0, v116
	v_or_b32_e32 v30, 56, v2
	v_ashrrev_i32_e32 v31, 31, v30
	v_lshlrev_b64 v[30:31], 11, v[30:31]
	v_lshl_add_u64 v[30:31], v[4:5], 0, v[30:31]
	global_store_short v[30:31], v0, off
	v_cvt_f16_f32_e32 v0, v117
	v_or_b32_e32 v32, 57, v2
	v_ashrrev_i32_e32 v33, 31, v32
	v_lshlrev_b64 v[32:33], 11, v[32:33]
	v_lshl_add_u64 v[32:33], v[4:5], 0, v[32:33]
	global_store_short v[32:33], v0, off
	v_cvt_f16_f32_e32 v0, v114
	v_or_b32_e32 v34, 58, v2
	v_ashrrev_i32_e32 v35, 31, v34
	v_lshlrev_b64 v[34:35], 11, v[34:35]
	v_lshl_add_u64 v[34:35], v[4:5], 0, v[34:35]
	global_store_short v[34:35], v0, off
	v_cvt_f16_f32_e32 v0, v115
	v_or_b32_e32 v2, 59, v2
	v_ashrrev_i32_e32 v3, 31, v2
	v_lshlrev_b64 v[2:3], 11, v[2:3]
	v_lshl_add_u64 v[2:3], v[4:5], 0, v[2:3]
	global_store_short v[2:3], v0, off
	v_cvt_f16_f32_e32 v0, v112
	v_cvt_f16_f32_e32 v4, v113
	v_cvt_f16_f32_e32 v5, v110
	v_cvt_f16_f32_e32 v36, v111
	global_store_short v[6:7], v0, off offset:64
	global_store_short v[8:9], v4, off offset:64
	global_store_short v[10:11], v5, off offset:64
	global_store_short v[12:13], v36, off offset:64
	v_cvt_f16_f32_e32 v0, v108
	v_cvt_f16_f32_e32 v4, v109
	v_cvt_f16_f32_e32 v5, v106
	v_cvt_f16_f32_e32 v6, v107
	global_store_short v[14:15], v0, off offset:64
	global_store_short v[16:17], v4, off offset:64
	global_store_short v[18:19], v5, off offset:64
	global_store_short v[20:21], v6, off offset:64
	v_cvt_f16_f32_e32 v0, v104
	v_cvt_f16_f32_e32 v4, v105
	v_cvt_f16_f32_e32 v5, v102
	v_cvt_f16_f32_e32 v6, v103
	global_store_short v[22:23], v0, off offset:64
	global_store_short v[24:25], v4, off offset:64
	global_store_short v[26:27], v5, off offset:64
	global_store_short v[28:29], v6, off offset:64
	v_cvt_f16_f32_e32 v0, v100
	v_cvt_f16_f32_e32 v4, v101
	v_cvt_f16_f32_e32 v5, v98
	v_cvt_f16_f32_e32 v6, v99
	global_store_short v[30:31], v0, off offset:64
	global_store_short v[32:33], v4, off offset:64
	global_store_short v[34:35], v5, off offset:64
	global_store_short v[2:3], v6, off offset:64
	s_branch .LBB0_1731
